# full-line lane-contiguous epilogue stores extended to FFN2 (both layers) and layer-1 Wo GEMMs (6 GEMM instances now)
# speedup vs baseline: 1.0057x; 1.0057x over previous
; #define PG8_WAIT_V(n) asm volatile("s_waitcnt vmcnt(" #n ")" ::: "memory")
; #define PG8_BAR __builtin_amdgcn_s_barrier()
; template <class Epi, class Sched, bool ALIGN_EPI = false, bool SP2 = false>
; __device__ __forceinline__ void gemm_phase(PG8_LAS unsigned char* lds, const Gemm g, const Sched& S, const Epi& E) {
;     int tid_l_ = threadIdx.x; asm volatile("" : "+v"(tid_l_)); const int tid = tid_l_, wid = __builtin_amdgcn_readfirstlane(tid >> 6), lane = tid & 63, wr = wid >> 2, wc = wid & 3, fr = lane & 15, fq = lane >> 4;
;     const int K = g.K, nt = K / BK;
;     unsigned voffA[2], voffB[2];
; #pragma unroll
;     for (int i = 0; i < 2; ++i) { int R, C; stage_rc(tid * 16 + i * 8192, R, C); const int Rb = Epi::PERM ? ((R & ~31) + perm32(R & 31)) : R;
;         voffA[i] = (unsigned)(R * K + C) * 2u; voffB[i] = (unsigned)(Rb * K + C) * 2u; }
;     const size_t kstep = (size_t)(BK * 2);
;     const size_t hstep = (size_t)HALF * K * 2;
;     const size_t tstep = 2 * hstep;
;     const unsigned ldsw = (unsigned)wid * 1024u;
;     const int aoff = lds_byte(wr * 64 + fr, fq * 8), boff = lds_byte(wc * 32 + fr, fq * 8);
;     ...
;     Unit cur, nxt; int ui = 0;
;     if (!S.next(0, cur)) return;
;     f32x4 acc[2][2][4][2];
; #pragma unroll
;     for (int a = 0; a < 2; ++a)
; #pragma unroll
;         for (int b = 0; b < 2; ++b)
; #pragma unroll
;             for (int m = 0; m < 4; ++m)
; #pragma unroll
;                 for (int n = 0; n < 2; ++n) acc[a][b][m][n] = (f32x4){0.f, 0.f, 0.f, 0.f};
;     bf16x8 At[4][2], B0[2][2], B1[2][2];
;     const char* cA = (const char*)g.A + (size_t)cur.pm * tstep; const char* cB = (const char*)g.Bt + (size_t)cur.pn * tstep;
;     S.a_ready(cur);
;     if constexpr (SP2) {
;         PG8_STAGE(PG8_SB(0, 0), cB, voffB); PG8_STAGE(PG8_SB(0, 1), cB + hstep, voffB); PG8_STAGE(PG8_SA(0, 0), cA, voffA); PG8_STAGE(PG8_SA(0, 1), cA + hstep, voffA);
;         if (wr == 1) PG8_BAR;
;         PG8_WAIT_V(2); PG8_BAR;
;         PG8_STAGE(PG8_SB(1, 0), cB + kstep, voffB); PG8_STAGE(PG8_SA(1, 0), cA + kstep, voffA); PG8_STAGE(PG8_SB(1, 1), cB + hstep + kstep, voffB);
;         PG8_WAIT_V(6); PG8_BAR;
;     } else {
;         PG8_STAGE(PG8_SB(0, 0), cB, voffB); PG8_STAGE(PG8_SA(0, 0), cA, voffA); PG8_STAGE(PG8_SB(0, 1), cB + hstep, voffB); PG8_STAGE(PG8_SA(0, 1), cA + hstep, voffA);
;         if (wr == 1) PG8_BAR;
;         PG8_WAIT_V(4); PG8_BAR;
.LBB0_23:
	s_andn2_b64 vcc, exec, s[30:31]
	s_cbranch_vccnz .LBB0_44
	s_waitcnt vmcnt(0)
	v_mov_b32_e32 v6, v208
	s_cmpk_gt_i32 s23, 0x1ff
	s_nop 0
	v_readfirstlane_b32 s33, v6
	s_cbranch_scc1 .LBB0_44
	v_lshlrev_b32_e32 v3, 4, v6
	v_add_u32_e32 v1, 0x2000, v3
	v_ashrrev_i32_e32 v0, 31, v1
	v_lshrrev_b32_e32 v0, 22, v0
	v_add_u32_e32 v0, v1, v0
	v_ashrrev_i32_e32 v0, 10, v0
	v_mul_i32_i24_e32 v2, 0x400, v0
	v_sub_u32_e32 v1, v1, v2
	v_lshrrev_b32_e32 v2, 4, v1
	v_bitop3_b32 v2, v2, v1, 32 bitop3:0x6c
	v_ashrrev_i32_e32 v1, 31, v2
	v_lshrrev_b32_e32 v1, 26, v1
	v_add_u32_e32 v4, v2, v1
	v_lshlrev_b32_e32 v5, 3, v0
	v_ashrrev_i32_e32 v1, 6, v4
	v_and_b32_e32 v5, -16, v5
	v_add_u32_e32 v5, v1, v5
	v_and_b32_e32 v7, 3, v1
	s_mov_b32 s7, 0x3ffe0
	v_lshrrev_b32_e32 v8, 2, v5
	v_lshlrev_b32_e32 v9, 1, v5
	v_and_b32_e32 v4, 0xc0, v4
	v_and_b32_e32 v252, s7, v5
	v_lshl_or_b32 v7, v252, 1, v7
	v_and_b32_e32 v8, 4, v8
	v_and_b32_e32 v9, 24, v9
	v_sub_u32_e32 v2, v2, v4
	v_mov_b32_e32 v12, 1
	v_or3_b32 v7, v7, v8, v9
	v_lshlrev_b32_e32 v8, 5, v0
	v_ashrrev_i16_sdwa v2, v12, sext(v2) dst_sel:DWORD dst_unused:UNUSED_PAD src0_sel:DWORD src1_sel:BYTE_0
	v_and_b32_e32 v8, 32, v8
	v_bfe_i32 v2, v2, 0, 16
	v_add_lshl_u32 v4, v8, v2, 1
	v_lshl_add_u32 v130, v7, 14, v4
	v_lshl_add_u32 v132, v5, 14, v4
	v_bfe_i32 v4, v6, 27, 1
	v_lshrrev_b32_e32 v4, 22, v4
	v_add_u32_e32 v4, v3, v4
	v_and_b32_e32 v4, 0xfffffc00, v4
	v_sub_u32_e32 v3, v3, v4
	v_lshrrev_b32_e32 v4, 4, v3
	v_bitop3_b32 v5, v4, v3, 32 bitop3:0x6c
	v_ashrrev_i32_e32 v4, 31, v6
	v_lshrrev_b32_e32 v4, 26, v4
	v_ashrrev_i32_e32 v3, 31, v5
	v_add_u32_e32 v4, v6, v4
	v_lshrrev_b32_e32 v3, 26, v3
	v_ashrrev_i32_e32 v4, 6, v4
	v_add_u32_e32 v7, v5, v3
	v_lshlrev_b32_e32 v8, 3, v4
	v_ashrrev_i32_e32 v3, 6, v7
	v_and_b32_e32 v8, -16, v8
	v_add_u32_e32 v8, v3, v8
	v_and_b32_e32 v9, 3, v3
	s_ashr_i32 s28, s33, 6
	v_and_b32_e32 v252, s7, v8
	v_lshl_or_b32 v9, v252, 1, v9
	v_readlane_b32 s6, v255, 2
	s_ashr_i32 s29, s33, 8
	s_lshl_b32 s2, s28, 10
	v_readlane_b32 s7, v255, 3
	s_and_b64 s[26:27], s[6:7], exec
	s_cselect_b32 s7, s91, s17
	s_add_i32 s7, s7, s74
	s_ashr_i32 s10, s7, 31
	s_lshr_b32 s10, s10, 27
	s_add_i32 s10, s7, s10
	s_mov_b32 s6, s17
	s_ashr_i32 s17, s10, 5
	s_lshl_b32 s17, s17, 2
	s_sub_i32 s26, 64, s17
	s_min_i32 s26, s26, 4
	v_and_b32_e32 v7, 0xc0, v7
	s_abs_i32 s27, s26
	v_sub_u32_e32 v5, v5, v7
	v_cvt_f32_u32_e32 v7, s27
	s_sub_i32 s31, 0, s27
	s_andn2_b32 s10, s10, 31
	s_sub_i32 s7, s7, s10
	v_rcp_iflag_f32_e32 v7, v7
	s_abs_i32 s30, s7
	s_xor_b32 s10, s7, s26
	s_ashr_i32 s10, s10, 31
	v_mul_f32_e32 v7, 0x4f7ffffe, v7
	v_cvt_u32_f32_e32 v7, v7
	v_lshrrev_b32_e32 v10, 2, v8
	v_lshlrev_b32_e32 v11, 1, v8
	v_and_b32_e32 v10, 4, v10
	v_readfirstlane_b32 s34, v7
	s_mul_i32 s31, s31, s34
	s_mul_hi_u32 s31, s34, s31
	s_add_i32 s34, s34, s31
	s_mul_hi_u32 s31, s30, s34
	s_mul_i32 s34, s31, s27
	s_sub_i32 s30, s30, s34
	s_add_i32 s34, s31, 1
	s_sub_i32 s35, s30, s27
	s_cmp_ge_u32 s30, s27
	s_cselect_b32 s31, s34, s31
	s_cselect_b32 s30, s35, s30
	s_add_i32 s34, s31, 1
	s_cmp_ge_u32 s30, s27
	s_cselect_b32 s27, s34, s31
	s_xor_b32 s27, s27, s10
	s_sub_i32 s10, s27, s10
	s_mul_i32 s26, s10, s26
	s_sub_i32 s7, s7, s26
	s_add_i32 s7, s7, s90
	s_add_i32 s48, s7, s17
	s_add_i32 s50, s10, s94
	v_and_b32_e32 v11, 24, v11
	s_ashr_i32 s49, s48, 31
	s_ashr_i32 s51, s50, 31
	v_or3_b32 v9, v9, v10, v11
	v_lshlrev_b32_e32 v10, 5, v4
	v_ashrrev_i16_sdwa v5, v12, sext(v5) dst_sel:DWORD dst_unused:UNUSED_PAD src0_sel:DWORD src1_sel:BYTE_0
	s_lshl_b64 s[26:27], s[48:49], 22
	s_lshl_b64 s[30:31], s[50:51], 22
	v_and_b32_e32 v10, 32, v10
	v_bfe_i32 v5, v5, 0, 16
	s_add_u32 s58, s18, s30
	v_add_lshl_u32 v10, v10, v5, 1
	s_addc_u32 s59, s19, s31
	s_add_i32 s10, s2, 0
	v_lshl_add_u32 v128, v9, 14, v10
	s_add_i32 m0, s10, 0x10000
	v_lshl_add_u32 v134, v8, 14, v10
	global_load_lds_dwordx4 v128, s[58:59]
	s_add_i32 m0, s10, 0x12000
	s_add_u32 s30, s58, 0x80000
	global_load_lds_dwordx4 v130, s[58:59]
	s_addc_u32 s31, s59, 0
	s_add_i32 m0, s10, 0x14000
	s_nop 0
	global_load_lds_dwordx4 v128, s[30:31]
	s_add_i32 m0, s10, 0x16000
	s_add_u32 s56, s8, s26
	s_addc_u32 s57, s9, s27
	s_add_i32 s17, s10, 0x2000
	global_load_lds_dwordx4 v130, s[30:31]
	s_mov_b32 m0, s10
	s_add_u32 s30, s56, 0x200000
	global_load_lds_dwordx4 v134, s[56:57]
	s_mov_b32 m0, s17
	s_addc_u32 s31, s57, 0
	s_add_i32 s26, s10, 0x4000
	global_load_lds_dwordx4 v132, s[56:57]
	s_mov_b32 m0, s26
	s_add_i32 s27, s10, 0x6000
	global_load_lds_dwordx4 v134, s[30:31]
	s_mov_b32 m0, s27
	s_cmp_eq_u32 s29, 1
	global_load_lds_dwordx4 v132, s[30:31]
	s_cselect_b64 s[30:31], -1, 0
	s_cmp_lg_u32 s29, 1
	s_cbranch_scc1 .LBB0_27
	s_barrier
.LBB0_27:
	v_lshrrev_b32_e32 v16, 1, v6
	v_and_b32_e32 v16, 24, v16
	v_and_b32_e32 v7, 15, v6
	v_lshlrev_b32_e32 v17, 1, v16
	v_lshlrev_b32_e32 v6, 2, v6
	v_bfe_u32 v252, v208, 3, 3
	v_lshl_or_b32 v142, s29, 6, v252
	v_lshl_or_b32 v7, v7, 6, v17
	s_lshl_b32 s7, s29, 13
	v_and_b32_e32 v6, 32, v6
	v_bitop3_b32 v17, v7, s7, v6 bitop3:0xde
	s_lshl_b32 s7, s28, 5
	s_and_b32 s7, s7, 0x60
	v_lshl_add_u64 v[8:9], s[58:59], 0, v[128:129]
	v_mov_b32_e32 v131, v129
	s_lshl_b32 s28, s7, 7
	v_lshl_add_u64 v[10:11], s[58:59], 0, v[130:131]
	v_mov_b32_e32 v135, v129
	v_bitop3_b32 v143, v7, s28, v6 bitop3:0xde
	s_add_i32 m0, s10, 0x18000
	v_lshl_add_u64 v[6:7], v[8:9], 0, s[20:21]
	v_lshl_add_u64 v[12:13], s[56:57], 0, v[134:135]
	v_mov_b32_e32 v133, v129
	s_waitcnt vmcnt(2)
	s_barrier
	global_load_lds_dwordx4 v[6:7], off
	v_lshl_add_u64 v[6:7], v[10:11], 0, s[20:21]
	s_add_i32 m0, s10, 0x1a000
	s_add_i32 s28, s10, 0x8000
	s_add_i32 s29, s10, 0xa000
	v_lshl_add_u64 v[14:15], s[56:57], 0, v[132:133]
	global_load_lds_dwordx4 v[6:7], off
	v_lshl_add_u64 v[6:7], v[12:13], 0, s[20:21]
	s_mov_b32 m0, s28
	s_add_u32 s34, s58, 0x80080
	global_load_lds_dwordx4 v[6:7], off
	v_lshl_add_u64 v[6:7], v[14:15], 0, s[20:21]
	s_mov_b32 m0, s29
	s_addc_u32 s35, s59, 0
	global_load_lds_dwordx4 v[6:7], off
	s_add_i32 m0, s10, 0x1c000
	v_lshl_add_u64 v[6:7], s[34:35], 0, v[128:129]
	global_load_lds_dwordx4 v[6:7], off
	v_lshl_add_u64 v[6:7], s[34:35], 0, v[130:131]
	s_add_i32 m0, s10, 0x1e000
	s_cmpk_lt_u32 s33, 0x100
	global_load_lds_dwordx4 v[6:7], off
	v_lshlrev_b32_e32 v6, 17, v4
	v_and_b32_e32 v6, 0xfffc0000, v6
	v_lshl_add_u32 v3, v3, 14, v6
	v_and_b32_e32 v4, 1, v4
	v_lshl_or_b32 v3, v4, 6, v3
	v_lshl_add_u32 v136, v5, 1, v3
	v_lshlrev_b32_e32 v3, 17, v0
	v_and_b32_e32 v3, 0xfffc0000, v3
	s_waitcnt vmcnt(6)
	v_lshl_add_u32 v1, v1, 14, v3
	v_and_b32_e32 v0, 1, v0
	v_lshl_or_b32 v0, v0, 6, v1
	s_cselect_b64 s[42:43], -1, 0
	v_and_b32_e32 v252, 7, v208
	v_lshlrev_b32_e32 v252, 3, v252
	v_lshl_or_b32 v144, s7, 1, v252
	v_mov_b32_e32 v137, v129
	v_lshl_add_u32 v138, v2, 1, v0
	v_mov_b32_e32 v139, v129
	s_mov_b32 s33, 0
	v_add_u32_e32 v145, 0, v17
	s_barrier
	s_branch .LBB0_30

; #define PG8_STAGE(bufoff, gbase, voff) do { _Pragma("unroll") for (int _i = 0; _i < 2; ++_i) \
;         __builtin_amdgcn_global_load_lds((const unsigned*)((const char*)(gbase) + (voff)[_i]), (PG8_LAS unsigned*)(lds + (bufoff) + ldsw + _i * 8192), 16, 0, 0); } while (0)
; #define PG8_LDA(dst, b, h) do { _Pragma("unroll") for (int m = 0; m < 4; ++m) _Pragma("unroll") for (int k = 0; k < 2; ++k) dst[m][k] = *(const PG8_LAS bf16x8*)(lds + PG8_SA(b, h) + aoff + m * 2048 + k * 1024); } while (0)
; #define PG8_MMA(ai, bj, At, Bt) do { __builtin_amdgcn_s_setprio(1); _Pragma("unroll") for (int m = 0; m < 4; ++m) _Pragma("unroll") for (int n = 0; n < 2; ++n) _Pragma("unroll") for (int k = 0; k < 2; ++k) \
;         acc[ai][bj][m][n] = __builtin_amdgcn_mfma_f32_16x16x32_bf16(Bt[n][k], At[m][k], acc[ai][bj][m][n], 0, 0, 0); __builtin_amdgcn_s_setprio(0); } while (0)
; #define PG8_WAIT_V(n) asm volatile("s_waitcnt vmcnt(" #n ")" ::: "memory")
; #define PG8_WAIT_L(n) asm volatile("s_waitcnt lgkmcnt(" #n ")" ::: "memory")
; #define PG8_BAR __builtin_amdgcn_s_barrier()
; #define PG8_SCHED __builtin_amdgcn_sched_barrier(0)
; template <class Epi, class Sched, bool ALIGN_EPI = false, bool SP2 = false>
; __device__ __forceinline__ void gemm_phase(PG8_LAS unsigned char* lds, const Gemm g, const Sched& S, const Epi& E) {
;     ...
;             PG8_WAIT_V(8); PG8_WAIT_L(0); PG8_BAR; PG8_MMA(0, 0, At, B0); PG8_MMA(0, 1, At, B1); PG8_BAR; PG8_SCHED;
;             PG8_LDA(At, 0, 1); PG8_STAGE(PG8_SB(0, 0), b2, voffB); PG8_STAGE(PG8_SB(0, 1), b2 + hstep, voffB); PG8_STAGE(PG8_SA(0, 0), a2, voffA);
;             PG8_WAIT_V(8); PG8_WAIT_L(0); PG8_BAR; PG8_MMA(1, 0, At, B0); PG8_MMA(1, 1, At, B1); PG8_BAR; PG8_SCHED;
.Lrx19_0_join:
	s_waitcnt lgkmcnt(0)
	s_barrier
	s_setprio 1
	s_waitcnt lgkmcnt(0)
	v_mfma_f32_16x16x32_bf16 v[124:127], v[146:149], v[178:181], v[124:127]
	v_mfma_f32_16x16x32_bf16 v[120:123], v[154:157], v[178:181], v[120:123]
	v_mfma_f32_16x16x32_bf16 v[116:119], v[146:149], v[186:189], v[116:119]
	v_mfma_f32_16x16x32_bf16 v[108:111], v[154:157], v[186:189], v[108:111]
	v_mfma_f32_16x16x32_bf16 v[100:103], v[146:149], v[214:217], v[100:103]
	v_mfma_f32_16x16x32_bf16 v[92:95], v[154:157], v[214:217], v[92:95]
	v_mfma_f32_16x16x32_bf16 v[84:87], v[146:149], v[224:227], v[84:87]
	v_mfma_f32_16x16x32_bf16 v[76:79], v[154:157], v[224:227], v[76:79]
	v_mfma_f32_16x16x32_bf16 v[124:127], v[150:153], v[182:185], v[124:127]
	v_mfma_f32_16x16x32_bf16 v[120:123], v[158:161], v[182:185], v[120:123]
	v_mfma_f32_16x16x32_bf16 v[116:119], v[150:153], v[190:193], v[116:119]
	v_mfma_f32_16x16x32_bf16 v[108:111], v[158:161], v[190:193], v[108:111]
	v_mfma_f32_16x16x32_bf16 v[100:103], v[150:153], v[220:223], v[100:103]
	v_mfma_f32_16x16x32_bf16 v[92:95], v[158:161], v[220:223], v[92:95]
	v_mfma_f32_16x16x32_bf16 v[84:87], v[150:153], v[228:231], v[84:87]
	v_mfma_f32_16x16x32_bf16 v[76:79], v[158:161], v[228:231], v[76:79]
	s_setprio 0
	s_setprio 1
	v_mfma_f32_16x16x32_bf16 v[112:115], v[162:165], v[178:181], v[112:115]
	v_mfma_f32_16x16x32_bf16 v[104:107], v[170:173], v[178:181], v[104:107]
	v_mfma_f32_16x16x32_bf16 v[96:99], v[162:165], v[186:189], v[96:99]
	v_mfma_f32_16x16x32_bf16 v[88:91], v[170:173], v[186:189], v[88:91]
	v_mfma_f32_16x16x32_bf16 v[80:83], v[162:165], v[214:217], v[80:83]
	v_mfma_f32_16x16x32_bf16 v[72:75], v[170:173], v[214:217], v[72:75]
	v_mfma_f32_16x16x32_bf16 v[68:71], v[162:165], v[224:227], v[68:71]
	v_mfma_f32_16x16x32_bf16 v[64:67], v[170:173], v[224:227], v[64:67]
	v_mfma_f32_16x16x32_bf16 v[112:115], v[166:169], v[182:185], v[112:115]
	v_mfma_f32_16x16x32_bf16 v[104:107], v[174:177], v[182:185], v[104:107]
	v_mfma_f32_16x16x32_bf16 v[96:99], v[166:169], v[190:193], v[96:99]
	v_mfma_f32_16x16x32_bf16 v[88:91], v[174:177], v[190:193], v[88:91]
	v_mfma_f32_16x16x32_bf16 v[80:83], v[166:169], v[220:223], v[80:83]
	v_mfma_f32_16x16x32_bf16 v[72:75], v[174:177], v[220:223], v[72:75]
	v_mfma_f32_16x16x32_bf16 v[68:71], v[166:169], v[228:231], v[68:71]
	v_mfma_f32_16x16x32_bf16 v[64:67], v[174:177], v[228:231], v[64:67]
	s_setprio 0
	s_barrier
	s_add_i32 s62, s62, s2
	v_lshl_add_u64 v[140:141], s[58:59], 0, v[128:129]
	s_mov_b32 m0, s62
	ds_read_b128 v[178:181], v145 offset:16384
	ds_read_b128 v[182:185], v145 offset:17408
	ds_read_b128 v[186:189], v145 offset:18432
	ds_read_b128 v[190:193], v145 offset:19456
	ds_read_b128 v[214:217], v145 offset:20480
	ds_read_b128 v[220:223], v145 offset:21504
	ds_read_b128 v[224:227], v145 offset:22528
	ds_read_b128 v[228:231], v145 offset:23552
	global_load_lds_dwordx4 v[140:141], off
	s_add_i32 m0, s62, 0x2000
	s_add_u32 s62, s58, 0x80000
	v_lshl_add_u64 v[206:207], s[58:59], 0, v[130:131]
	s_addc_u32 s63, s59, 0
	s_add_i32 s7, s7, s2
	global_load_lds_dwordx4 v[206:207], off
	v_lshl_add_u64 v[232:233], s[62:63], 0, v[128:129]
	s_mov_b32 m0, s7
	v_lshl_add_u64 v[234:235], s[60:61], 0, v[132:133]
	global_load_lds_dwordx4 v[232:233], off
	v_lshl_add_u64 v[232:233], s[62:63], 0, v[130:131]
	s_add_i32 m0, s7, 0x2000
	s_nop 0
	global_load_lds_dwordx4 v[232:233], off
	v_lshl_add_u64 v[232:233], s[60:61], 0, v[134:135]
	s_mov_b32 m0, s10
	s_nop 0
	global_load_lds_dwordx4 v[232:233], off
	s_mov_b32 m0, s17
	s_nop 0
	global_load_lds_dwordx4 v[234:235], off
	s_cmp_lt_i32 s51, 0
	s_cbranch_scc0 .Lrx19_1_norm
	s_cmp_lt_u32 s33, 2
	s_cbranch_scc1 .Lrx19_1_norm
	s_waitcnt vmcnt(24)
	s_branch .Lrx19_1_join

; #define PG8_STAGE(bufoff, gbase, voff) do { _Pragma("unroll") for (int _i = 0; _i < 2; ++_i) \
;         __builtin_amdgcn_global_load_lds((const unsigned*)((const char*)(gbase) + (voff)[_i]), (PG8_LAS unsigned*)(lds + (bufoff) + ldsw + _i * 8192), 16, 0, 0); } while (0)
; #define PG8_LDA(dst, b, h) do { _Pragma("unroll") for (int m = 0; m < 4; ++m) _Pragma("unroll") for (int k = 0; k < 2; ++k) dst[m][k] = *(const PG8_LAS bf16x8*)(lds + PG8_SA(b, h) + aoff + m * 2048 + k * 1024); } while (0)
; #define PG8_LDB(dst, b, h) do { _Pragma("unroll") for (int n = 0; n < 2; ++n) _Pragma("unroll") for (int k = 0; k < 2; ++k) dst[n][k] = *(const PG8_LAS bf16x8*)(lds + PG8_SB(b, h) + boff + n * 2048 + k * 1024); } while (0)
; #define PG8_MMA(ai, bj, At, Bt) do { __builtin_amdgcn_s_setprio(1); _Pragma("unroll") for (int m = 0; m < 4; ++m) _Pragma("unroll") for (int n = 0; n < 2; ++n) _Pragma("unroll") for (int k = 0; k < 2; ++k) \
;         acc[ai][bj][m][n] = __builtin_amdgcn_mfma_f32_16x16x32_bf16(Bt[n][k], At[m][k], acc[ai][bj][m][n], 0, 0, 0); __builtin_amdgcn_s_setprio(0); } while (0)
; #define PG8_WAIT_V(n) asm volatile("s_waitcnt vmcnt(" #n ")" ::: "memory")
; #define PG8_WAIT_L(n) asm volatile("s_waitcnt lgkmcnt(" #n ")" ::: "memory")
; #define PG8_BAR __builtin_amdgcn_s_barrier()
; #define PG8_SCHED __builtin_amdgcn_sched_barrier(0)
; template <class Epi, class Sched, bool ALIGN_EPI = false, bool SP2 = false>
; __device__ __forceinline__ void gemm_phase(PG8_LAS unsigned char* lds, const Gemm g, const Sched& S, const Epi& E) {
;     ...
;             PG8_WAIT_V(8); PG8_WAIT_L(0); PG8_BAR; PG8_MMA(1, 0, At, B0); PG8_MMA(1, 1, At, B1); PG8_BAR; PG8_SCHED;
;             PG8_LDB(B0, 1, 0); PG8_LDB(B1, 1, 1); PG8_SCHED; PG8_LDA(At, 1, 0); PG8_STAGE(PG8_SA(0, 1), a2 + hstep, voffA);
;             PG8_WAIT_V(8); PG8_WAIT_L(0); PG8_BAR; PG8_MMA(0, 0, At, B0); PG8_MMA(0, 1, At, B1); PG8_BAR; PG8_SCHED;
.Lrx19_1_join:
	s_waitcnt lgkmcnt(0)
	s_barrier
	s_setprio 1
	s_waitcnt lgkmcnt(0)
	v_mfma_f32_16x16x32_bf16 v[60:63], v[146:149], v[178:181], v[60:63]
	v_mfma_f32_16x16x32_bf16 v[56:59], v[154:157], v[178:181], v[56:59]
	v_mfma_f32_16x16x32_bf16 v[52:55], v[146:149], v[186:189], v[52:55]
	v_mfma_f32_16x16x32_bf16 v[44:47], v[154:157], v[186:189], v[44:47]
	v_mfma_f32_16x16x32_bf16 v[36:39], v[146:149], v[214:217], v[36:39]
	v_mfma_f32_16x16x32_bf16 v[28:31], v[154:157], v[214:217], v[28:31]
	v_mfma_f32_16x16x32_bf16 v[20:23], v[146:149], v[224:227], v[20:23]
	v_mfma_f32_16x16x32_bf16 v[12:15], v[154:157], v[224:227], v[12:15]
	v_mfma_f32_16x16x32_bf16 v[60:63], v[150:153], v[182:185], v[60:63]
	v_mfma_f32_16x16x32_bf16 v[56:59], v[158:161], v[182:185], v[56:59]
	v_mfma_f32_16x16x32_bf16 v[52:55], v[150:153], v[190:193], v[52:55]
	v_mfma_f32_16x16x32_bf16 v[44:47], v[158:161], v[190:193], v[44:47]
	v_mfma_f32_16x16x32_bf16 v[36:39], v[150:153], v[220:223], v[36:39]
	v_mfma_f32_16x16x32_bf16 v[28:31], v[158:161], v[220:223], v[28:31]
	v_mfma_f32_16x16x32_bf16 v[20:23], v[150:153], v[228:231], v[20:23]
	v_mfma_f32_16x16x32_bf16 v[12:15], v[158:161], v[228:231], v[12:15]
	s_setprio 0
	s_setprio 1
	v_mfma_f32_16x16x32_bf16 v[48:51], v[162:165], v[178:181], v[48:51]
	v_mfma_f32_16x16x32_bf16 v[40:43], v[170:173], v[178:181], v[40:43]
	v_mfma_f32_16x16x32_bf16 v[32:35], v[162:165], v[186:189], v[32:35]
	v_mfma_f32_16x16x32_bf16 v[24:27], v[170:173], v[186:189], v[24:27]
	v_mfma_f32_16x16x32_bf16 v[16:19], v[162:165], v[214:217], v[16:19]
	v_mfma_f32_16x16x32_bf16 v[8:11], v[170:173], v[214:217], v[8:11]
	v_mfma_f32_16x16x32_bf16 v[4:7], v[162:165], v[224:227], v[4:7]
	v_mfma_f32_16x16x32_bf16 v[0:3], v[170:173], v[224:227], v[0:3]
	v_mfma_f32_16x16x32_bf16 v[48:51], v[166:169], v[182:185], v[48:51]
	v_mfma_f32_16x16x32_bf16 v[40:43], v[174:177], v[182:185], v[40:43]
	v_mfma_f32_16x16x32_bf16 v[32:35], v[166:169], v[190:193], v[32:35]
	v_mfma_f32_16x16x32_bf16 v[24:27], v[174:177], v[190:193], v[24:27]
	v_mfma_f32_16x16x32_bf16 v[16:19], v[166:169], v[220:223], v[16:19]
	v_mfma_f32_16x16x32_bf16 v[8:11], v[174:177], v[220:223], v[8:11]
	v_mfma_f32_16x16x32_bf16 v[4:7], v[166:169], v[228:231], v[4:7]
	v_mfma_f32_16x16x32_bf16 v[0:3], v[174:177], v[228:231], v[0:3]
	s_setprio 0
	s_barrier
	s_add_i32 s7, 0, 0x18000
	s_add_i32 s62, 0, 0x1c000
	v_add_u32_e32 v158, s7, v143
	v_add_u32_e32 v174, s62, v143
	ds_read_b128 v[146:149], v158
	ds_read_b128 v[150:153], v158 offset:1024
	ds_read_b128 v[154:157], v158 offset:2048
	ds_read_b128 v[158:161], v158 offset:3072
	ds_read_b128 v[162:165], v174
	ds_read_b128 v[166:169], v174 offset:1024
	ds_read_b128 v[170:173], v174 offset:2048
	ds_read_b128 v[174:177], v174 offset:3072
	s_add_u32 s60, s60, 0x200000
	s_addc_u32 s61, s61, 0
	s_mov_b32 m0, s26
	v_lshl_add_u64 v[236:237], s[60:61], 0, v[134:135]
	ds_read_b128 v[178:181], v145 offset:32768
	ds_read_b128 v[182:185], v145 offset:33792
	ds_read_b128 v[186:189], v145 offset:34816
	ds_read_b128 v[190:193], v145 offset:35840
	ds_read_b128 v[214:217], v145 offset:36864
	ds_read_b128 v[220:223], v145 offset:37888
	ds_read_b128 v[224:227], v145 offset:38912
	ds_read_b128 v[228:231], v145 offset:39936
	global_load_lds_dwordx4 v[236:237], off
	v_lshl_add_u64 v[236:237], s[60:61], 0, v[132:133]
	s_mov_b32 m0, s27
	s_nop 0
	global_load_lds_dwordx4 v[236:237], off
	s_waitcnt vmcnt(8)
	s_waitcnt lgkmcnt(0)
	s_barrier
	s_setprio 1
	s_waitcnt lgkmcnt(0)
	v_mfma_f32_16x16x32_bf16 v[124:127], v[146:149], v[178:181], v[124:127]
	v_mfma_f32_16x16x32_bf16 v[120:123], v[154:157], v[178:181], v[120:123]
	v_mfma_f32_16x16x32_bf16 v[116:119], v[146:149], v[186:189], v[116:119]
	v_mfma_f32_16x16x32_bf16 v[108:111], v[154:157], v[186:189], v[108:111]
	v_mfma_f32_16x16x32_bf16 v[100:103], v[146:149], v[214:217], v[100:103]
	v_mfma_f32_16x16x32_bf16 v[92:95], v[154:157], v[214:217], v[92:95]
	v_mfma_f32_16x16x32_bf16 v[84:87], v[146:149], v[224:227], v[84:87]
	v_mfma_f32_16x16x32_bf16 v[76:79], v[154:157], v[224:227], v[76:79]
	v_mfma_f32_16x16x32_bf16 v[124:127], v[150:153], v[182:185], v[124:127]
	v_mfma_f32_16x16x32_bf16 v[120:123], v[158:161], v[182:185], v[120:123]
	v_mfma_f32_16x16x32_bf16 v[116:119], v[150:153], v[190:193], v[116:119]
	v_mfma_f32_16x16x32_bf16 v[108:111], v[158:161], v[190:193], v[108:111]
	v_mfma_f32_16x16x32_bf16 v[100:103], v[150:153], v[220:223], v[100:103]
	v_mfma_f32_16x16x32_bf16 v[92:95], v[158:161], v[220:223], v[92:95]
	v_mfma_f32_16x16x32_bf16 v[84:87], v[150:153], v[228:231], v[84:87]
	v_mfma_f32_16x16x32_bf16 v[76:79], v[158:161], v[228:231], v[76:79]
	s_setprio 0
	s_setprio 1
	v_mfma_f32_16x16x32_bf16 v[112:115], v[162:165], v[178:181], v[112:115]
	v_mfma_f32_16x16x32_bf16 v[104:107], v[170:173], v[178:181], v[104:107]
	v_mfma_f32_16x16x32_bf16 v[96:99], v[162:165], v[186:189], v[96:99]
	v_mfma_f32_16x16x32_bf16 v[88:91], v[170:173], v[186:189], v[88:91]
	v_mfma_f32_16x16x32_bf16 v[80:83], v[162:165], v[214:217], v[80:83]
	v_mfma_f32_16x16x32_bf16 v[72:75], v[170:173], v[214:217], v[72:75]
	v_mfma_f32_16x16x32_bf16 v[68:71], v[162:165], v[224:227], v[68:71]
	v_mfma_f32_16x16x32_bf16 v[64:67], v[170:173], v[224:227], v[64:67]
	v_mfma_f32_16x16x32_bf16 v[112:115], v[166:169], v[182:185], v[112:115]
	v_mfma_f32_16x16x32_bf16 v[104:107], v[174:177], v[182:185], v[104:107]
	v_mfma_f32_16x16x32_bf16 v[96:99], v[166:169], v[190:193], v[96:99]
	v_mfma_f32_16x16x32_bf16 v[88:91], v[174:177], v[190:193], v[88:91]
	v_mfma_f32_16x16x32_bf16 v[80:83], v[166:169], v[220:223], v[80:83]
	v_mfma_f32_16x16x32_bf16 v[72:75], v[174:177], v[220:223], v[72:75]
	v_mfma_f32_16x16x32_bf16 v[68:71], v[166:169], v[228:231], v[68:71]
	v_mfma_f32_16x16x32_bf16 v[64:67], v[174:177], v[228:231], v[64:67]
	s_setprio 0
	s_barrier
; __device__ __forceinline__ u32x4 pack8_bf16(f32x4 a, f32x4 b) { u32x4 w; w.x = cvt_pk_bf16(a[0], a[1]); w.y = cvt_pk_bf16(a[2], a[3]); w.z = cvt_pk_bf16(b[0], b[1]); w.w = cvt_pk_bf16(b[2], b[3]); return w; }
; #define PG8_STAGE(bufoff, gbase, voff) do { _Pragma("unroll") for (int _i = 0; _i < 2; ++_i) \
;         __builtin_amdgcn_global_load_lds((const unsigned*)((const char*)(gbase) + (voff)[_i]), (PG8_LAS unsigned*)(lds + (bufoff) + ldsw + _i * 8192), 16, 0, 0); } while (0)
; #define PG8_LDA(dst, b, h) do { _Pragma("unroll") for (int m = 0; m < 4; ++m) _Pragma("unroll") for (int k = 0; k < 2; ++k) dst[m][k] = *(const PG8_LAS bf16x8*)(lds + PG8_SA(b, h) + aoff + m * 2048 + k * 1024); } while (0)
; #define PG8_WAIT_V(n) asm volatile("s_waitcnt vmcnt(" #n ")" ::: "memory")
; #define PG8_WAIT_L(n) asm volatile("s_waitcnt lgkmcnt(" #n ")" ::: "memory")
;     __device__ __forceinline__ void operator()(const f32x4 (&acc)[2][2][4][2], const Unit& u, int wr, int wc, int fr, int fq) const {
;         const int g = u.pn / nNper, pnl = u.pn - g * nNper, pml = u.pm & 63;
;         bf16_t* base = O + (size_t)g * gstride;
;         const int row0 = pml * BM + wr * 64 + fr, col0 = pnl * BM + wc * 32 + 8 * fq;
; #pragma unroll
;         for (int ai = 0; ai < 2; ++ai)
; #pragma unroll
;             for (int m = 0; m < 4; ++m) { bf16_t* rowp = base + (size_t)(row0 + ai * HALF + m * 16) * ldc + col0;
; #pragma unroll
;                 for (int bj = 0; bj < 2; ++bj) { f32x4 v0 = acc[ai][bj][m][0], v1 = acc[ai][bj][m][1];
;                     if (ACT == 1) {
; #pragma unroll
;                         for (int j = 0; j < 4; ++j) { float a = fmaxf(v0[j], 0.f), b = fmaxf(v1[j], 0.f); v0[j] = a * a; v1[j] = b * b; } }
;                     *(u32x4*)(rowp + bj * HALF) = pack8_bf16(v0, v1); } }
; template <class Epi, class Sched, bool ALIGN_EPI = false, bool SP2 = false>
; __device__ __forceinline__ void gemm_phase(PG8_LAS unsigned char* lds, const Gemm g, const Sched& S, const Epi& E) {
;     ...
;             PG8_WAIT_V(8); PG8_WAIT_L(0); PG8_BAR; PG8_MMA(0, 0, At, B0); PG8_MMA(0, 1, At, B1); PG8_BAR; PG8_SCHED;
;             PG8_LDA(At, 1, 1); PG8_STAGE(PG8_SB(1, 0), b3, voffB); PG8_STAGE(PG8_SB(1, 1), b3 + hstep, voffB); PG8_STAGE(PG8_SA(1, 0), a3, voffA);
;             PG8_WAIT_V(8); PG8_WAIT_L(0); PG8_BAR; PG8_MMA(1, 0, At, B0); PG8_MMA(1, 1, At, B1); PG8_BAR; PG8_SCHED;
	s_add_i32 s7, s7, s2
	v_lshl_add_u64 v[140:141], v[140:141], 0, s[20:21]
	s_mov_b32 m0, s7
	ds_read_b128 v[178:181], v145 offset:49152
	ds_read_b128 v[182:185], v145 offset:50176
	ds_read_b128 v[186:189], v145 offset:51200
	ds_read_b128 v[190:193], v145 offset:52224
	ds_read_b128 v[214:217], v145 offset:53248
	ds_read_b128 v[220:223], v145 offset:54272
	ds_read_b128 v[224:227], v145 offset:55296
	ds_read_b128 v[228:231], v145 offset:56320
	global_load_lds_dwordx4 v[140:141], off
	s_add_i32 m0, s7, 0x2000
	s_add_u32 s58, s58, 0x80080
	v_lshl_add_u64 v[140:141], v[206:207], 0, s[20:21]
	s_addc_u32 s59, s59, 0
	s_add_i32 s7, s62, s2
	global_load_lds_dwordx4 v[140:141], off
	v_lshl_add_u64 v[140:141], s[58:59], 0, v[128:129]
	s_mov_b32 m0, s7
	s_nop 0
	global_load_lds_dwordx4 v[140:141], off
	v_lshl_add_u64 v[140:141], s[58:59], 0, v[130:131]
	s_add_i32 m0, s7, 0x2000
	s_nop 0
	global_load_lds_dwordx4 v[140:141], off
	v_lshl_add_u64 v[140:141], v[232:233], 0, s[20:21]
	s_mov_b32 m0, s28
	s_nop 0
	global_load_lds_dwordx4 v[140:141], off
	v_lshl_add_u64 v[140:141], v[234:235], 0, s[20:21]
	s_mov_b32 m0, s29
	s_nop 0
	global_load_lds_dwordx4 v[140:141], off
	s_waitcnt vmcnt(8)
	s_waitcnt lgkmcnt(0)
	s_barrier
	s_setprio 1
	s_waitcnt lgkmcnt(0)
	v_mfma_f32_16x16x32_bf16 v[60:63], v[146:149], v[178:181], v[60:63]
	v_mfma_f32_16x16x32_bf16 v[56:59], v[154:157], v[178:181], v[56:59]
	v_mfma_f32_16x16x32_bf16 v[52:55], v[146:149], v[186:189], v[52:55]
	v_mfma_f32_16x16x32_bf16 v[44:47], v[154:157], v[186:189], v[44:47]
	v_mfma_f32_16x16x32_bf16 v[36:39], v[146:149], v[214:217], v[36:39]
	v_mfma_f32_16x16x32_bf16 v[28:31], v[154:157], v[214:217], v[28:31]
	v_mfma_f32_16x16x32_bf16 v[20:23], v[146:149], v[224:227], v[20:23]
	v_mfma_f32_16x16x32_bf16 v[12:15], v[154:157], v[224:227], v[12:15]
	v_mfma_f32_16x16x32_bf16 v[60:63], v[150:153], v[182:185], v[60:63]
	v_mfma_f32_16x16x32_bf16 v[56:59], v[158:161], v[182:185], v[56:59]
	v_mfma_f32_16x16x32_bf16 v[52:55], v[150:153], v[190:193], v[52:55]
	v_mfma_f32_16x16x32_bf16 v[44:47], v[158:161], v[190:193], v[44:47]
	v_mfma_f32_16x16x32_bf16 v[36:39], v[150:153], v[220:223], v[36:39]
	v_mfma_f32_16x16x32_bf16 v[28:31], v[158:161], v[220:223], v[28:31]
	v_mfma_f32_16x16x32_bf16 v[20:23], v[150:153], v[228:231], v[20:23]
	v_mfma_f32_16x16x32_bf16 v[12:15], v[158:161], v[228:231], v[12:15]
	s_setprio 0
	s_setprio 1
	v_mfma_f32_16x16x32_bf16 v[48:51], v[162:165], v[178:181], v[48:51]
	v_mfma_f32_16x16x32_bf16 v[40:43], v[170:173], v[178:181], v[40:43]
	v_mfma_f32_16x16x32_bf16 v[32:35], v[162:165], v[186:189], v[32:35]
	v_mfma_f32_16x16x32_bf16 v[24:27], v[170:173], v[186:189], v[24:27]
	v_mfma_f32_16x16x32_bf16 v[16:19], v[162:165], v[214:217], v[16:19]
	v_mfma_f32_16x16x32_bf16 v[8:11], v[170:173], v[214:217], v[8:11]
	v_mfma_f32_16x16x32_bf16 v[4:7], v[162:165], v[224:227], v[4:7]
	v_mfma_f32_16x16x32_bf16 v[0:3], v[170:173], v[224:227], v[0:3]
	v_mfma_f32_16x16x32_bf16 v[48:51], v[166:169], v[182:185], v[48:51]
	v_mfma_f32_16x16x32_bf16 v[40:43], v[174:177], v[182:185], v[40:43]
	v_mfma_f32_16x16x32_bf16 v[32:35], v[166:169], v[190:193], v[32:35]
	v_mfma_f32_16x16x32_bf16 v[24:27], v[174:177], v[190:193], v[24:27]
	v_mfma_f32_16x16x32_bf16 v[16:19], v[166:169], v[220:223], v[16:19]
	v_mfma_f32_16x16x32_bf16 v[8:11], v[174:177], v[220:223], v[8:11]
	v_mfma_f32_16x16x32_bf16 v[4:7], v[166:169], v[228:231], v[4:7]
	v_mfma_f32_16x16x32_bf16 v[0:3], v[174:177], v[228:231], v[0:3]
	s_setprio 0
	s_barrier
	s_add_i32 s51, s51, 2
	s_add_u32 s56, s56, 0x100
	s_addc_u32 s57, s57, 0
	s_add_u32 s47, s47, 0x100
	s_addc_u32 s49, s49, 0
	s_cmpk_gt_u32 s51, 0x7d
	s_cbranch_scc0 .LBB0_37
	s_and_b64 vcc, exec, s[42:43]
	s_cbranch_vccz .LBB0_40
	s_barrier
.LBB0_40:
	s_ashr_i32 s7, s50, 31
	s_lshr_b32 s7, s7, 29
	s_add_i32 s7, s50, s7
	s_and_b32 s7, s7, 0xfffff8
	s_lshl_b32 s34, s48, 8
	s_sub_i32 s7, s50, s7
	s_and_b32 s34, s34, 0x3f00
	v_add_u32_e32 v146, s34, v142
	v_lshl_or_b32 v140, s7, 8, v144
	v_ashrrev_i32_e32 v141, 31, v140
	v_ashrrev_i32_e32 v147, 31, v146
	v_lshl_add_u64 v[148:149], v[140:141], 1, s[12:13]
	v_lshlrev_b64 v[140:141], 12, v[146:147]
	v_lshl_add_u64 v[140:141], v[148:149], 0, v[140:141]
	s_mov_b64 s[34:35], 0x10000
	v_mov_b32_e32 v242, 0x8000
	v_mov_b32_e32 v243, 0
	v_and_b32_e32 v238, 8, v208
	v_cmp_ne_u32_e32 vcc, 0, v238
	v_and_b32_e32 v240, 63, v208
	v_lshrrev_b32_e32 v241, 3, v240
	v_and_b32_e32 v244, 3, v240
	v_lshl_add_u32 v241, v244, 4, v241
	v_and_b32_e32 v244, 4, v240
	v_lshl_add_u32 v241, v244, 1, v241
	v_lshlrev_b32_e32 v240, 2, v241
	v_cvt_pk_bf16_f32 v124, v124, v125
	v_cvt_pk_bf16_f32 v125, v126, v127
	v_cvt_pk_bf16_f32 v126, v120, v121
	v_cvt_pk_bf16_f32 v127, v122, v123
	v_cvt_pk_bf16_f32 v112, v112, v113
	v_cvt_pk_bf16_f32 v113, v114, v115
	v_cvt_pk_bf16_f32 v114, v104, v105
	v_cvt_pk_bf16_f32 v115, v106, v107
	v_mov_b32_dpp v246, v112 row_ror:8 row_mask:0xf bank_mask:0xf
	v_mov_b32_dpp v247, v113 row_ror:8 row_mask:0xf bank_mask:0xf
	v_mov_b32_dpp v248, v114 row_ror:8 row_mask:0xf bank_mask:0xf
	v_mov_b32_dpp v249, v115 row_ror:8 row_mask:0xf bank_mask:0xf
	v_mov_b32_dpp v250, v124 row_ror:8 row_mask:0xf bank_mask:0xf
	v_mov_b32_dpp v251, v125 row_ror:8 row_mask:0xf bank_mask:0xf
	v_mov_b32_dpp v252, v126 row_ror:8 row_mask:0xf bank_mask:0xf
	v_mov_b32_dpp v253, v127 row_ror:8 row_mask:0xf bank_mask:0xf
	v_cndmask_b32_e32 v246, v124, v246, vcc
	v_cndmask_b32_e32 v247, v125, v247, vcc
	v_cndmask_b32_e32 v248, v126, v248, vcc
	v_cndmask_b32_e32 v249, v127, v249, vcc
	v_cndmask_b32_e32 v250, v250, v112, vcc
	v_cndmask_b32_e32 v251, v251, v113, vcc
	v_cndmask_b32_e32 v252, v252, v114, vcc
	v_cndmask_b32_e32 v253, v253, v115, vcc
	ds_bpermute_b32 v246, v240, v246
	ds_bpermute_b32 v247, v240, v247
	ds_bpermute_b32 v248, v240, v248
	ds_bpermute_b32 v249, v240, v249
	ds_bpermute_b32 v250, v240, v250
	ds_bpermute_b32 v251, v240, v251
	ds_bpermute_b32 v252, v240, v252
	ds_bpermute_b32 v253, v240, v253
	v_lshl_add_u64 v[238:239], v[140:141], 0, v[242:243]
	s_waitcnt lgkmcnt(4)
; __device__ __forceinline__ u32x4 pack8_bf16(f32x4 a, f32x4 b) { u32x4 w; w.x = cvt_pk_bf16(a[0], a[1]); w.y = cvt_pk_bf16(a[2], a[3]); w.z = cvt_pk_bf16(b[0], b[1]); w.w = cvt_pk_bf16(b[2], b[3]); return w; }
; #define ACT(t) (KBASE(t) <= qlo + QBLK - 1 && KBASE(t) + KVBLK - 1 >= qlo - W + 1)
;     __device__ __forceinline__ void operator()(const f32x4 (&acc)[2][2][4][2], const Unit& u, int wr, int wc, int fr, int fq) const {
;         const int g = u.pn / nNper, pnl = u.pn - g * nNper, pml = u.pm & 63;
;         bf16_t* base = O + (size_t)g * gstride;
;         const int row0 = pml * BM + wr * 64 + fr, col0 = pnl * BM + wc * 32 + 8 * fq;
; #pragma unroll
;         for (int ai = 0; ai < 2; ++ai)
; #pragma unroll
;             for (int m = 0; m < 4; ++m) { bf16_t* rowp = base + (size_t)(row0 + ai * HALF + m * 16) * ldc + col0;
; #pragma unroll
;                 for (int bj = 0; bj < 2; ++bj) { f32x4 v0 = acc[ai][bj][m][0], v1 = acc[ai][bj][m][1];
;                     if (ACT == 1) {
; #pragma unroll
;                         for (int j = 0; j < 4; ++j) { float a = fmaxf(v0[j], 0.f), b = fmaxf(v1[j], 0.f); v0[j] = a * a; v1[j] = b * b; } }
;                     *(u32x4*)(rowp + bj * HALF) = pack8_bf16(v0, v1); } }
	global_store_dwordx4 v[140:141], v[246:249], off
	s_waitcnt lgkmcnt(0)
	global_store_dwordx4 v[238:239], v[250:253], off
	v_lshl_add_u64 v[140:141], v[140:141], 0, s[34:35]
	v_cvt_pk_bf16_f32 v116, v116, v117
	v_cvt_pk_bf16_f32 v117, v118, v119
	v_cvt_pk_bf16_f32 v118, v108, v109
	v_cvt_pk_bf16_f32 v119, v110, v111
	v_cvt_pk_bf16_f32 v96, v96, v97
	v_cvt_pk_bf16_f32 v97, v98, v99
	v_cvt_pk_bf16_f32 v98, v88, v89
	v_cvt_pk_bf16_f32 v99, v90, v91
	v_mov_b32_dpp v246, v96 row_ror:8 row_mask:0xf bank_mask:0xf
	v_mov_b32_dpp v247, v97 row_ror:8 row_mask:0xf bank_mask:0xf
	v_mov_b32_dpp v248, v98 row_ror:8 row_mask:0xf bank_mask:0xf
	v_mov_b32_dpp v249, v99 row_ror:8 row_mask:0xf bank_mask:0xf
	v_mov_b32_dpp v250, v116 row_ror:8 row_mask:0xf bank_mask:0xf
	v_mov_b32_dpp v251, v117 row_ror:8 row_mask:0xf bank_mask:0xf
	v_mov_b32_dpp v252, v118 row_ror:8 row_mask:0xf bank_mask:0xf
	v_mov_b32_dpp v253, v119 row_ror:8 row_mask:0xf bank_mask:0xf
	v_cndmask_b32_e32 v246, v116, v246, vcc
	v_cndmask_b32_e32 v247, v117, v247, vcc
	v_cndmask_b32_e32 v248, v118, v248, vcc
	v_cndmask_b32_e32 v249, v119, v249, vcc
	v_cndmask_b32_e32 v250, v250, v96, vcc
	v_cndmask_b32_e32 v251, v251, v97, vcc
	v_cndmask_b32_e32 v252, v252, v98, vcc
	v_cndmask_b32_e32 v253, v253, v99, vcc
	ds_bpermute_b32 v246, v240, v246
	ds_bpermute_b32 v247, v240, v247
	ds_bpermute_b32 v248, v240, v248
	ds_bpermute_b32 v249, v240, v249
	ds_bpermute_b32 v250, v240, v250
	ds_bpermute_b32 v251, v240, v251
	ds_bpermute_b32 v252, v240, v252
	ds_bpermute_b32 v253, v240, v253
	v_lshl_add_u64 v[238:239], v[140:141], 0, v[242:243]
	s_waitcnt lgkmcnt(4)
	global_store_dwordx4 v[140:141], v[246:249], off
	s_waitcnt lgkmcnt(0)
	global_store_dwordx4 v[238:239], v[250:253], off
	v_lshl_add_u64 v[140:141], v[140:141], 0, s[34:35]
	v_cvt_pk_bf16_f32 v100, v100, v101
	v_cvt_pk_bf16_f32 v101, v102, v103
	v_cvt_pk_bf16_f32 v102, v92, v93
	v_cvt_pk_bf16_f32 v103, v94, v95
	v_cvt_pk_bf16_f32 v80, v80, v81
	v_cvt_pk_bf16_f32 v81, v82, v83
	v_cvt_pk_bf16_f32 v82, v72, v73
	v_cvt_pk_bf16_f32 v83, v74, v75
	v_mov_b32_dpp v246, v80 row_ror:8 row_mask:0xf bank_mask:0xf
	v_mov_b32_dpp v247, v81 row_ror:8 row_mask:0xf bank_mask:0xf
	v_mov_b32_dpp v248, v82 row_ror:8 row_mask:0xf bank_mask:0xf
	v_mov_b32_dpp v249, v83 row_ror:8 row_mask:0xf bank_mask:0xf
	v_mov_b32_dpp v250, v100 row_ror:8 row_mask:0xf bank_mask:0xf
	v_mov_b32_dpp v251, v101 row_ror:8 row_mask:0xf bank_mask:0xf
	v_mov_b32_dpp v252, v102 row_ror:8 row_mask:0xf bank_mask:0xf
	v_mov_b32_dpp v253, v103 row_ror:8 row_mask:0xf bank_mask:0xf
	v_cndmask_b32_e32 v246, v100, v246, vcc
	v_cndmask_b32_e32 v247, v101, v247, vcc
	v_cndmask_b32_e32 v248, v102, v248, vcc
	v_cndmask_b32_e32 v249, v103, v249, vcc
	v_cndmask_b32_e32 v250, v250, v80, vcc
	v_cndmask_b32_e32 v251, v251, v81, vcc
	v_cndmask_b32_e32 v252, v252, v82, vcc
	v_cndmask_b32_e32 v253, v253, v83, vcc
	ds_bpermute_b32 v246, v240, v246
	ds_bpermute_b32 v247, v240, v247
	ds_bpermute_b32 v248, v240, v248
	ds_bpermute_b32 v249, v240, v249
	ds_bpermute_b32 v250, v240, v250
	ds_bpermute_b32 v251, v240, v251
	ds_bpermute_b32 v252, v240, v252
	ds_bpermute_b32 v253, v240, v253
	v_lshl_add_u64 v[238:239], v[140:141], 0, v[242:243]
	s_waitcnt lgkmcnt(4)
	global_store_dwordx4 v[140:141], v[246:249], off
	s_waitcnt lgkmcnt(0)
	global_store_dwordx4 v[238:239], v[250:253], off
	v_lshl_add_u64 v[140:141], v[140:141], 0, s[34:35]
	v_cvt_pk_bf16_f32 v84, v84, v85
	v_cvt_pk_bf16_f32 v85, v86, v87
	v_cvt_pk_bf16_f32 v86, v76, v77
	v_cvt_pk_bf16_f32 v87, v78, v79
	v_cvt_pk_bf16_f32 v68, v68, v69
	v_cvt_pk_bf16_f32 v69, v70, v71
	v_cvt_pk_bf16_f32 v70, v64, v65
	v_cvt_pk_bf16_f32 v71, v66, v67
	v_mov_b32_dpp v246, v68 row_ror:8 row_mask:0xf bank_mask:0xf
	v_mov_b32_dpp v247, v69 row_ror:8 row_mask:0xf bank_mask:0xf
	v_mov_b32_dpp v248, v70 row_ror:8 row_mask:0xf bank_mask:0xf
	v_mov_b32_dpp v249, v71 row_ror:8 row_mask:0xf bank_mask:0xf
	v_mov_b32_dpp v250, v84 row_ror:8 row_mask:0xf bank_mask:0xf
	v_mov_b32_dpp v251, v85 row_ror:8 row_mask:0xf bank_mask:0xf
	v_mov_b32_dpp v252, v86 row_ror:8 row_mask:0xf bank_mask:0xf
	v_mov_b32_dpp v253, v87 row_ror:8 row_mask:0xf bank_mask:0xf
	v_cndmask_b32_e32 v246, v84, v246, vcc
	v_cndmask_b32_e32 v247, v85, v247, vcc
	v_cndmask_b32_e32 v248, v86, v248, vcc
	v_cndmask_b32_e32 v249, v87, v249, vcc
	v_cndmask_b32_e32 v250, v250, v68, vcc
	v_cndmask_b32_e32 v251, v251, v69, vcc
	v_cndmask_b32_e32 v252, v252, v70, vcc
	v_cndmask_b32_e32 v253, v253, v71, vcc
	ds_bpermute_b32 v246, v240, v246
	ds_bpermute_b32 v247, v240, v247
	ds_bpermute_b32 v248, v240, v248
	ds_bpermute_b32 v249, v240, v249
	ds_bpermute_b32 v250, v240, v250
	ds_bpermute_b32 v251, v240, v251
	ds_bpermute_b32 v252, v240, v252
	ds_bpermute_b32 v253, v240, v253
	v_lshl_add_u64 v[238:239], v[140:141], 0, v[242:243]
	s_waitcnt lgkmcnt(4)
	global_store_dwordx4 v[140:141], v[246:249], off
	s_waitcnt lgkmcnt(0)
; __device__ __forceinline__ u32x4 pack8_bf16(f32x4 a, f32x4 b) { u32x4 w; w.x = cvt_pk_bf16(a[0], a[1]); w.y = cvt_pk_bf16(a[2], a[3]); w.z = cvt_pk_bf16(b[0], b[1]); w.w = cvt_pk_bf16(b[2], b[3]); return w; }
; #define ACT(t) (KBASE(t) <= qlo + QBLK - 1 && KBASE(t) + KVBLK - 1 >= qlo - W + 1)
;     __device__ __forceinline__ void operator()(const f32x4 (&acc)[2][2][4][2], const Unit& u, int wr, int wc, int fr, int fq) const {
;         const int g = u.pn / nNper, pnl = u.pn - g * nNper, pml = u.pm & 63;
;         bf16_t* base = O + (size_t)g * gstride;
;         const int row0 = pml * BM + wr * 64 + fr, col0 = pnl * BM + wc * 32 + 8 * fq;
; #pragma unroll
;         for (int ai = 0; ai < 2; ++ai)
; #pragma unroll
;             for (int m = 0; m < 4; ++m) { bf16_t* rowp = base + (size_t)(row0 + ai * HALF + m * 16) * ldc + col0;
; #pragma unroll
;                 for (int bj = 0; bj < 2; ++bj) { f32x4 v0 = acc[ai][bj][m][0], v1 = acc[ai][bj][m][1];
;                     if (ACT == 1) {
; #pragma unroll
;                         for (int j = 0; j < 4; ++j) { float a = fmaxf(v0[j], 0.f), b = fmaxf(v1[j], 0.f); v0[j] = a * a; v1[j] = b * b; } }
;                     *(u32x4*)(rowp + bj * HALF) = pack8_bf16(v0, v1); } }
	global_store_dwordx4 v[238:239], v[250:253], off
	s_mov_b64 s[34:35], 0x50000
	v_lshl_add_u64 v[140:141], v[140:141], 0, s[34:35]
	s_mov_b64 s[34:35], 0x10000
	v_cvt_pk_bf16_f32 v60, v60, v61
	v_cvt_pk_bf16_f32 v61, v62, v63
	v_cvt_pk_bf16_f32 v62, v56, v57
	v_cvt_pk_bf16_f32 v63, v58, v59
	v_cvt_pk_bf16_f32 v48, v48, v49
	v_cvt_pk_bf16_f32 v49, v50, v51
	v_cvt_pk_bf16_f32 v50, v40, v41
	v_cvt_pk_bf16_f32 v51, v42, v43
	v_mov_b32_dpp v246, v48 row_ror:8 row_mask:0xf bank_mask:0xf
	v_mov_b32_dpp v247, v49 row_ror:8 row_mask:0xf bank_mask:0xf
	v_mov_b32_dpp v248, v50 row_ror:8 row_mask:0xf bank_mask:0xf
	v_mov_b32_dpp v249, v51 row_ror:8 row_mask:0xf bank_mask:0xf
	v_mov_b32_dpp v250, v60 row_ror:8 row_mask:0xf bank_mask:0xf
	v_mov_b32_dpp v251, v61 row_ror:8 row_mask:0xf bank_mask:0xf
	v_mov_b32_dpp v252, v62 row_ror:8 row_mask:0xf bank_mask:0xf
	v_mov_b32_dpp v253, v63 row_ror:8 row_mask:0xf bank_mask:0xf
	v_cndmask_b32_e32 v246, v60, v246, vcc
	v_cndmask_b32_e32 v247, v61, v247, vcc
	v_cndmask_b32_e32 v248, v62, v248, vcc
	v_cndmask_b32_e32 v249, v63, v249, vcc
	v_cndmask_b32_e32 v250, v250, v48, vcc
	v_cndmask_b32_e32 v251, v251, v49, vcc
	v_cndmask_b32_e32 v252, v252, v50, vcc
	v_cndmask_b32_e32 v253, v253, v51, vcc
	ds_bpermute_b32 v246, v240, v246
	ds_bpermute_b32 v247, v240, v247
	ds_bpermute_b32 v248, v240, v248
	ds_bpermute_b32 v249, v240, v249
	ds_bpermute_b32 v250, v240, v250
	ds_bpermute_b32 v251, v240, v251
	ds_bpermute_b32 v252, v240, v252
	ds_bpermute_b32 v253, v240, v253
	v_lshl_add_u64 v[238:239], v[140:141], 0, v[242:243]
	s_waitcnt lgkmcnt(4)
	global_store_dwordx4 v[140:141], v[246:249], off
	s_waitcnt lgkmcnt(0)
	global_store_dwordx4 v[238:239], v[250:253], off
	v_lshl_add_u64 v[140:141], v[140:141], 0, s[34:35]
	v_cvt_pk_bf16_f32 v52, v52, v53
	v_cvt_pk_bf16_f32 v53, v54, v55
	v_cvt_pk_bf16_f32 v54, v44, v45
	v_cvt_pk_bf16_f32 v55, v46, v47
	v_cvt_pk_bf16_f32 v32, v32, v33
	v_cvt_pk_bf16_f32 v33, v34, v35
	v_cvt_pk_bf16_f32 v34, v24, v25
	v_cvt_pk_bf16_f32 v35, v26, v27
	v_mov_b32_dpp v246, v32 row_ror:8 row_mask:0xf bank_mask:0xf
	v_mov_b32_dpp v247, v33 row_ror:8 row_mask:0xf bank_mask:0xf
	v_mov_b32_dpp v248, v34 row_ror:8 row_mask:0xf bank_mask:0xf
	v_mov_b32_dpp v249, v35 row_ror:8 row_mask:0xf bank_mask:0xf
	v_mov_b32_dpp v250, v52 row_ror:8 row_mask:0xf bank_mask:0xf
	v_mov_b32_dpp v251, v53 row_ror:8 row_mask:0xf bank_mask:0xf
	v_mov_b32_dpp v252, v54 row_ror:8 row_mask:0xf bank_mask:0xf
	v_mov_b32_dpp v253, v55 row_ror:8 row_mask:0xf bank_mask:0xf
	v_cndmask_b32_e32 v246, v52, v246, vcc
	v_cndmask_b32_e32 v247, v53, v247, vcc
	v_cndmask_b32_e32 v248, v54, v248, vcc
	v_cndmask_b32_e32 v249, v55, v249, vcc
	v_cndmask_b32_e32 v250, v250, v32, vcc
	v_cndmask_b32_e32 v251, v251, v33, vcc
	v_cndmask_b32_e32 v252, v252, v34, vcc
	v_cndmask_b32_e32 v253, v253, v35, vcc
	ds_bpermute_b32 v246, v240, v246
	ds_bpermute_b32 v247, v240, v247
	ds_bpermute_b32 v248, v240, v248
	ds_bpermute_b32 v249, v240, v249
	ds_bpermute_b32 v250, v240, v250
	ds_bpermute_b32 v251, v240, v251
	ds_bpermute_b32 v252, v240, v252
	ds_bpermute_b32 v253, v240, v253
	v_lshl_add_u64 v[238:239], v[140:141], 0, v[242:243]
	s_waitcnt lgkmcnt(4)
	global_store_dwordx4 v[140:141], v[246:249], off
	s_waitcnt lgkmcnt(0)
	global_store_dwordx4 v[238:239], v[250:253], off
	v_lshl_add_u64 v[140:141], v[140:141], 0, s[34:35]
	v_cvt_pk_bf16_f32 v36, v36, v37
	v_cvt_pk_bf16_f32 v37, v38, v39
	v_cvt_pk_bf16_f32 v38, v28, v29
	v_cvt_pk_bf16_f32 v39, v30, v31
	v_cvt_pk_bf16_f32 v16, v16, v17
	v_cvt_pk_bf16_f32 v17, v18, v19
	v_cvt_pk_bf16_f32 v18, v8, v9
	v_cvt_pk_bf16_f32 v19, v10, v11
	v_mov_b32_dpp v246, v16 row_ror:8 row_mask:0xf bank_mask:0xf
	v_mov_b32_dpp v247, v17 row_ror:8 row_mask:0xf bank_mask:0xf
	v_mov_b32_dpp v248, v18 row_ror:8 row_mask:0xf bank_mask:0xf
	v_mov_b32_dpp v249, v19 row_ror:8 row_mask:0xf bank_mask:0xf
	v_mov_b32_dpp v250, v36 row_ror:8 row_mask:0xf bank_mask:0xf
	v_mov_b32_dpp v251, v37 row_ror:8 row_mask:0xf bank_mask:0xf
	v_mov_b32_dpp v252, v38 row_ror:8 row_mask:0xf bank_mask:0xf
	v_mov_b32_dpp v253, v39 row_ror:8 row_mask:0xf bank_mask:0xf
	v_cndmask_b32_e32 v246, v36, v246, vcc
	v_cndmask_b32_e32 v247, v37, v247, vcc
	v_cndmask_b32_e32 v248, v38, v248, vcc
	v_cndmask_b32_e32 v249, v39, v249, vcc
	v_cndmask_b32_e32 v250, v250, v16, vcc
	v_cndmask_b32_e32 v251, v251, v17, vcc
	v_cndmask_b32_e32 v252, v252, v18, vcc
	v_cndmask_b32_e32 v253, v253, v19, vcc
	ds_bpermute_b32 v246, v240, v246
	ds_bpermute_b32 v247, v240, v247
	ds_bpermute_b32 v248, v240, v248
	ds_bpermute_b32 v249, v240, v249
	ds_bpermute_b32 v250, v240, v250
	ds_bpermute_b32 v251, v240, v251
	ds_bpermute_b32 v252, v240, v252
	ds_bpermute_b32 v253, v240, v253
	v_lshl_add_u64 v[238:239], v[140:141], 0, v[242:243]
	s_waitcnt lgkmcnt(4)
	global_store_dwordx4 v[140:141], v[246:249], off
	s_waitcnt lgkmcnt(0)
	global_store_dwordx4 v[238:239], v[250:253], off
	v_lshl_add_u64 v[140:141], v[140:141], 0, s[34:35]
	v_cvt_pk_bf16_f32 v20, v20, v21
	v_cvt_pk_bf16_f32 v21, v22, v23
	v_cvt_pk_bf16_f32 v22, v12, v13
	v_cvt_pk_bf16_f32 v23, v14, v15
	v_cvt_pk_bf16_f32 v4, v4, v5
	v_cvt_pk_bf16_f32 v5, v6, v7
	v_cvt_pk_bf16_f32 v6, v0, v1
	v_cvt_pk_bf16_f32 v7, v2, v3
	v_mov_b32_dpp v246, v4 row_ror:8 row_mask:0xf bank_mask:0xf
	v_mov_b32_dpp v247, v5 row_ror:8 row_mask:0xf bank_mask:0xf
	v_mov_b32_dpp v248, v6 row_ror:8 row_mask:0xf bank_mask:0xf
	v_mov_b32_dpp v249, v7 row_ror:8 row_mask:0xf bank_mask:0xf
	v_mov_b32_dpp v250, v20 row_ror:8 row_mask:0xf bank_mask:0xf
	v_mov_b32_dpp v251, v21 row_ror:8 row_mask:0xf bank_mask:0xf
	v_mov_b32_dpp v252, v22 row_ror:8 row_mask:0xf bank_mask:0xf
	v_mov_b32_dpp v253, v23 row_ror:8 row_mask:0xf bank_mask:0xf
	v_cndmask_b32_e32 v246, v20, v246, vcc
	v_cndmask_b32_e32 v247, v21, v247, vcc
	v_cndmask_b32_e32 v248, v22, v248, vcc
	v_cndmask_b32_e32 v249, v23, v249, vcc
	v_cndmask_b32_e32 v250, v250, v4, vcc
	v_cndmask_b32_e32 v251, v251, v5, vcc
	v_cndmask_b32_e32 v252, v252, v6, vcc
	v_cndmask_b32_e32 v253, v253, v7, vcc
	ds_bpermute_b32 v246, v240, v246
	ds_bpermute_b32 v247, v240, v247
	ds_bpermute_b32 v248, v240, v248
	ds_bpermute_b32 v249, v240, v249
	ds_bpermute_b32 v250, v240, v250
	ds_bpermute_b32 v251, v240, v251
	ds_bpermute_b32 v252, v240, v252
	ds_bpermute_b32 v253, v240, v253
	v_lshl_add_u64 v[238:239], v[140:141], 0, v[242:243]
	s_waitcnt lgkmcnt(4)
	global_store_dwordx4 v[140:141], v[246:249], off
	s_waitcnt lgkmcnt(0)
	global_store_dwordx4 v[238:239], v[250:253], off
	s_andn2_b64 vcc, exec, s[40:41]
	s_mov_b64 s[34:35], -1
	s_cbranch_vccnz .LBB0_29
	s_andn2_b64 vcc, exec, s[30:31]
	s_cbranch_vccnz .LBB0_28
	s_barrier
	s_branch .LBB0_28

; #define PG8_WAIT_V(n) asm volatile("s_waitcnt vmcnt(" #n ")" ::: "memory")
; #define PG8_BAR __builtin_amdgcn_s_barrier()
; template <class Epi, class Sched, bool ALIGN_EPI = false, bool SP2 = false>
; __device__ __forceinline__ void gemm_phase(PG8_LAS unsigned char* lds, const Gemm g, const Sched& S, const Epi& E) {
;     int tid_l_ = threadIdx.x; asm volatile("" : "+v"(tid_l_)); const int tid = tid_l_, wid = __builtin_amdgcn_readfirstlane(tid >> 6), lane = tid & 63, wr = wid >> 2, wc = wid & 3, fr = lane & 15, fq = lane >> 4;
;     const int K = g.K, nt = K / BK;
;     unsigned voffA[2], voffB[2];
; #pragma unroll
;     for (int i = 0; i < 2; ++i) { int R, C; stage_rc(tid * 16 + i * 8192, R, C); const int Rb = Epi::PERM ? ((R & ~31) + perm32(R & 31)) : R;
;         voffA[i] = (unsigned)(R * K + C) * 2u; voffB[i] = (unsigned)(Rb * K + C) * 2u; }
;     const size_t kstep = (size_t)(BK * 2);
;     const size_t hstep = (size_t)HALF * K * 2;
;     const size_t tstep = 2 * hstep;
;     const unsigned ldsw = (unsigned)wid * 1024u;
;     const int aoff = lds_byte(wr * 64 + fr, fq * 8), boff = lds_byte(wc * 32 + fr, fq * 8);
;     ...
;     Unit cur, nxt; int ui = 0;
;     if (!S.next(0, cur)) return;
;     f32x4 acc[2][2][4][2];
; #pragma unroll
;     for (int a = 0; a < 2; ++a)
; #pragma unroll
;         for (int b = 0; b < 2; ++b)
; #pragma unroll
;             for (int m = 0; m < 4; ++m)
; #pragma unroll
;                 for (int n = 0; n < 2; ++n) acc[a][b][m][n] = (f32x4){0.f, 0.f, 0.f, 0.f};
;     bf16x8 At[4][2], B0[2][2], B1[2][2];
;     const char* cA = (const char*)g.A + (size_t)cur.pm * tstep; const char* cB = (const char*)g.Bt + (size_t)cur.pn * tstep;
;     S.a_ready(cur);
;     if constexpr (SP2) {
;         PG8_STAGE(PG8_SB(0, 0), cB, voffB); PG8_STAGE(PG8_SB(0, 1), cB + hstep, voffB); PG8_STAGE(PG8_SA(0, 0), cA, voffA); PG8_STAGE(PG8_SA(0, 1), cA + hstep, voffA);
;         if (wr == 1) PG8_BAR;
;         PG8_WAIT_V(2); PG8_BAR;
;         PG8_STAGE(PG8_SB(1, 0), cB + kstep, voffB); PG8_STAGE(PG8_SA(1, 0), cA + kstep, voffA); PG8_STAGE(PG8_SB(1, 1), cB + hstep + kstep, voffB);
;         PG8_WAIT_V(6); PG8_BAR;
;     } else {
;         PG8_STAGE(PG8_SB(0, 0), cB, voffB); PG8_STAGE(PG8_SA(0, 0), cA, voffA); PG8_STAGE(PG8_SB(0, 1), cB + hstep, voffB); PG8_STAGE(PG8_SA(0, 1), cA + hstep, voffA);
;         if (wr == 1) PG8_BAR;
;         PG8_WAIT_V(4); PG8_BAR;
.LBB0_82:
	s_and_b64 vcc, exec, s[30:31]
	s_cbranch_vccz .LBB0_103
	s_waitcnt vmcnt(0)
	v_mov_b32_e32 v6, v208
	s_cmpk_gt_i32 s23, 0x1ff
	s_nop 0
	v_readfirstlane_b32 s30, v6
	s_cbranch_scc1 .LBB0_103
	v_lshlrev_b32_e32 v3, 4, v6
	v_add_u32_e32 v1, 0x2000, v3
	v_ashrrev_i32_e32 v0, 31, v1
	v_lshrrev_b32_e32 v0, 22, v0
	v_add_u32_e32 v0, v1, v0
	v_ashrrev_i32_e32 v0, 10, v0
	v_mul_i32_i24_e32 v2, 0x400, v0
	v_sub_u32_e32 v1, v1, v2
	v_lshrrev_b32_e32 v2, 4, v1
	v_bitop3_b32 v2, v2, v1, 32 bitop3:0x6c
	v_ashrrev_i32_e32 v1, 31, v2
	v_lshrrev_b32_e32 v1, 26, v1
	v_add_u32_e32 v4, v2, v1
	v_lshlrev_b32_e32 v5, 3, v0
	v_ashrrev_i32_e32 v1, 6, v4
	v_and_b32_e32 v5, -16, v5
	v_add_u32_e32 v5, v1, v5
	v_and_b32_e32 v7, 3, v1
	s_mov_b32 s7, 0xfffe0
	v_lshrrev_b32_e32 v8, 2, v5
	v_lshlrev_b32_e32 v9, 1, v5
	v_and_b32_e32 v4, 0xc0, v4
	v_and_b32_e32 v252, s7, v5
	v_lshl_or_b32 v7, v252, 1, v7
	v_and_b32_e32 v8, 4, v8
	v_and_b32_e32 v9, 24, v9
	v_sub_u32_e32 v2, v2, v4
	v_mov_b32_e32 v12, 1
	v_or3_b32 v7, v7, v8, v9
	v_lshlrev_b32_e32 v8, 5, v0
	v_ashrrev_i16_sdwa v2, v12, sext(v2) dst_sel:DWORD dst_unused:UNUSED_PAD src0_sel:DWORD src1_sel:BYTE_0
	v_and_b32_e32 v8, 32, v8
	v_bfe_i32 v2, v2, 0, 16
	v_add_lshl_u32 v4, v8, v2, 1
	v_lshl_add_u32 v130, v7, 12, v4
	v_lshl_add_u32 v132, v5, 12, v4
	v_bfe_i32 v4, v6, 27, 1
	v_lshrrev_b32_e32 v4, 22, v4
	v_add_u32_e32 v4, v3, v4
	v_and_b32_e32 v4, 0xfffffc00, v4
	v_sub_u32_e32 v3, v3, v4
	v_lshrrev_b32_e32 v4, 4, v3
	v_bitop3_b32 v5, v4, v3, 32 bitop3:0x6c
	v_ashrrev_i32_e32 v4, 31, v6
	v_lshrrev_b32_e32 v4, 26, v4
	v_ashrrev_i32_e32 v3, 31, v5
	v_add_u32_e32 v4, v6, v4
	v_lshrrev_b32_e32 v3, 26, v3
	v_ashrrev_i32_e32 v4, 6, v4
	v_add_u32_e32 v7, v5, v3
	v_lshlrev_b32_e32 v8, 3, v4
	v_ashrrev_i32_e32 v3, 6, v7
	v_and_b32_e32 v8, -16, v8
	v_add_u32_e32 v8, v3, v8
	v_and_b32_e32 v9, 3, v3
	s_ashr_i32 s28, s30, 6
	v_and_b32_e32 v252, s7, v8
	v_lshl_or_b32 v9, v252, 1, v9
	v_readlane_b32 s6, v255, 2
	s_ashr_i32 s29, s30, 8
	s_lshl_b32 s2, s28, 10
	v_readlane_b32 s7, v255, 3
	s_and_b64 s[18:19], s[6:7], exec
	s_cselect_b32 s7, s91, s17
	s_add_i32 s7, s7, s74
	s_ashr_i32 s10, s7, 31
	s_lshr_b32 s10, s10, 27
	s_add_i32 s10, s7, s10
	s_mov_b32 s6, s17
	s_ashr_i32 s17, s10, 5
	s_lshl_b32 s17, s17, 2
	s_sub_i32 s18, 64, s17
	s_min_i32 s18, s18, 4
	v_and_b32_e32 v7, 0xc0, v7
	s_abs_i32 s19, s18
	v_sub_u32_e32 v5, v5, v7
	v_cvt_f32_u32_e32 v7, s19
	s_sub_i32 s27, 0, s19
	s_andn2_b32 s10, s10, 31
	s_sub_i32 s7, s7, s10
	v_rcp_iflag_f32_e32 v7, v7
	s_abs_i32 s26, s7
	s_xor_b32 s10, s7, s18
	s_ashr_i32 s10, s10, 31
	v_mul_f32_e32 v7, 0x4f7ffffe, v7
	v_cvt_u32_f32_e32 v7, v7
	v_lshrrev_b32_e32 v10, 2, v8
	v_lshlrev_b32_e32 v11, 1, v8
	v_and_b32_e32 v10, 4, v10
	v_readfirstlane_b32 s31, v7
	s_mul_i32 s27, s27, s31
	s_mul_hi_u32 s27, s31, s27
	s_add_i32 s31, s31, s27
	s_mul_hi_u32 s27, s26, s31
	s_mul_i32 s31, s27, s19
	s_sub_i32 s26, s26, s31
	s_add_i32 s31, s27, 1
	s_sub_i32 s33, s26, s19
	s_cmp_ge_u32 s26, s19
	s_cselect_b32 s27, s31, s27
	s_cselect_b32 s26, s33, s26
	s_add_i32 s31, s27, 1
	s_cmp_ge_u32 s26, s19
	s_cselect_b32 s19, s31, s27
	s_xor_b32 s19, s19, s10
	s_sub_i32 s10, s19, s10
	s_mul_i32 s18, s10, s18
	s_sub_i32 s7, s7, s18
	s_add_i32 s7, s7, s90
	s_add_i32 s46, s7, s17
	s_add_i32 s48, s10, s94
	v_and_b32_e32 v11, 24, v11
	s_ashr_i32 s47, s46, 31
	s_ashr_i32 s49, s48, 31
	v_or3_b32 v9, v9, v10, v11
	v_lshlrev_b32_e32 v10, 5, v4
	v_ashrrev_i16_sdwa v5, v12, sext(v5) dst_sel:DWORD dst_unused:UNUSED_PAD src0_sel:DWORD src1_sel:BYTE_0
	s_lshl_b64 s[18:19], s[46:47], 20
	s_lshl_b64 s[26:27], s[48:49], 20
	v_and_b32_e32 v10, 32, v10
	v_bfe_i32 v5, v5, 0, 16
	s_add_u32 s56, s80, s26
	v_add_lshl_u32 v10, v10, v5, 1
	s_addc_u32 s57, s81, s27
	s_add_i32 s10, s2, 0
	v_lshl_add_u32 v128, v9, 12, v10
	s_add_i32 m0, s10, 0x10000
	v_lshl_add_u32 v134, v8, 12, v10
	global_load_lds_dwordx4 v128, s[56:57]
	s_add_i32 m0, s10, 0x12000
	s_add_u32 s26, s56, 0x20000
	global_load_lds_dwordx4 v130, s[56:57]
	s_addc_u32 s27, s57, 0
	s_add_i32 m0, s10, 0x14000
	s_nop 0
	global_load_lds_dwordx4 v128, s[26:27]
	s_add_i32 m0, s10, 0x16000
	s_add_u32 s54, s83, s18
	s_addc_u32 s55, s93, s19
	s_add_i32 s17, s10, 0x2000
	global_load_lds_dwordx4 v130, s[26:27]
	s_mov_b32 m0, s10
	s_add_u32 s18, s54, 0x80000
	global_load_lds_dwordx4 v134, s[54:55]
	s_mov_b32 m0, s17
	s_addc_u32 s19, s55, 0
	s_add_i32 s26, s10, 0x4000
	global_load_lds_dwordx4 v132, s[54:55]
	s_mov_b32 m0, s26
	s_add_i32 s27, s10, 0x6000
	global_load_lds_dwordx4 v134, s[18:19]
	s_mov_b32 m0, s27
	s_cmp_eq_u32 s29, 1
	global_load_lds_dwordx4 v132, s[18:19]
	s_cselect_b64 s[18:19], -1, 0
	s_cmp_lg_u32 s29, 1
	s_cbranch_scc1 .LBB0_86
	s_barrier
.LBB0_86:
	v_lshrrev_b32_e32 v16, 1, v6
	v_and_b32_e32 v16, 24, v16
	v_and_b32_e32 v7, 15, v6
	v_lshlrev_b32_e32 v17, 1, v16
	v_lshlrev_b32_e32 v6, 2, v6
	v_bfe_u32 v252, v208, 3, 3
	v_lshl_or_b32 v142, s29, 6, v252
	v_lshl_or_b32 v7, v7, 6, v17
	s_lshl_b32 s7, s29, 13
	v_and_b32_e32 v6, 32, v6
	v_bitop3_b32 v17, v7, s7, v6 bitop3:0xde
	s_lshl_b32 s7, s28, 5
	s_and_b32 s7, s7, 0x60
	v_lshl_add_u64 v[8:9], s[56:57], 0, v[128:129]
	v_mov_b32_e32 v131, v129
	s_lshl_b32 s28, s7, 7
	v_lshl_add_u64 v[10:11], s[56:57], 0, v[130:131]
	v_mov_b32_e32 v135, v129
	v_bitop3_b32 v143, v7, s28, v6 bitop3:0xde
	s_add_i32 m0, s10, 0x18000
	v_lshl_add_u64 v[6:7], v[8:9], 0, s[20:21]
	v_lshl_add_u64 v[12:13], s[54:55], 0, v[134:135]
	v_mov_b32_e32 v133, v129
	s_waitcnt vmcnt(2)
	s_barrier
	global_load_lds_dwordx4 v[6:7], off
	v_lshl_add_u64 v[6:7], v[10:11], 0, s[20:21]
	s_add_i32 m0, s10, 0x1a000
	s_add_i32 s28, s10, 0x8000
	s_add_i32 s29, s10, 0xa000
	v_lshl_add_u64 v[14:15], s[54:55], 0, v[132:133]
	global_load_lds_dwordx4 v[6:7], off
	v_lshl_add_u64 v[6:7], v[12:13], 0, s[20:21]
	s_mov_b32 m0, s28
	s_add_u32 s34, s56, 0x20080
	global_load_lds_dwordx4 v[6:7], off
	v_lshl_add_u64 v[6:7], v[14:15], 0, s[20:21]
	s_mov_b32 m0, s29
	s_addc_u32 s35, s57, 0
	global_load_lds_dwordx4 v[6:7], off
	s_add_i32 m0, s10, 0x1c000
	v_lshl_add_u64 v[6:7], s[34:35], 0, v[128:129]
	global_load_lds_dwordx4 v[6:7], off
	v_lshl_add_u64 v[6:7], s[34:35], 0, v[130:131]
	s_add_i32 m0, s10, 0x1e000
	s_cmpk_lt_u32 s30, 0x100
	global_load_lds_dwordx4 v[6:7], off
	v_lshlrev_b32_e32 v6, 15, v4
	v_and_b32_e32 v6, 0xffff0000, v6
	v_lshl_add_u32 v3, v3, 12, v6
	v_and_b32_e32 v4, 1, v4
	v_lshl_or_b32 v3, v4, 6, v3
	v_lshl_add_u32 v136, v5, 1, v3
	v_lshlrev_b32_e32 v3, 15, v0
	v_and_b32_e32 v3, 0xffff0000, v3
	s_waitcnt vmcnt(6)
	v_lshl_add_u32 v1, v1, 12, v3
	v_and_b32_e32 v0, 1, v0
	v_lshl_or_b32 v0, v0, 6, v1
	s_cselect_b64 s[30:31], -1, 0
	v_and_b32_e32 v252, 7, v208
	v_lshlrev_b32_e32 v252, 3, v252
	v_lshl_or_b32 v144, s7, 1, v252
	v_mov_b32_e32 v137, v129
	v_lshl_add_u32 v138, v2, 1, v0
	v_mov_b32_e32 v139, v129
	s_mov_b32 s33, 0
	v_add_u32_e32 v145, 0, v17
	s_barrier
	s_branch .LBB0_89

; #define PG8_STAGE(bufoff, gbase, voff) do { _Pragma("unroll") for (int _i = 0; _i < 2; ++_i) \
;         __builtin_amdgcn_global_load_lds((const unsigned*)((const char*)(gbase) + (voff)[_i]), (PG8_LAS unsigned*)(lds + (bufoff) + ldsw + _i * 8192), 16, 0, 0); } while (0)
; #define PG8_LDA(dst, b, h) do { _Pragma("unroll") for (int m = 0; m < 4; ++m) _Pragma("unroll") for (int k = 0; k < 2; ++k) dst[m][k] = *(const PG8_LAS bf16x8*)(lds + PG8_SA(b, h) + aoff + m * 2048 + k * 1024); } while (0)
; #define PG8_MMA(ai, bj, At, Bt) do { __builtin_amdgcn_s_setprio(1); _Pragma("unroll") for (int m = 0; m < 4; ++m) _Pragma("unroll") for (int n = 0; n < 2; ++n) _Pragma("unroll") for (int k = 0; k < 2; ++k) \
;         acc[ai][bj][m][n] = __builtin_amdgcn_mfma_f32_16x16x32_bf16(Bt[n][k], At[m][k], acc[ai][bj][m][n], 0, 0, 0); __builtin_amdgcn_s_setprio(0); } while (0)
; #define PG8_WAIT_V(n) asm volatile("s_waitcnt vmcnt(" #n ")" ::: "memory")
; #define PG8_WAIT_L(n) asm volatile("s_waitcnt lgkmcnt(" #n ")" ::: "memory")
; #define PG8_BAR __builtin_amdgcn_s_barrier()
; #define PG8_SCHED __builtin_amdgcn_sched_barrier(0)
; template <class Epi, class Sched, bool ALIGN_EPI = false, bool SP2 = false>
; __device__ __forceinline__ void gemm_phase(PG8_LAS unsigned char* lds, const Gemm g, const Sched& S, const Epi& E) {
;     ...
;             PG8_WAIT_V(8); PG8_WAIT_L(0); PG8_BAR; PG8_MMA(0, 0, At, B0); PG8_MMA(0, 1, At, B1); PG8_BAR; PG8_SCHED;
;             PG8_LDA(At, 0, 1); PG8_STAGE(PG8_SB(0, 0), b2, voffB); PG8_STAGE(PG8_SB(0, 1), b2 + hstep, voffB); PG8_STAGE(PG8_SA(0, 0), a2, voffA);
;             PG8_WAIT_V(8); PG8_WAIT_L(0); PG8_BAR; PG8_MMA(1, 0, At, B0); PG8_MMA(1, 1, At, B1); PG8_BAR; PG8_SCHED;
.Lrx16_0_join:
	s_waitcnt lgkmcnt(0)
	s_barrier
	s_setprio 1
	s_waitcnt lgkmcnt(0)
	v_mfma_f32_16x16x32_bf16 v[124:127], v[146:149], v[178:181], v[124:127]
	v_mfma_f32_16x16x32_bf16 v[120:123], v[154:157], v[178:181], v[120:123]
	v_mfma_f32_16x16x32_bf16 v[116:119], v[146:149], v[186:189], v[116:119]
	v_mfma_f32_16x16x32_bf16 v[108:111], v[154:157], v[186:189], v[108:111]
	v_mfma_f32_16x16x32_bf16 v[100:103], v[146:149], v[214:217], v[100:103]
	v_mfma_f32_16x16x32_bf16 v[92:95], v[154:157], v[214:217], v[92:95]
	v_mfma_f32_16x16x32_bf16 v[84:87], v[146:149], v[224:227], v[84:87]
	v_mfma_f32_16x16x32_bf16 v[76:79], v[154:157], v[224:227], v[76:79]
	v_mfma_f32_16x16x32_bf16 v[124:127], v[150:153], v[182:185], v[124:127]
	v_mfma_f32_16x16x32_bf16 v[120:123], v[158:161], v[182:185], v[120:123]
	v_mfma_f32_16x16x32_bf16 v[116:119], v[150:153], v[190:193], v[116:119]
	v_mfma_f32_16x16x32_bf16 v[108:111], v[158:161], v[190:193], v[108:111]
	v_mfma_f32_16x16x32_bf16 v[100:103], v[150:153], v[220:223], v[100:103]
	v_mfma_f32_16x16x32_bf16 v[92:95], v[158:161], v[220:223], v[92:95]
	v_mfma_f32_16x16x32_bf16 v[84:87], v[150:153], v[228:231], v[84:87]
	v_mfma_f32_16x16x32_bf16 v[76:79], v[158:161], v[228:231], v[76:79]
	s_setprio 0
	s_setprio 1
	v_mfma_f32_16x16x32_bf16 v[112:115], v[162:165], v[178:181], v[112:115]
	v_mfma_f32_16x16x32_bf16 v[104:107], v[170:173], v[178:181], v[104:107]
	v_mfma_f32_16x16x32_bf16 v[96:99], v[162:165], v[186:189], v[96:99]
	v_mfma_f32_16x16x32_bf16 v[88:91], v[170:173], v[186:189], v[88:91]
	v_mfma_f32_16x16x32_bf16 v[80:83], v[162:165], v[214:217], v[80:83]
	v_mfma_f32_16x16x32_bf16 v[72:75], v[170:173], v[214:217], v[72:75]
	v_mfma_f32_16x16x32_bf16 v[68:71], v[162:165], v[224:227], v[68:71]
	v_mfma_f32_16x16x32_bf16 v[64:67], v[170:173], v[224:227], v[64:67]
	v_mfma_f32_16x16x32_bf16 v[112:115], v[166:169], v[182:185], v[112:115]
	v_mfma_f32_16x16x32_bf16 v[104:107], v[174:177], v[182:185], v[104:107]
	v_mfma_f32_16x16x32_bf16 v[96:99], v[166:169], v[190:193], v[96:99]
	v_mfma_f32_16x16x32_bf16 v[88:91], v[174:177], v[190:193], v[88:91]
	v_mfma_f32_16x16x32_bf16 v[80:83], v[166:169], v[220:223], v[80:83]
	v_mfma_f32_16x16x32_bf16 v[72:75], v[174:177], v[220:223], v[72:75]
	v_mfma_f32_16x16x32_bf16 v[68:71], v[166:169], v[228:231], v[68:71]
	v_mfma_f32_16x16x32_bf16 v[64:67], v[174:177], v[228:231], v[64:67]
	s_setprio 0
	s_barrier
	s_add_i32 s60, s60, s2
	v_lshl_add_u64 v[140:141], s[56:57], 0, v[128:129]
	s_mov_b32 m0, s60
	ds_read_b128 v[178:181], v145 offset:16384
	ds_read_b128 v[182:185], v145 offset:17408
	ds_read_b128 v[186:189], v145 offset:18432
	ds_read_b128 v[190:193], v145 offset:19456
	ds_read_b128 v[214:217], v145 offset:20480
	ds_read_b128 v[220:223], v145 offset:21504
	ds_read_b128 v[224:227], v145 offset:22528
	ds_read_b128 v[228:231], v145 offset:23552
	global_load_lds_dwordx4 v[140:141], off
	s_add_i32 m0, s60, 0x2000
	s_add_u32 s60, s56, 0x20000
	v_lshl_add_u64 v[206:207], s[56:57], 0, v[130:131]
	s_addc_u32 s61, s57, 0
	s_add_i32 s7, s7, s2
	global_load_lds_dwordx4 v[206:207], off
	v_lshl_add_u64 v[232:233], s[60:61], 0, v[128:129]
	s_mov_b32 m0, s7
	v_lshl_add_u64 v[234:235], s[58:59], 0, v[132:133]
	global_load_lds_dwordx4 v[232:233], off
	v_lshl_add_u64 v[232:233], s[60:61], 0, v[130:131]
	s_add_i32 m0, s7, 0x2000
	s_nop 0
	global_load_lds_dwordx4 v[232:233], off
	v_lshl_add_u64 v[232:233], s[58:59], 0, v[134:135]
	s_mov_b32 m0, s10
	s_nop 0
	global_load_lds_dwordx4 v[232:233], off
	s_mov_b32 m0, s17
	s_nop 0
	global_load_lds_dwordx4 v[234:235], off
	s_cmp_lt_i32 s49, 0
	s_cbranch_scc0 .Lrx16_1_norm
	s_cmp_lt_u32 s33, 2
	s_cbranch_scc1 .Lrx16_1_norm
	s_waitcnt vmcnt(24)
	s_branch .Lrx16_1_join

; #define PG8_STAGE(bufoff, gbase, voff) do { _Pragma("unroll") for (int _i = 0; _i < 2; ++_i) \
;         __builtin_amdgcn_global_load_lds((const unsigned*)((const char*)(gbase) + (voff)[_i]), (PG8_LAS unsigned*)(lds + (bufoff) + ldsw + _i * 8192), 16, 0, 0); } while (0)
; #define PG8_LDA(dst, b, h) do { _Pragma("unroll") for (int m = 0; m < 4; ++m) _Pragma("unroll") for (int k = 0; k < 2; ++k) dst[m][k] = *(const PG8_LAS bf16x8*)(lds + PG8_SA(b, h) + aoff + m * 2048 + k * 1024); } while (0)
; #define PG8_LDB(dst, b, h) do { _Pragma("unroll") for (int n = 0; n < 2; ++n) _Pragma("unroll") for (int k = 0; k < 2; ++k) dst[n][k] = *(const PG8_LAS bf16x8*)(lds + PG8_SB(b, h) + boff + n * 2048 + k * 1024); } while (0)
; #define PG8_MMA(ai, bj, At, Bt) do { __builtin_amdgcn_s_setprio(1); _Pragma("unroll") for (int m = 0; m < 4; ++m) _Pragma("unroll") for (int n = 0; n < 2; ++n) _Pragma("unroll") for (int k = 0; k < 2; ++k) \
;         acc[ai][bj][m][n] = __builtin_amdgcn_mfma_f32_16x16x32_bf16(Bt[n][k], At[m][k], acc[ai][bj][m][n], 0, 0, 0); __builtin_amdgcn_s_setprio(0); } while (0)
; #define PG8_WAIT_V(n) asm volatile("s_waitcnt vmcnt(" #n ")" ::: "memory")
; #define PG8_WAIT_L(n) asm volatile("s_waitcnt lgkmcnt(" #n ")" ::: "memory")
; #define PG8_BAR __builtin_amdgcn_s_barrier()
; #define PG8_SCHED __builtin_amdgcn_sched_barrier(0)
; template <class Epi, class Sched, bool ALIGN_EPI = false, bool SP2 = false>
; __device__ __forceinline__ void gemm_phase(PG8_LAS unsigned char* lds, const Gemm g, const Sched& S, const Epi& E) {
;     ...
;             PG8_WAIT_V(8); PG8_WAIT_L(0); PG8_BAR; PG8_MMA(1, 0, At, B0); PG8_MMA(1, 1, At, B1); PG8_BAR; PG8_SCHED;
;             PG8_LDB(B0, 1, 0); PG8_LDB(B1, 1, 1); PG8_SCHED; PG8_LDA(At, 1, 0); PG8_STAGE(PG8_SA(0, 1), a2 + hstep, voffA);
;             PG8_WAIT_V(8); PG8_WAIT_L(0); PG8_BAR; PG8_MMA(0, 0, At, B0); PG8_MMA(0, 1, At, B1); PG8_BAR; PG8_SCHED;
.Lrx16_1_join:
	s_waitcnt lgkmcnt(0)
	s_barrier
	s_setprio 1
	s_waitcnt lgkmcnt(0)
	v_mfma_f32_16x16x32_bf16 v[60:63], v[146:149], v[178:181], v[60:63]
	v_mfma_f32_16x16x32_bf16 v[56:59], v[154:157], v[178:181], v[56:59]
	v_mfma_f32_16x16x32_bf16 v[52:55], v[146:149], v[186:189], v[52:55]
	v_mfma_f32_16x16x32_bf16 v[44:47], v[154:157], v[186:189], v[44:47]
	v_mfma_f32_16x16x32_bf16 v[36:39], v[146:149], v[214:217], v[36:39]
	v_mfma_f32_16x16x32_bf16 v[28:31], v[154:157], v[214:217], v[28:31]
	v_mfma_f32_16x16x32_bf16 v[20:23], v[146:149], v[224:227], v[20:23]
	v_mfma_f32_16x16x32_bf16 v[12:15], v[154:157], v[224:227], v[12:15]
	v_mfma_f32_16x16x32_bf16 v[60:63], v[150:153], v[182:185], v[60:63]
	v_mfma_f32_16x16x32_bf16 v[56:59], v[158:161], v[182:185], v[56:59]
	v_mfma_f32_16x16x32_bf16 v[52:55], v[150:153], v[190:193], v[52:55]
	v_mfma_f32_16x16x32_bf16 v[44:47], v[158:161], v[190:193], v[44:47]
	v_mfma_f32_16x16x32_bf16 v[36:39], v[150:153], v[220:223], v[36:39]
	v_mfma_f32_16x16x32_bf16 v[28:31], v[158:161], v[220:223], v[28:31]
	v_mfma_f32_16x16x32_bf16 v[20:23], v[150:153], v[228:231], v[20:23]
	v_mfma_f32_16x16x32_bf16 v[12:15], v[158:161], v[228:231], v[12:15]
	s_setprio 0
	s_setprio 1
	v_mfma_f32_16x16x32_bf16 v[48:51], v[162:165], v[178:181], v[48:51]
	v_mfma_f32_16x16x32_bf16 v[40:43], v[170:173], v[178:181], v[40:43]
	v_mfma_f32_16x16x32_bf16 v[32:35], v[162:165], v[186:189], v[32:35]
	v_mfma_f32_16x16x32_bf16 v[24:27], v[170:173], v[186:189], v[24:27]
	v_mfma_f32_16x16x32_bf16 v[16:19], v[162:165], v[214:217], v[16:19]
	v_mfma_f32_16x16x32_bf16 v[8:11], v[170:173], v[214:217], v[8:11]
	v_mfma_f32_16x16x32_bf16 v[4:7], v[162:165], v[224:227], v[4:7]
	v_mfma_f32_16x16x32_bf16 v[0:3], v[170:173], v[224:227], v[0:3]
	v_mfma_f32_16x16x32_bf16 v[48:51], v[166:169], v[182:185], v[48:51]
	v_mfma_f32_16x16x32_bf16 v[40:43], v[174:177], v[182:185], v[40:43]
	v_mfma_f32_16x16x32_bf16 v[32:35], v[166:169], v[190:193], v[32:35]
	v_mfma_f32_16x16x32_bf16 v[24:27], v[174:177], v[190:193], v[24:27]
	v_mfma_f32_16x16x32_bf16 v[16:19], v[166:169], v[220:223], v[16:19]
	v_mfma_f32_16x16x32_bf16 v[8:11], v[174:177], v[220:223], v[8:11]
	v_mfma_f32_16x16x32_bf16 v[4:7], v[166:169], v[228:231], v[4:7]
	v_mfma_f32_16x16x32_bf16 v[0:3], v[174:177], v[228:231], v[0:3]
	s_setprio 0
	s_barrier
	s_add_i32 s7, 0, 0x18000
	s_add_i32 s60, 0, 0x1c000
	v_add_u32_e32 v158, s7, v143
	v_add_u32_e32 v174, s60, v143
	ds_read_b128 v[146:149], v158
	ds_read_b128 v[150:153], v158 offset:1024
	ds_read_b128 v[154:157], v158 offset:2048
	ds_read_b128 v[158:161], v158 offset:3072
	ds_read_b128 v[162:165], v174
	ds_read_b128 v[166:169], v174 offset:1024
	ds_read_b128 v[170:173], v174 offset:2048
	ds_read_b128 v[174:177], v174 offset:3072
	s_add_u32 s58, s58, 0x80000
	s_addc_u32 s59, s59, 0
	s_mov_b32 m0, s26
	v_lshl_add_u64 v[236:237], s[58:59], 0, v[134:135]
	ds_read_b128 v[178:181], v145 offset:32768
	ds_read_b128 v[182:185], v145 offset:33792
	ds_read_b128 v[186:189], v145 offset:34816
	ds_read_b128 v[190:193], v145 offset:35840
	ds_read_b128 v[214:217], v145 offset:36864
	ds_read_b128 v[220:223], v145 offset:37888
	ds_read_b128 v[224:227], v145 offset:38912
	ds_read_b128 v[228:231], v145 offset:39936
	global_load_lds_dwordx4 v[236:237], off
	v_lshl_add_u64 v[236:237], s[58:59], 0, v[132:133]
	s_mov_b32 m0, s27
	s_nop 0
	global_load_lds_dwordx4 v[236:237], off
	s_waitcnt vmcnt(8)
	s_waitcnt lgkmcnt(0)
	s_barrier
	s_setprio 1
	s_waitcnt lgkmcnt(0)
	v_mfma_f32_16x16x32_bf16 v[124:127], v[146:149], v[178:181], v[124:127]
	v_mfma_f32_16x16x32_bf16 v[120:123], v[154:157], v[178:181], v[120:123]
	v_mfma_f32_16x16x32_bf16 v[116:119], v[146:149], v[186:189], v[116:119]
	v_mfma_f32_16x16x32_bf16 v[108:111], v[154:157], v[186:189], v[108:111]
	v_mfma_f32_16x16x32_bf16 v[100:103], v[146:149], v[214:217], v[100:103]
	v_mfma_f32_16x16x32_bf16 v[92:95], v[154:157], v[214:217], v[92:95]
	v_mfma_f32_16x16x32_bf16 v[84:87], v[146:149], v[224:227], v[84:87]
	v_mfma_f32_16x16x32_bf16 v[76:79], v[154:157], v[224:227], v[76:79]
	v_mfma_f32_16x16x32_bf16 v[124:127], v[150:153], v[182:185], v[124:127]
	v_mfma_f32_16x16x32_bf16 v[120:123], v[158:161], v[182:185], v[120:123]
	v_mfma_f32_16x16x32_bf16 v[116:119], v[150:153], v[190:193], v[116:119]
	v_mfma_f32_16x16x32_bf16 v[108:111], v[158:161], v[190:193], v[108:111]
	v_mfma_f32_16x16x32_bf16 v[100:103], v[150:153], v[220:223], v[100:103]
	v_mfma_f32_16x16x32_bf16 v[92:95], v[158:161], v[220:223], v[92:95]
	v_mfma_f32_16x16x32_bf16 v[84:87], v[150:153], v[228:231], v[84:87]
	v_mfma_f32_16x16x32_bf16 v[76:79], v[158:161], v[228:231], v[76:79]
	s_setprio 0
	s_setprio 1
	v_mfma_f32_16x16x32_bf16 v[112:115], v[162:165], v[178:181], v[112:115]
	v_mfma_f32_16x16x32_bf16 v[104:107], v[170:173], v[178:181], v[104:107]
	v_mfma_f32_16x16x32_bf16 v[96:99], v[162:165], v[186:189], v[96:99]
	v_mfma_f32_16x16x32_bf16 v[88:91], v[170:173], v[186:189], v[88:91]
	v_mfma_f32_16x16x32_bf16 v[80:83], v[162:165], v[214:217], v[80:83]
	v_mfma_f32_16x16x32_bf16 v[72:75], v[170:173], v[214:217], v[72:75]
	v_mfma_f32_16x16x32_bf16 v[68:71], v[162:165], v[224:227], v[68:71]
	v_mfma_f32_16x16x32_bf16 v[64:67], v[170:173], v[224:227], v[64:67]
	v_mfma_f32_16x16x32_bf16 v[112:115], v[166:169], v[182:185], v[112:115]
	v_mfma_f32_16x16x32_bf16 v[104:107], v[174:177], v[182:185], v[104:107]
	v_mfma_f32_16x16x32_bf16 v[96:99], v[166:169], v[190:193], v[96:99]
	v_mfma_f32_16x16x32_bf16 v[88:91], v[174:177], v[190:193], v[88:91]
	v_mfma_f32_16x16x32_bf16 v[80:83], v[166:169], v[220:223], v[80:83]
	v_mfma_f32_16x16x32_bf16 v[72:75], v[174:177], v[220:223], v[72:75]
	v_mfma_f32_16x16x32_bf16 v[68:71], v[166:169], v[228:231], v[68:71]
	v_mfma_f32_16x16x32_bf16 v[64:67], v[174:177], v[228:231], v[64:67]
	s_setprio 0
	s_barrier
; __device__ __forceinline__ u32x4 pack8_bf16(f32x4 a, f32x4 b) { u32x4 w; w.x = cvt_pk_bf16(a[0], a[1]); w.y = cvt_pk_bf16(a[2], a[3]); w.z = cvt_pk_bf16(b[0], b[1]); w.w = cvt_pk_bf16(b[2], b[3]); return w; }
; #define PG8_STAGE(bufoff, gbase, voff) do { _Pragma("unroll") for (int _i = 0; _i < 2; ++_i) \
;         __builtin_amdgcn_global_load_lds((const unsigned*)((const char*)(gbase) + (voff)[_i]), (PG8_LAS unsigned*)(lds + (bufoff) + ldsw + _i * 8192), 16, 0, 0); } while (0)
; #define PG8_LDA(dst, b, h) do { _Pragma("unroll") for (int m = 0; m < 4; ++m) _Pragma("unroll") for (int k = 0; k < 2; ++k) dst[m][k] = *(const PG8_LAS bf16x8*)(lds + PG8_SA(b, h) + aoff + m * 2048 + k * 1024); } while (0)
; #define PG8_WAIT_V(n) asm volatile("s_waitcnt vmcnt(" #n ")" ::: "memory")
; #define PG8_WAIT_L(n) asm volatile("s_waitcnt lgkmcnt(" #n ")" ::: "memory")
; #define PG8_BAR __builtin_amdgcn_s_barrier()
; #define PG8_SCHED __builtin_amdgcn_sched_barrier(0)
;     __device__ __forceinline__ void operator()(const f32x4 (&acc)[2][2][4][2], const Unit& u, int wr, int wc, int fr, int fq) const {
;         const int g = u.pn / nNper, pnl = u.pn - g * nNper, pml = u.pm & 63;
;         bf16_t* base = O + (size_t)g * gstride;
;         const int row0 = pml * BM + wr * 64 + fr, col0 = pnl * BM + wc * 32 + 8 * fq;
; #pragma unroll
;         for (int ai = 0; ai < 2; ++ai)
; #pragma unroll
;             for (int m = 0; m < 4; ++m) { bf16_t* rowp = base + (size_t)(row0 + ai * HALF + m * 16) * ldc + col0;
; #pragma unroll
;                 for (int bj = 0; bj < 2; ++bj) { f32x4 v0 = acc[ai][bj][m][0], v1 = acc[ai][bj][m][1];
;                     if (ACT == 1) {
; #pragma unroll
;                         for (int j = 0; j < 4; ++j) { float a = fmaxf(v0[j], 0.f), b = fmaxf(v1[j], 0.f); v0[j] = a * a; v1[j] = b * b; } }
;                     *(u32x4*)(rowp + bj * HALF) = pack8_bf16(v0, v1); } }
; template <class Epi, class Sched, bool ALIGN_EPI = false, bool SP2 = false>
; __device__ __forceinline__ void gemm_phase(PG8_LAS unsigned char* lds, const Gemm g, const Sched& S, const Epi& E) {
;     ...
;             PG8_LDA(At, 1, 1); PG8_STAGE(PG8_SB(1, 0), b3, voffB); PG8_STAGE(PG8_SB(1, 1), b3 + hstep, voffB); PG8_STAGE(PG8_SA(1, 0), a3, voffA);
;             PG8_WAIT_V(8); PG8_WAIT_L(0); PG8_BAR; PG8_MMA(1, 0, At, B0); PG8_MMA(1, 1, At, B1); PG8_BAR; PG8_SCHED;
	s_add_i32 s7, s7, s2
	v_lshl_add_u64 v[140:141], v[140:141], 0, s[20:21]
	s_mov_b32 m0, s7
	ds_read_b128 v[178:181], v145 offset:49152
	ds_read_b128 v[182:185], v145 offset:50176
	ds_read_b128 v[186:189], v145 offset:51200
	ds_read_b128 v[190:193], v145 offset:52224
	ds_read_b128 v[214:217], v145 offset:53248
	ds_read_b128 v[220:223], v145 offset:54272
	ds_read_b128 v[224:227], v145 offset:55296
	ds_read_b128 v[228:231], v145 offset:56320
	global_load_lds_dwordx4 v[140:141], off
	s_add_i32 m0, s7, 0x2000
	s_add_u32 s56, s56, 0x20080
	v_lshl_add_u64 v[140:141], v[206:207], 0, s[20:21]
	s_addc_u32 s57, s57, 0
	s_add_i32 s7, s60, s2
	global_load_lds_dwordx4 v[140:141], off
	v_lshl_add_u64 v[140:141], s[56:57], 0, v[128:129]
	s_mov_b32 m0, s7
	s_nop 0
	global_load_lds_dwordx4 v[140:141], off
	v_lshl_add_u64 v[140:141], s[56:57], 0, v[130:131]
	s_add_i32 m0, s7, 0x2000
	s_nop 0
	global_load_lds_dwordx4 v[140:141], off
	v_lshl_add_u64 v[140:141], v[232:233], 0, s[20:21]
	s_mov_b32 m0, s28
	s_nop 0
	global_load_lds_dwordx4 v[140:141], off
	v_lshl_add_u64 v[140:141], v[234:235], 0, s[20:21]
	s_mov_b32 m0, s29
	s_nop 0
	global_load_lds_dwordx4 v[140:141], off
	s_waitcnt vmcnt(8)
	s_waitcnt lgkmcnt(0)
	s_barrier
	s_setprio 1
	s_waitcnt lgkmcnt(0)
	v_mfma_f32_16x16x32_bf16 v[60:63], v[146:149], v[178:181], v[60:63]
	v_mfma_f32_16x16x32_bf16 v[56:59], v[154:157], v[178:181], v[56:59]
	v_mfma_f32_16x16x32_bf16 v[52:55], v[146:149], v[186:189], v[52:55]
	v_mfma_f32_16x16x32_bf16 v[44:47], v[154:157], v[186:189], v[44:47]
	v_mfma_f32_16x16x32_bf16 v[36:39], v[146:149], v[214:217], v[36:39]
	v_mfma_f32_16x16x32_bf16 v[28:31], v[154:157], v[214:217], v[28:31]
	v_mfma_f32_16x16x32_bf16 v[20:23], v[146:149], v[224:227], v[20:23]
	v_mfma_f32_16x16x32_bf16 v[12:15], v[154:157], v[224:227], v[12:15]
	v_mfma_f32_16x16x32_bf16 v[60:63], v[150:153], v[182:185], v[60:63]
	v_mfma_f32_16x16x32_bf16 v[56:59], v[158:161], v[182:185], v[56:59]
	v_mfma_f32_16x16x32_bf16 v[52:55], v[150:153], v[190:193], v[52:55]
	v_mfma_f32_16x16x32_bf16 v[44:47], v[158:161], v[190:193], v[44:47]
	v_mfma_f32_16x16x32_bf16 v[36:39], v[150:153], v[220:223], v[36:39]
	v_mfma_f32_16x16x32_bf16 v[28:31], v[158:161], v[220:223], v[28:31]
	v_mfma_f32_16x16x32_bf16 v[20:23], v[150:153], v[228:231], v[20:23]
	v_mfma_f32_16x16x32_bf16 v[12:15], v[158:161], v[228:231], v[12:15]
	s_setprio 0
	s_setprio 1
	v_mfma_f32_16x16x32_bf16 v[48:51], v[162:165], v[178:181], v[48:51]
	v_mfma_f32_16x16x32_bf16 v[40:43], v[170:173], v[178:181], v[40:43]
	v_mfma_f32_16x16x32_bf16 v[32:35], v[162:165], v[186:189], v[32:35]
	v_mfma_f32_16x16x32_bf16 v[24:27], v[170:173], v[186:189], v[24:27]
	v_mfma_f32_16x16x32_bf16 v[16:19], v[162:165], v[214:217], v[16:19]
	v_mfma_f32_16x16x32_bf16 v[8:11], v[170:173], v[214:217], v[8:11]
	v_mfma_f32_16x16x32_bf16 v[4:7], v[162:165], v[224:227], v[4:7]
	v_mfma_f32_16x16x32_bf16 v[0:3], v[170:173], v[224:227], v[0:3]
	v_mfma_f32_16x16x32_bf16 v[48:51], v[166:169], v[182:185], v[48:51]
	v_mfma_f32_16x16x32_bf16 v[40:43], v[174:177], v[182:185], v[40:43]
	v_mfma_f32_16x16x32_bf16 v[32:35], v[166:169], v[190:193], v[32:35]
	v_mfma_f32_16x16x32_bf16 v[24:27], v[174:177], v[190:193], v[24:27]
	v_mfma_f32_16x16x32_bf16 v[16:19], v[166:169], v[220:223], v[16:19]
	v_mfma_f32_16x16x32_bf16 v[8:11], v[174:177], v[220:223], v[8:11]
	v_mfma_f32_16x16x32_bf16 v[4:7], v[166:169], v[228:231], v[4:7]
	v_mfma_f32_16x16x32_bf16 v[0:3], v[174:177], v[228:231], v[0:3]
	s_setprio 0
	s_barrier
	s_add_i32 s49, s49, 2
	s_add_u32 s54, s54, 0x100
	s_addc_u32 s55, s55, 0
	s_add_u32 s45, s45, 0x100
	s_addc_u32 s47, s47, 0
	s_cmp_gt_u32 s49, 29
	s_cbranch_scc0 .LBB0_96
	s_and_b64 vcc, exec, s[30:31]
	s_cbranch_vccz .LBB0_99
	s_barrier
.LBB0_99:
	s_ashr_i32 s7, s48, 31
	s_lshr_b32 s7, s7, 29
	s_add_i32 s7, s48, s7
	s_and_b32 s7, s7, 0xfffff8
	s_lshl_b32 s34, s46, 8
	s_sub_i32 s7, s48, s7
	s_and_b32 s34, s34, 0x3f00
	v_add_u32_e32 v146, s34, v142
	v_lshl_or_b32 v140, s7, 8, v144
	v_ashrrev_i32_e32 v141, 31, v140
	v_ashrrev_i32_e32 v147, 31, v146
	v_lshl_add_u64 v[148:149], v[140:141], 1, s[12:13]
	v_lshlrev_b64 v[140:141], 12, v[146:147]
	v_lshl_add_u64 v[140:141], v[148:149], 0, v[140:141]
	s_mov_b64 s[34:35], 0x10000
	v_mov_b32_e32 v242, 0x8000
	v_mov_b32_e32 v243, 0
	v_and_b32_e32 v238, 8, v208
	v_cmp_ne_u32_e32 vcc, 0, v238
	v_and_b32_e32 v240, 63, v208
	v_lshrrev_b32_e32 v241, 3, v240
	v_and_b32_e32 v244, 3, v240
	v_lshl_add_u32 v241, v244, 4, v241
	v_and_b32_e32 v244, 4, v240
	v_lshl_add_u32 v241, v244, 1, v241
	v_lshlrev_b32_e32 v240, 2, v241
	v_cvt_pk_bf16_f32 v124, v124, v125
	v_cvt_pk_bf16_f32 v125, v126, v127
	v_cvt_pk_bf16_f32 v126, v120, v121
	v_cvt_pk_bf16_f32 v127, v122, v123
	v_cvt_pk_bf16_f32 v112, v112, v113
	v_cvt_pk_bf16_f32 v113, v114, v115
	v_cvt_pk_bf16_f32 v114, v104, v105
	v_cvt_pk_bf16_f32 v115, v106, v107
	v_mov_b32_dpp v246, v112 row_ror:8 row_mask:0xf bank_mask:0xf
	v_mov_b32_dpp v247, v113 row_ror:8 row_mask:0xf bank_mask:0xf
	v_mov_b32_dpp v248, v114 row_ror:8 row_mask:0xf bank_mask:0xf
	v_mov_b32_dpp v249, v115 row_ror:8 row_mask:0xf bank_mask:0xf
	v_mov_b32_dpp v250, v124 row_ror:8 row_mask:0xf bank_mask:0xf
	v_mov_b32_dpp v251, v125 row_ror:8 row_mask:0xf bank_mask:0xf
	v_mov_b32_dpp v252, v126 row_ror:8 row_mask:0xf bank_mask:0xf
	v_mov_b32_dpp v253, v127 row_ror:8 row_mask:0xf bank_mask:0xf
	v_cndmask_b32_e32 v246, v124, v246, vcc
	v_cndmask_b32_e32 v247, v125, v247, vcc
	v_cndmask_b32_e32 v248, v126, v248, vcc
	v_cndmask_b32_e32 v249, v127, v249, vcc
	v_cndmask_b32_e32 v250, v250, v112, vcc
	v_cndmask_b32_e32 v251, v251, v113, vcc
	v_cndmask_b32_e32 v252, v252, v114, vcc
	v_cndmask_b32_e32 v253, v253, v115, vcc
	ds_bpermute_b32 v246, v240, v246
	ds_bpermute_b32 v247, v240, v247
	ds_bpermute_b32 v248, v240, v248
	ds_bpermute_b32 v249, v240, v249
	ds_bpermute_b32 v250, v240, v250
	ds_bpermute_b32 v251, v240, v251
	ds_bpermute_b32 v252, v240, v252
	ds_bpermute_b32 v253, v240, v253
	v_lshl_add_u64 v[238:239], v[140:141], 0, v[242:243]
	s_waitcnt lgkmcnt(4)
; __device__ __forceinline__ u32x4 pack8_bf16(f32x4 a, f32x4 b) { u32x4 w; w.x = cvt_pk_bf16(a[0], a[1]); w.y = cvt_pk_bf16(a[2], a[3]); w.z = cvt_pk_bf16(b[0], b[1]); w.w = cvt_pk_bf16(b[2], b[3]); return w; }
; #define ACT(t) (KBASE(t) <= qlo + QBLK - 1 && KBASE(t) + KVBLK - 1 >= qlo - W + 1)
;     __device__ __forceinline__ void operator()(const f32x4 (&acc)[2][2][4][2], const Unit& u, int wr, int wc, int fr, int fq) const {
;     ...
; #pragma unroll
;         for (int ai = 0; ai < 2; ++ai)
; #pragma unroll
;             for (int m = 0; m < 4; ++m) { bf16_t* rowp = base + (size_t)(row0 + ai * HALF + m * 16) * ldc + col0;
; #pragma unroll
;                 for (int bj = 0; bj < 2; ++bj) { f32x4 v0 = acc[ai][bj][m][0], v1 = acc[ai][bj][m][1];
;                     if (ACT == 1) {
; #pragma unroll
;                         for (int j = 0; j < 4; ++j) { float a = fmaxf(v0[j], 0.f), b = fmaxf(v1[j], 0.f); v0[j] = a * a; v1[j] = b * b; } }
;                     *(u32x4*)(rowp + bj * HALF) = pack8_bf16(v0, v1); } }
	global_store_dwordx4 v[140:141], v[246:249], off
	s_waitcnt lgkmcnt(0)
	global_store_dwordx4 v[238:239], v[250:253], off
	v_lshl_add_u64 v[140:141], v[140:141], 0, s[34:35]
	v_cvt_pk_bf16_f32 v116, v116, v117
	v_cvt_pk_bf16_f32 v117, v118, v119
	v_cvt_pk_bf16_f32 v118, v108, v109
	v_cvt_pk_bf16_f32 v119, v110, v111
	v_cvt_pk_bf16_f32 v96, v96, v97
	v_cvt_pk_bf16_f32 v97, v98, v99
	v_cvt_pk_bf16_f32 v98, v88, v89
	v_cvt_pk_bf16_f32 v99, v90, v91
	v_mov_b32_dpp v246, v96 row_ror:8 row_mask:0xf bank_mask:0xf
	v_mov_b32_dpp v247, v97 row_ror:8 row_mask:0xf bank_mask:0xf
	v_mov_b32_dpp v248, v98 row_ror:8 row_mask:0xf bank_mask:0xf
	v_mov_b32_dpp v249, v99 row_ror:8 row_mask:0xf bank_mask:0xf
	v_mov_b32_dpp v250, v116 row_ror:8 row_mask:0xf bank_mask:0xf
	v_mov_b32_dpp v251, v117 row_ror:8 row_mask:0xf bank_mask:0xf
	v_mov_b32_dpp v252, v118 row_ror:8 row_mask:0xf bank_mask:0xf
	v_mov_b32_dpp v253, v119 row_ror:8 row_mask:0xf bank_mask:0xf
	v_cndmask_b32_e32 v246, v116, v246, vcc
	v_cndmask_b32_e32 v247, v117, v247, vcc
	v_cndmask_b32_e32 v248, v118, v248, vcc
	v_cndmask_b32_e32 v249, v119, v249, vcc
	v_cndmask_b32_e32 v250, v250, v96, vcc
	v_cndmask_b32_e32 v251, v251, v97, vcc
	v_cndmask_b32_e32 v252, v252, v98, vcc
	v_cndmask_b32_e32 v253, v253, v99, vcc
	ds_bpermute_b32 v246, v240, v246
	ds_bpermute_b32 v247, v240, v247
	ds_bpermute_b32 v248, v240, v248
	ds_bpermute_b32 v249, v240, v249
	ds_bpermute_b32 v250, v240, v250
	ds_bpermute_b32 v251, v240, v251
	ds_bpermute_b32 v252, v240, v252
	ds_bpermute_b32 v253, v240, v253
	v_lshl_add_u64 v[238:239], v[140:141], 0, v[242:243]
	s_waitcnt lgkmcnt(4)
	global_store_dwordx4 v[140:141], v[246:249], off
	s_waitcnt lgkmcnt(0)
	global_store_dwordx4 v[238:239], v[250:253], off
	v_lshl_add_u64 v[140:141], v[140:141], 0, s[34:35]
	v_cvt_pk_bf16_f32 v100, v100, v101
	v_cvt_pk_bf16_f32 v101, v102, v103
	v_cvt_pk_bf16_f32 v102, v92, v93
	v_cvt_pk_bf16_f32 v103, v94, v95
	v_cvt_pk_bf16_f32 v80, v80, v81
	v_cvt_pk_bf16_f32 v81, v82, v83
	v_cvt_pk_bf16_f32 v82, v72, v73
	v_cvt_pk_bf16_f32 v83, v74, v75
	v_mov_b32_dpp v246, v80 row_ror:8 row_mask:0xf bank_mask:0xf
	v_mov_b32_dpp v247, v81 row_ror:8 row_mask:0xf bank_mask:0xf
	v_mov_b32_dpp v248, v82 row_ror:8 row_mask:0xf bank_mask:0xf
	v_mov_b32_dpp v249, v83 row_ror:8 row_mask:0xf bank_mask:0xf
	v_mov_b32_dpp v250, v100 row_ror:8 row_mask:0xf bank_mask:0xf
	v_mov_b32_dpp v251, v101 row_ror:8 row_mask:0xf bank_mask:0xf
	v_mov_b32_dpp v252, v102 row_ror:8 row_mask:0xf bank_mask:0xf
	v_mov_b32_dpp v253, v103 row_ror:8 row_mask:0xf bank_mask:0xf
	v_cndmask_b32_e32 v246, v100, v246, vcc
	v_cndmask_b32_e32 v247, v101, v247, vcc
	v_cndmask_b32_e32 v248, v102, v248, vcc
	v_cndmask_b32_e32 v249, v103, v249, vcc
	v_cndmask_b32_e32 v250, v250, v80, vcc
	v_cndmask_b32_e32 v251, v251, v81, vcc
	v_cndmask_b32_e32 v252, v252, v82, vcc
	v_cndmask_b32_e32 v253, v253, v83, vcc
	ds_bpermute_b32 v246, v240, v246
	ds_bpermute_b32 v247, v240, v247
	ds_bpermute_b32 v248, v240, v248
	ds_bpermute_b32 v249, v240, v249
	ds_bpermute_b32 v250, v240, v250
	ds_bpermute_b32 v251, v240, v251
	ds_bpermute_b32 v252, v240, v252
	ds_bpermute_b32 v253, v240, v253
	v_lshl_add_u64 v[238:239], v[140:141], 0, v[242:243]
	s_waitcnt lgkmcnt(4)
	global_store_dwordx4 v[140:141], v[246:249], off
	s_waitcnt lgkmcnt(0)
	global_store_dwordx4 v[238:239], v[250:253], off
	v_lshl_add_u64 v[140:141], v[140:141], 0, s[34:35]
	v_cvt_pk_bf16_f32 v84, v84, v85
	v_cvt_pk_bf16_f32 v85, v86, v87
	v_cvt_pk_bf16_f32 v86, v76, v77
	v_cvt_pk_bf16_f32 v87, v78, v79
	v_cvt_pk_bf16_f32 v68, v68, v69
	v_cvt_pk_bf16_f32 v69, v70, v71
	v_cvt_pk_bf16_f32 v70, v64, v65
	v_cvt_pk_bf16_f32 v71, v66, v67
	v_mov_b32_dpp v246, v68 row_ror:8 row_mask:0xf bank_mask:0xf
	v_mov_b32_dpp v247, v69 row_ror:8 row_mask:0xf bank_mask:0xf
	v_mov_b32_dpp v248, v70 row_ror:8 row_mask:0xf bank_mask:0xf
	v_mov_b32_dpp v249, v71 row_ror:8 row_mask:0xf bank_mask:0xf
	v_mov_b32_dpp v250, v84 row_ror:8 row_mask:0xf bank_mask:0xf
	v_mov_b32_dpp v251, v85 row_ror:8 row_mask:0xf bank_mask:0xf
	v_mov_b32_dpp v252, v86 row_ror:8 row_mask:0xf bank_mask:0xf
	v_mov_b32_dpp v253, v87 row_ror:8 row_mask:0xf bank_mask:0xf
	v_cndmask_b32_e32 v246, v84, v246, vcc
	v_cndmask_b32_e32 v247, v85, v247, vcc
	v_cndmask_b32_e32 v248, v86, v248, vcc
	v_cndmask_b32_e32 v249, v87, v249, vcc
	v_cndmask_b32_e32 v250, v250, v68, vcc
	v_cndmask_b32_e32 v251, v251, v69, vcc
	v_cndmask_b32_e32 v252, v252, v70, vcc
	v_cndmask_b32_e32 v253, v253, v71, vcc
	ds_bpermute_b32 v246, v240, v246
	ds_bpermute_b32 v247, v240, v247
	ds_bpermute_b32 v248, v240, v248
	ds_bpermute_b32 v249, v240, v249
	ds_bpermute_b32 v250, v240, v250
	ds_bpermute_b32 v251, v240, v251
	ds_bpermute_b32 v252, v240, v252
	ds_bpermute_b32 v253, v240, v253
	v_lshl_add_u64 v[238:239], v[140:141], 0, v[242:243]
	s_waitcnt lgkmcnt(4)
	global_store_dwordx4 v[140:141], v[246:249], off
	s_waitcnt lgkmcnt(0)
; __device__ __forceinline__ u32x4 pack8_bf16(f32x4 a, f32x4 b) { u32x4 w; w.x = cvt_pk_bf16(a[0], a[1]); w.y = cvt_pk_bf16(a[2], a[3]); w.z = cvt_pk_bf16(b[0], b[1]); w.w = cvt_pk_bf16(b[2], b[3]); return w; }
; #define ACT(t) (KBASE(t) <= qlo + QBLK - 1 && KBASE(t) + KVBLK - 1 >= qlo - W + 1)
;     __device__ __forceinline__ void operator()(const f32x4 (&acc)[2][2][4][2], const Unit& u, int wr, int wc, int fr, int fq) const {
;     ...
; #pragma unroll
;         for (int ai = 0; ai < 2; ++ai)
; #pragma unroll
;             for (int m = 0; m < 4; ++m) { bf16_t* rowp = base + (size_t)(row0 + ai * HALF + m * 16) * ldc + col0;
; #pragma unroll
;                 for (int bj = 0; bj < 2; ++bj) { f32x4 v0 = acc[ai][bj][m][0], v1 = acc[ai][bj][m][1];
;                     if (ACT == 1) {
; #pragma unroll
;                         for (int j = 0; j < 4; ++j) { float a = fmaxf(v0[j], 0.f), b = fmaxf(v1[j], 0.f); v0[j] = a * a; v1[j] = b * b; } }
;                     *(u32x4*)(rowp + bj * HALF) = pack8_bf16(v0, v1); } }
	global_store_dwordx4 v[238:239], v[250:253], off
	s_mov_b64 s[34:35], 0x50000
	v_lshl_add_u64 v[140:141], v[140:141], 0, s[34:35]
	s_mov_b64 s[34:35], 0x10000
	v_cvt_pk_bf16_f32 v60, v60, v61
	v_cvt_pk_bf16_f32 v61, v62, v63
	v_cvt_pk_bf16_f32 v62, v56, v57
	v_cvt_pk_bf16_f32 v63, v58, v59
	v_cvt_pk_bf16_f32 v48, v48, v49
	v_cvt_pk_bf16_f32 v49, v50, v51
	v_cvt_pk_bf16_f32 v50, v40, v41
	v_cvt_pk_bf16_f32 v51, v42, v43
	v_mov_b32_dpp v246, v48 row_ror:8 row_mask:0xf bank_mask:0xf
	v_mov_b32_dpp v247, v49 row_ror:8 row_mask:0xf bank_mask:0xf
	v_mov_b32_dpp v248, v50 row_ror:8 row_mask:0xf bank_mask:0xf
	v_mov_b32_dpp v249, v51 row_ror:8 row_mask:0xf bank_mask:0xf
	v_mov_b32_dpp v250, v60 row_ror:8 row_mask:0xf bank_mask:0xf
	v_mov_b32_dpp v251, v61 row_ror:8 row_mask:0xf bank_mask:0xf
	v_mov_b32_dpp v252, v62 row_ror:8 row_mask:0xf bank_mask:0xf
	v_mov_b32_dpp v253, v63 row_ror:8 row_mask:0xf bank_mask:0xf
	v_cndmask_b32_e32 v246, v60, v246, vcc
	v_cndmask_b32_e32 v247, v61, v247, vcc
	v_cndmask_b32_e32 v248, v62, v248, vcc
	v_cndmask_b32_e32 v249, v63, v249, vcc
	v_cndmask_b32_e32 v250, v250, v48, vcc
	v_cndmask_b32_e32 v251, v251, v49, vcc
	v_cndmask_b32_e32 v252, v252, v50, vcc
	v_cndmask_b32_e32 v253, v253, v51, vcc
	ds_bpermute_b32 v246, v240, v246
	ds_bpermute_b32 v247, v240, v247
	ds_bpermute_b32 v248, v240, v248
	ds_bpermute_b32 v249, v240, v249
	ds_bpermute_b32 v250, v240, v250
	ds_bpermute_b32 v251, v240, v251
	ds_bpermute_b32 v252, v240, v252
	ds_bpermute_b32 v253, v240, v253
	v_lshl_add_u64 v[238:239], v[140:141], 0, v[242:243]
	s_waitcnt lgkmcnt(4)
	global_store_dwordx4 v[140:141], v[246:249], off
	s_waitcnt lgkmcnt(0)
	global_store_dwordx4 v[238:239], v[250:253], off
	v_lshl_add_u64 v[140:141], v[140:141], 0, s[34:35]
	v_cvt_pk_bf16_f32 v52, v52, v53
	v_cvt_pk_bf16_f32 v53, v54, v55
	v_cvt_pk_bf16_f32 v54, v44, v45
	v_cvt_pk_bf16_f32 v55, v46, v47
	v_cvt_pk_bf16_f32 v32, v32, v33
	v_cvt_pk_bf16_f32 v33, v34, v35
	v_cvt_pk_bf16_f32 v34, v24, v25
	v_cvt_pk_bf16_f32 v35, v26, v27
	v_mov_b32_dpp v246, v32 row_ror:8 row_mask:0xf bank_mask:0xf
	v_mov_b32_dpp v247, v33 row_ror:8 row_mask:0xf bank_mask:0xf
	v_mov_b32_dpp v248, v34 row_ror:8 row_mask:0xf bank_mask:0xf
	v_mov_b32_dpp v249, v35 row_ror:8 row_mask:0xf bank_mask:0xf
	v_mov_b32_dpp v250, v52 row_ror:8 row_mask:0xf bank_mask:0xf
	v_mov_b32_dpp v251, v53 row_ror:8 row_mask:0xf bank_mask:0xf
	v_mov_b32_dpp v252, v54 row_ror:8 row_mask:0xf bank_mask:0xf
	v_mov_b32_dpp v253, v55 row_ror:8 row_mask:0xf bank_mask:0xf
	v_cndmask_b32_e32 v246, v52, v246, vcc
	v_cndmask_b32_e32 v247, v53, v247, vcc
	v_cndmask_b32_e32 v248, v54, v248, vcc
	v_cndmask_b32_e32 v249, v55, v249, vcc
	v_cndmask_b32_e32 v250, v250, v32, vcc
	v_cndmask_b32_e32 v251, v251, v33, vcc
	v_cndmask_b32_e32 v252, v252, v34, vcc
	v_cndmask_b32_e32 v253, v253, v35, vcc
	ds_bpermute_b32 v246, v240, v246
	ds_bpermute_b32 v247, v240, v247
	ds_bpermute_b32 v248, v240, v248
	ds_bpermute_b32 v249, v240, v249
	ds_bpermute_b32 v250, v240, v250
	ds_bpermute_b32 v251, v240, v251
	ds_bpermute_b32 v252, v240, v252
	ds_bpermute_b32 v253, v240, v253
	v_lshl_add_u64 v[238:239], v[140:141], 0, v[242:243]
	s_waitcnt lgkmcnt(4)
	global_store_dwordx4 v[140:141], v[246:249], off
	s_waitcnt lgkmcnt(0)
	global_store_dwordx4 v[238:239], v[250:253], off
	v_lshl_add_u64 v[140:141], v[140:141], 0, s[34:35]
	v_cvt_pk_bf16_f32 v36, v36, v37
	v_cvt_pk_bf16_f32 v37, v38, v39
	v_cvt_pk_bf16_f32 v38, v28, v29
	v_cvt_pk_bf16_f32 v39, v30, v31
	v_cvt_pk_bf16_f32 v16, v16, v17
	v_cvt_pk_bf16_f32 v17, v18, v19
	v_cvt_pk_bf16_f32 v18, v8, v9
	v_cvt_pk_bf16_f32 v19, v10, v11
	v_mov_b32_dpp v246, v16 row_ror:8 row_mask:0xf bank_mask:0xf
	v_mov_b32_dpp v247, v17 row_ror:8 row_mask:0xf bank_mask:0xf
	v_mov_b32_dpp v248, v18 row_ror:8 row_mask:0xf bank_mask:0xf
	v_mov_b32_dpp v249, v19 row_ror:8 row_mask:0xf bank_mask:0xf
	v_mov_b32_dpp v250, v36 row_ror:8 row_mask:0xf bank_mask:0xf
	v_mov_b32_dpp v251, v37 row_ror:8 row_mask:0xf bank_mask:0xf
	v_mov_b32_dpp v252, v38 row_ror:8 row_mask:0xf bank_mask:0xf
	v_mov_b32_dpp v253, v39 row_ror:8 row_mask:0xf bank_mask:0xf
	v_cndmask_b32_e32 v246, v36, v246, vcc
	v_cndmask_b32_e32 v247, v37, v247, vcc
	v_cndmask_b32_e32 v248, v38, v248, vcc
	v_cndmask_b32_e32 v249, v39, v249, vcc
	v_cndmask_b32_e32 v250, v250, v16, vcc
	v_cndmask_b32_e32 v251, v251, v17, vcc
	v_cndmask_b32_e32 v252, v252, v18, vcc
	v_cndmask_b32_e32 v253, v253, v19, vcc
	ds_bpermute_b32 v246, v240, v246
	ds_bpermute_b32 v247, v240, v247
	ds_bpermute_b32 v248, v240, v248
	ds_bpermute_b32 v249, v240, v249
	ds_bpermute_b32 v250, v240, v250
	ds_bpermute_b32 v251, v240, v251
	ds_bpermute_b32 v252, v240, v252
	ds_bpermute_b32 v253, v240, v253
	v_lshl_add_u64 v[238:239], v[140:141], 0, v[242:243]
	s_waitcnt lgkmcnt(4)
	global_store_dwordx4 v[140:141], v[246:249], off
	s_waitcnt lgkmcnt(0)
	global_store_dwordx4 v[238:239], v[250:253], off
	v_lshl_add_u64 v[140:141], v[140:141], 0, s[34:35]
	v_cvt_pk_bf16_f32 v20, v20, v21
	v_cvt_pk_bf16_f32 v21, v22, v23
	v_cvt_pk_bf16_f32 v22, v12, v13
	v_cvt_pk_bf16_f32 v23, v14, v15
	v_cvt_pk_bf16_f32 v4, v4, v5
	v_cvt_pk_bf16_f32 v5, v6, v7
	v_cvt_pk_bf16_f32 v6, v0, v1
	v_cvt_pk_bf16_f32 v7, v2, v3
	v_mov_b32_dpp v246, v4 row_ror:8 row_mask:0xf bank_mask:0xf
	v_mov_b32_dpp v247, v5 row_ror:8 row_mask:0xf bank_mask:0xf
	v_mov_b32_dpp v248, v6 row_ror:8 row_mask:0xf bank_mask:0xf
	v_mov_b32_dpp v249, v7 row_ror:8 row_mask:0xf bank_mask:0xf
	v_mov_b32_dpp v250, v20 row_ror:8 row_mask:0xf bank_mask:0xf
	v_mov_b32_dpp v251, v21 row_ror:8 row_mask:0xf bank_mask:0xf
	v_mov_b32_dpp v252, v22 row_ror:8 row_mask:0xf bank_mask:0xf
	v_mov_b32_dpp v253, v23 row_ror:8 row_mask:0xf bank_mask:0xf
	v_cndmask_b32_e32 v246, v20, v246, vcc
	v_cndmask_b32_e32 v247, v21, v247, vcc
	v_cndmask_b32_e32 v248, v22, v248, vcc
	v_cndmask_b32_e32 v249, v23, v249, vcc
	v_cndmask_b32_e32 v250, v250, v4, vcc
	v_cndmask_b32_e32 v251, v251, v5, vcc
	v_cndmask_b32_e32 v252, v252, v6, vcc
	v_cndmask_b32_e32 v253, v253, v7, vcc
	ds_bpermute_b32 v246, v240, v246
	ds_bpermute_b32 v247, v240, v247
	ds_bpermute_b32 v248, v240, v248
	ds_bpermute_b32 v249, v240, v249
	ds_bpermute_b32 v250, v240, v250
	ds_bpermute_b32 v251, v240, v251
	ds_bpermute_b32 v252, v240, v252
	ds_bpermute_b32 v253, v240, v253
	v_lshl_add_u64 v[238:239], v[140:141], 0, v[242:243]
	s_waitcnt lgkmcnt(4)
	global_store_dwordx4 v[140:141], v[246:249], off
	s_waitcnt lgkmcnt(0)
	global_store_dwordx4 v[238:239], v[250:253], off
	s_andn2_b64 vcc, exec, s[40:41]
	s_mov_b64 s[34:35], -1
	s_cbranch_vccnz .LBB0_88
	s_andn2_b64 vcc, exec, s[18:19]
	s_cbranch_vccnz .LBB0_87
	s_barrier
	s_branch .LBB0_87

; #define PG8_STAGE(bufoff, gbase, voff) do { _Pragma("unroll") for (int _i = 0; _i < 2; ++_i) \
;         __builtin_amdgcn_global_load_lds((const unsigned*)((const char*)(gbase) + (voff)[_i]), (PG8_LAS unsigned*)(lds + (bufoff) + ldsw + _i * 8192), 16, 0, 0); } while (0)
; #define PG8_WAIT_V(n) asm volatile("s_waitcnt vmcnt(" #n ")" ::: "memory")
; template <class Epi, class Sched, bool ALIGN_EPI = false, bool SP2 = false>
; __device__ __forceinline__ void gemm_phase(PG8_LAS unsigned char* lds, const Gemm g, const Sched& S, const Epi& E) {
;     int tid_l_ = threadIdx.x; asm volatile("" : "+v"(tid_l_)); const int tid = tid_l_, wid = __builtin_amdgcn_readfirstlane(tid >> 6), lane = tid & 63, wr = wid >> 2, wc = wid & 3, fr = lane & 15, fq = lane >> 4;
;     const int K = g.K, nt = K / BK;
;     unsigned voffA[2], voffB[2];
; #pragma unroll
;     for (int i = 0; i < 2; ++i) { int R, C; stage_rc(tid * 16 + i * 8192, R, C); const int Rb = Epi::PERM ? ((R & ~31) + perm32(R & 31)) : R;
;         voffA[i] = (unsigned)(R * K + C) * 2u; voffB[i] = (unsigned)(Rb * K + C) * 2u; }
;     const size_t kstep = (size_t)(BK * 2);
;     const size_t hstep = (size_t)HALF * K * 2;
;     const size_t tstep = 2 * hstep;
;     const unsigned ldsw = (unsigned)wid * 1024u;
;     const int aoff = lds_byte(wr * 64 + fr, fq * 8), boff = lds_byte(wc * 32 + fr, fq * 8);
;     ...
;     Unit cur, nxt; int ui = 0;
;     if (!S.next(0, cur)) return;
;     f32x4 acc[2][2][4][2];
; #pragma unroll
;     for (int a = 0; a < 2; ++a)
; #pragma unroll
;         for (int b = 0; b < 2; ++b)
; #pragma unroll
;             for (int m = 0; m < 4; ++m)
; #pragma unroll
;                 for (int n = 0; n < 2; ++n) acc[a][b][m][n] = (f32x4){0.f, 0.f, 0.f, 0.f};
;     bf16x8 At[4][2], B0[2][2], B1[2][2];
;     const char* cA = (const char*)g.A + (size_t)cur.pm * tstep; const char* cB = (const char*)g.Bt + (size_t)cur.pn * tstep;
;     S.a_ready(cur);
;     if constexpr (SP2) {
;         PG8_STAGE(PG8_SB(0, 0), cB, voffB); PG8_STAGE(PG8_SB(0, 1), cB + hstep, voffB); PG8_STAGE(PG8_SA(0, 0), cA, voffA); PG8_STAGE(PG8_SA(0, 1), cA + hstep, voffA);
;         if (wr == 1) PG8_BAR;
;         PG8_WAIT_V(2); PG8_BAR;
;         PG8_STAGE(PG8_SB(1, 0), cB + kstep, voffB); PG8_STAGE(PG8_SA(1, 0), cA + kstep, voffA); PG8_STAGE(PG8_SB(1, 1), cB + hstep + kstep, voffB);
;         PG8_WAIT_V(6); PG8_BAR;
.LBB0_418:
	s_andn2_b64 vcc, exec, s[8:9]
	s_cbranch_vccnz .LBB0_439
	s_waitcnt vmcnt(0)
	v_mov_b32_e32 v6, v208
	s_cmpk_gt_i32 s23, 0x1ff
	s_nop 0
	v_readfirstlane_b32 s12, v6
	s_cbranch_scc1 .LBB0_439
	v_lshlrev_b32_e32 v3, 4, v6
	v_add_u32_e32 v1, 0x2000, v3
	v_ashrrev_i32_e32 v0, 31, v1
	v_lshrrev_b32_e32 v0, 22, v0
	v_add_u32_e32 v0, v1, v0
	v_ashrrev_i32_e32 v0, 10, v0
	v_mul_i32_i24_e32 v2, 0x400, v0
	v_sub_u32_e32 v1, v1, v2
	v_lshrrev_b32_e32 v2, 4, v1
	v_bitop3_b32 v2, v2, v1, 32 bitop3:0x6c
	v_ashrrev_i32_e32 v1, 31, v2
	v_lshrrev_b32_e32 v1, 26, v1
	v_add_u32_e32 v4, v2, v1
	v_lshlrev_b32_e32 v5, 3, v0
	v_ashrrev_i32_e32 v1, 6, v4
	v_and_b32_e32 v5, -16, v5
	v_add_u32_e32 v5, v1, v5
	v_and_b32_e32 v7, 3, v1
	s_mov_b32 s7, 0x3ffe0
	v_lshrrev_b32_e32 v8, 2, v5
	v_lshlrev_b32_e32 v9, 1, v5
	v_and_b32_e32 v4, 0xc0, v4
	v_and_b32_e32 v252, s7, v5
	v_lshl_or_b32 v7, v252, 1, v7
	v_and_b32_e32 v8, 4, v8
	v_and_b32_e32 v9, 24, v9
	v_sub_u32_e32 v2, v2, v4
	v_mov_b32_e32 v12, 1
	v_or3_b32 v7, v7, v8, v9
	v_lshlrev_b32_e32 v8, 5, v0
	v_ashrrev_i16_sdwa v2, v12, sext(v2) dst_sel:DWORD dst_unused:UNUSED_PAD src0_sel:DWORD src1_sel:BYTE_0
	v_and_b32_e32 v8, 32, v8
	v_bfe_i32 v2, v2, 0, 16
	v_add_lshl_u32 v4, v8, v2, 1
	v_lshl_add_u32 v130, v7, 14, v4
	v_lshl_add_u32 v132, v5, 14, v4
	v_bfe_i32 v4, v6, 27, 1
	v_lshrrev_b32_e32 v4, 22, v4
	v_add_u32_e32 v4, v3, v4
	v_and_b32_e32 v4, 0xfffffc00, v4
	v_sub_u32_e32 v3, v3, v4
	v_lshrrev_b32_e32 v4, 4, v3
	v_bitop3_b32 v5, v4, v3, 32 bitop3:0x6c
	v_ashrrev_i32_e32 v4, 31, v6
	v_lshrrev_b32_e32 v4, 26, v4
	v_ashrrev_i32_e32 v3, 31, v5
	v_add_u32_e32 v4, v6, v4
	v_lshrrev_b32_e32 v3, 26, v3
	v_ashrrev_i32_e32 v4, 6, v4
	v_add_u32_e32 v7, v5, v3
	v_lshlrev_b32_e32 v8, 3, v4
	v_ashrrev_i32_e32 v3, 6, v7
	v_and_b32_e32 v8, -16, v8
	v_add_u32_e32 v8, v3, v8
	v_and_b32_e32 v9, 3, v3
	s_ashr_i32 s13, s12, 6
	v_and_b32_e32 v252, s7, v8
	v_lshl_or_b32 v9, v252, 1, v9
	v_readlane_b32 s6, v255, 2
	s_ashr_i32 s18, s12, 8
	s_lshl_b32 s2, s13, 10
	v_readlane_b32 s7, v255, 3
	s_and_b64 s[8:9], s[6:7], exec
	s_cselect_b32 s8, s91, s17
	s_add_i32 s8, s8, s74
	s_ashr_i32 s9, s8, 31
	s_lshr_b32 s9, s9, 27
	s_add_i32 s9, s8, s9
	s_ashr_i32 s10, s9, 5
	s_lshl_b32 s10, s10, 2
	s_mov_b32 s6, s17
	s_sub_i32 s17, 64, s10
	s_min_i32 s17, s17, 4
	v_and_b32_e32 v7, 0xc0, v7
	s_abs_i32 s19, s17
	v_sub_u32_e32 v5, v5, v7
	v_cvt_f32_u32_e32 v7, s19
	s_sub_i32 s27, 0, s19
	s_andn2_b32 s9, s9, 31
	s_sub_i32 s8, s8, s9
	v_rcp_iflag_f32_e32 v7, v7
	s_abs_i32 s26, s8
	s_xor_b32 s9, s8, s17
	s_ashr_i32 s9, s9, 31
	v_mul_f32_e32 v7, 0x4f7ffffe, v7
	v_cvt_u32_f32_e32 v7, v7
	v_lshrrev_b32_e32 v10, 2, v8
	v_lshlrev_b32_e32 v11, 1, v8
	v_and_b32_e32 v10, 4, v10
	v_readfirstlane_b32 s28, v7
	s_mul_i32 s27, s27, s28
	s_mul_hi_u32 s27, s28, s27
	s_add_i32 s28, s28, s27
	s_mul_hi_u32 s27, s26, s28
	s_mul_i32 s28, s27, s19
	s_sub_i32 s26, s26, s28
	s_add_i32 s28, s27, 1
	s_sub_i32 s29, s26, s19
	s_cmp_ge_u32 s26, s19
	s_cselect_b32 s27, s28, s27
	s_cselect_b32 s26, s29, s26
	s_add_i32 s28, s27, 1
	s_cmp_ge_u32 s26, s19
	s_cselect_b32 s19, s28, s27
	s_xor_b32 s19, s19, s9
	s_sub_i32 s9, s19, s9
	s_mul_i32 s17, s9, s17
	s_sub_i32 s8, s8, s17
	s_add_i32 s8, s8, s90
	s_add_i32 s42, s8, s10
	s_add_i32 s44, s9, s94
	v_and_b32_e32 v11, 24, v11
	s_ashr_i32 s43, s42, 31
	s_ashr_i32 s45, s44, 31
	v_or3_b32 v9, v9, v10, v11
	v_lshlrev_b32_e32 v10, 5, v4
	v_ashrrev_i16_sdwa v5, v12, sext(v5) dst_sel:DWORD dst_unused:UNUSED_PAD src0_sel:DWORD src1_sel:BYTE_0
	s_lshl_b64 s[8:9], s[42:43], 22
	s_lshl_b64 s[26:27], s[44:45], 22
	v_and_b32_e32 v10, 32, v10
	v_bfe_i32 v5, v5, 0, 16
	s_add_u32 s68, s50, s26
	v_add_lshl_u32 v10, v10, v5, 1
	s_addc_u32 s69, s51, s27
	s_add_i32 s10, s2, 0
	v_lshl_add_u32 v128, v9, 14, v10
	s_add_i32 m0, s10, 0x10000
	s_mov_b32 s72, s66
	global_load_lds_dwordx4 v128, s[68:69]
	s_add_i32 m0, s10, 0x12000
	s_add_u32 s26, s68, 0x80000
	global_load_lds_dwordx4 v130, s[68:69]
	s_addc_u32 s27, s69, 0
	s_add_i32 m0, s10, 0x14000
	s_mov_b32 s73, s67
	global_load_lds_dwordx4 v128, s[26:27]
	s_add_i32 m0, s10, 0x16000
	s_add_u32 s66, s60, s8
	s_addc_u32 s67, s61, s9
	s_add_i32 s17, s10, 0x2000
	v_lshl_add_u32 v134, v8, 14, v10
	global_load_lds_dwordx4 v130, s[26:27]
	s_mov_b32 m0, s10
	s_add_u32 s8, s66, 0x200000
	global_load_lds_dwordx4 v134, s[66:67]
	s_mov_b32 m0, s17
	s_addc_u32 s9, s67, 0
	s_add_i32 s26, s10, 0x4000
	global_load_lds_dwordx4 v132, s[66:67]
	s_mov_b32 m0, s26
	s_add_i32 s27, s10, 0x6000
	global_load_lds_dwordx4 v134, s[8:9]
	s_mov_b32 m0, s27
	s_cmp_eq_u32 s18, 1
	global_load_lds_dwordx4 v132, s[8:9]
	s_cselect_b64 s[8:9], -1, 0
	s_cmp_lg_u32 s18, 1
	s_cbranch_scc1 .LBB0_422
	s_barrier
.LBB0_422:
	v_lshrrev_b32_e32 v16, 1, v6
	v_and_b32_e32 v16, 24, v16
	s_lshl_b32 s13, s13, 5
	v_and_b32_e32 v7, 15, v6
	v_lshlrev_b32_e32 v17, 1, v16
	v_lshlrev_b32_e32 v6, 2, v6
	s_and_b32 s30, s13, 0x60
	v_lshl_add_u64 v[8:9], s[68:69], 0, v[128:129]
	v_mov_b32_e32 v131, v129
	v_bfe_u32 v252, v208, 3, 3
	v_lshl_or_b32 v142, s18, 6, v252
	v_lshl_or_b32 v7, v7, 6, v17
	s_lshl_b32 s18, s18, 13
	v_and_b32_e32 v6, 32, v6
	s_lshl_b32 s13, s30, 7
	v_lshl_add_u64 v[10:11], s[68:69], 0, v[130:131]
	v_mov_b32_e32 v135, v129
	v_bitop3_b32 v17, v7, s18, v6 bitop3:0xde
	v_bitop3_b32 v143, v7, s13, v6 bitop3:0xde
	s_add_i32 m0, s10, 0x18000
	v_lshl_add_u64 v[6:7], v[8:9], 0, s[20:21]
	v_lshl_add_u64 v[12:13], s[66:67], 0, v[134:135]
	v_mov_b32_e32 v133, v129
	s_waitcnt vmcnt(2)
	s_barrier
	global_load_lds_dwordx4 v[6:7], off
	v_lshl_add_u64 v[6:7], v[10:11], 0, s[20:21]
	s_add_i32 m0, s10, 0x1a000
	s_add_i32 s28, s10, 0x8000
	s_add_i32 s29, s10, 0xa000
	v_lshl_add_u64 v[14:15], s[66:67], 0, v[132:133]
	global_load_lds_dwordx4 v[6:7], off
	v_lshl_add_u64 v[6:7], v[12:13], 0, s[20:21]
	s_mov_b32 m0, s28
	s_add_u32 s18, s68, 0x80080
	global_load_lds_dwordx4 v[6:7], off
	v_lshl_add_u64 v[6:7], v[14:15], 0, s[20:21]
	s_mov_b32 m0, s29
	s_addc_u32 s19, s69, 0
	global_load_lds_dwordx4 v[6:7], off
	s_add_i32 m0, s10, 0x1c000
	v_lshl_add_u64 v[6:7], s[18:19], 0, v[128:129]
	global_load_lds_dwordx4 v[6:7], off
	v_lshl_add_u64 v[6:7], s[18:19], 0, v[130:131]
	s_add_i32 m0, s10, 0x1e000
	s_cmpk_lt_u32 s12, 0x100
	global_load_lds_dwordx4 v[6:7], off
	v_lshlrev_b32_e32 v6, 17, v4
	v_and_b32_e32 v6, 0xfffc0000, v6
	v_lshl_add_u32 v3, v3, 14, v6
	v_and_b32_e32 v4, 1, v4
	v_lshl_or_b32 v3, v4, 6, v3
	v_lshl_add_u32 v136, v5, 1, v3
	v_lshlrev_b32_e32 v3, 17, v0
	v_and_b32_e32 v3, 0xfffc0000, v3
	s_waitcnt vmcnt(6)
	v_lshl_add_u32 v1, v1, 14, v3
	v_and_b32_e32 v0, 1, v0
	v_lshl_or_b32 v0, v0, 6, v1
	s_cselect_b64 s[12:13], -1, 0
	v_and_b32_e32 v252, 7, v208
	v_lshlrev_b32_e32 v252, 3, v252
	v_lshl_or_b32 v144, s30, 1, v252
	v_mov_b32_e32 v137, v129
	v_lshl_add_u32 v138, v2, 1, v0
	v_mov_b32_e32 v139, v129
	s_mov_b32 s33, 0
	v_add_u32_e32 v145, 0, v17
	s_barrier
	s_branch .LBB0_425

; #define PG8_STAGE(bufoff, gbase, voff) do { _Pragma("unroll") for (int _i = 0; _i < 2; ++_i) \
;         __builtin_amdgcn_global_load_lds((const unsigned*)((const char*)(gbase) + (voff)[_i]), (PG8_LAS unsigned*)(lds + (bufoff) + ldsw + _i * 8192), 16, 0, 0); } while (0)
; #define PG8_LDA(dst, b, h) do { _Pragma("unroll") for (int m = 0; m < 4; ++m) _Pragma("unroll") for (int k = 0; k < 2; ++k) dst[m][k] = *(const PG8_LAS bf16x8*)(lds + PG8_SA(b, h) + aoff + m * 2048 + k * 1024); } while (0)
; #define PG8_MMA(ai, bj, At, Bt) do { __builtin_amdgcn_s_setprio(1); _Pragma("unroll") for (int m = 0; m < 4; ++m) _Pragma("unroll") for (int n = 0; n < 2; ++n) _Pragma("unroll") for (int k = 0; k < 2; ++k) \
;         acc[ai][bj][m][n] = __builtin_amdgcn_mfma_f32_16x16x32_bf16(Bt[n][k], At[m][k], acc[ai][bj][m][n], 0, 0, 0); __builtin_amdgcn_s_setprio(0); } while (0)
; #define PG8_WAIT_V(n) asm volatile("s_waitcnt vmcnt(" #n ")" ::: "memory")
; #define PG8_WAIT_L(n) asm volatile("s_waitcnt lgkmcnt(" #n ")" ::: "memory")
; #define PG8_BAR __builtin_amdgcn_s_barrier()
; #define PG8_SCHED __builtin_amdgcn_sched_barrier(0)
; template <class Epi, class Sched, bool ALIGN_EPI = false, bool SP2 = false>
; __device__ __forceinline__ void gemm_phase(PG8_LAS unsigned char* lds, const Gemm g, const Sched& S, const Epi& E) {
;     ...
;             PG8_WAIT_V(8); PG8_WAIT_L(0); PG8_BAR; PG8_MMA(0, 0, At, B0); PG8_MMA(0, 1, At, B1); PG8_BAR; PG8_SCHED;
;             PG8_LDA(At, 0, 1); PG8_STAGE(PG8_SB(0, 0), b2, voffB); PG8_STAGE(PG8_SB(0, 1), b2 + hstep, voffB); PG8_STAGE(PG8_SA(0, 0), a2, voffA);
;             PG8_WAIT_V(8); PG8_WAIT_L(0); PG8_BAR; PG8_MMA(1, 0, At, B0); PG8_MMA(1, 1, At, B1); PG8_BAR; PG8_SCHED;
.Lrx7_0_join:
	s_waitcnt lgkmcnt(0)
	s_barrier
	s_setprio 1
	s_waitcnt lgkmcnt(0)
	v_mfma_f32_16x16x32_bf16 v[124:127], v[146:149], v[178:181], v[124:127]
	v_mfma_f32_16x16x32_bf16 v[120:123], v[154:157], v[178:181], v[120:123]
	v_mfma_f32_16x16x32_bf16 v[116:119], v[146:149], v[186:189], v[116:119]
	v_mfma_f32_16x16x32_bf16 v[108:111], v[154:157], v[186:189], v[108:111]
	v_mfma_f32_16x16x32_bf16 v[100:103], v[146:149], v[220:223], v[100:103]
	v_mfma_f32_16x16x32_bf16 v[92:95], v[154:157], v[220:223], v[92:95]
	v_mfma_f32_16x16x32_bf16 v[84:87], v[146:149], v[228:231], v[84:87]
	v_mfma_f32_16x16x32_bf16 v[76:79], v[154:157], v[228:231], v[76:79]
	v_mfma_f32_16x16x32_bf16 v[124:127], v[150:153], v[182:185], v[124:127]
	v_mfma_f32_16x16x32_bf16 v[120:123], v[158:161], v[182:185], v[120:123]
	v_mfma_f32_16x16x32_bf16 v[116:119], v[150:153], v[190:193], v[116:119]
	v_mfma_f32_16x16x32_bf16 v[108:111], v[158:161], v[190:193], v[108:111]
	v_mfma_f32_16x16x32_bf16 v[100:103], v[150:153], v[224:227], v[100:103]
	v_mfma_f32_16x16x32_bf16 v[92:95], v[158:161], v[224:227], v[92:95]
	v_mfma_f32_16x16x32_bf16 v[84:87], v[150:153], v[232:235], v[84:87]
	v_mfma_f32_16x16x32_bf16 v[76:79], v[158:161], v[232:235], v[76:79]
	s_setprio 0
	s_setprio 1
	v_mfma_f32_16x16x32_bf16 v[112:115], v[162:165], v[178:181], v[112:115]
	v_mfma_f32_16x16x32_bf16 v[104:107], v[170:173], v[178:181], v[104:107]
	v_mfma_f32_16x16x32_bf16 v[96:99], v[162:165], v[186:189], v[96:99]
	v_mfma_f32_16x16x32_bf16 v[88:91], v[170:173], v[186:189], v[88:91]
	v_mfma_f32_16x16x32_bf16 v[80:83], v[162:165], v[220:223], v[80:83]
	v_mfma_f32_16x16x32_bf16 v[72:75], v[170:173], v[220:223], v[72:75]
	v_mfma_f32_16x16x32_bf16 v[68:71], v[162:165], v[228:231], v[68:71]
	v_mfma_f32_16x16x32_bf16 v[64:67], v[170:173], v[228:231], v[64:67]
	v_mfma_f32_16x16x32_bf16 v[112:115], v[166:169], v[182:185], v[112:115]
	v_mfma_f32_16x16x32_bf16 v[104:107], v[174:177], v[182:185], v[104:107]
	v_mfma_f32_16x16x32_bf16 v[96:99], v[166:169], v[190:193], v[96:99]
	v_mfma_f32_16x16x32_bf16 v[88:91], v[174:177], v[190:193], v[88:91]
	v_mfma_f32_16x16x32_bf16 v[80:83], v[166:169], v[224:227], v[80:83]
	v_mfma_f32_16x16x32_bf16 v[72:75], v[174:177], v[224:227], v[72:75]
	v_mfma_f32_16x16x32_bf16 v[68:71], v[166:169], v[232:235], v[68:71]
	v_mfma_f32_16x16x32_bf16 v[64:67], v[174:177], v[232:235], v[64:67]
	s_setprio 0
	s_barrier
	s_add_i32 s52, s53, s2
	v_lshl_add_u64 v[140:141], s[68:69], 0, v[128:129]
	s_mov_b32 m0, s52
	ds_read_b128 v[178:181], v145 offset:16384
	ds_read_b128 v[182:185], v145 offset:17408
	ds_read_b128 v[186:189], v145 offset:18432
	ds_read_b128 v[190:193], v145 offset:19456
	ds_read_b128 v[220:223], v145 offset:20480
	ds_read_b128 v[224:227], v145 offset:21504
	ds_read_b128 v[228:231], v145 offset:22528
	ds_read_b128 v[232:235], v145 offset:23552
	global_load_lds_dwordx4 v[140:141], off
	s_add_i32 m0, s52, 0x2000
	s_add_u32 s52, s68, 0x80000
	v_lshl_add_u64 v[206:207], s[68:69], 0, v[130:131]
	s_addc_u32 s53, s69, 0
	s_add_i32 s49, s49, s2
	global_load_lds_dwordx4 v[206:207], off
	v_lshl_add_u64 v[214:215], s[52:53], 0, v[128:129]
	s_mov_b32 m0, s49
	v_lshl_add_u64 v[216:217], s[70:71], 0, v[132:133]
	global_load_lds_dwordx4 v[214:215], off
	v_lshl_add_u64 v[214:215], s[52:53], 0, v[130:131]
	s_add_i32 m0, s49, 0x2000
	s_nop 0
	global_load_lds_dwordx4 v[214:215], off
	v_lshl_add_u64 v[214:215], s[70:71], 0, v[134:135]
	s_mov_b32 m0, s10
	s_nop 0
	global_load_lds_dwordx4 v[214:215], off
	s_mov_b32 m0, s17
	s_nop 0
	global_load_lds_dwordx4 v[216:217], off
	s_cmp_lt_i32 s45, 0
	s_cbranch_scc0 .Lrx7_1_norm
	s_cmp_lt_u32 s33, 2
	s_cbranch_scc1 .Lrx7_1_norm
	s_waitcnt vmcnt(24)
	s_branch .Lrx7_1_join

; #define PG8_STAGE(bufoff, gbase, voff) do { _Pragma("unroll") for (int _i = 0; _i < 2; ++_i) \
;         __builtin_amdgcn_global_load_lds((const unsigned*)((const char*)(gbase) + (voff)[_i]), (PG8_LAS unsigned*)(lds + (bufoff) + ldsw + _i * 8192), 16, 0, 0); } while (0)
; #define PG8_LDA(dst, b, h) do { _Pragma("unroll") for (int m = 0; m < 4; ++m) _Pragma("unroll") for (int k = 0; k < 2; ++k) dst[m][k] = *(const PG8_LAS bf16x8*)(lds + PG8_SA(b, h) + aoff + m * 2048 + k * 1024); } while (0)
; #define PG8_LDB(dst, b, h) do { _Pragma("unroll") for (int n = 0; n < 2; ++n) _Pragma("unroll") for (int k = 0; k < 2; ++k) dst[n][k] = *(const PG8_LAS bf16x8*)(lds + PG8_SB(b, h) + boff + n * 2048 + k * 1024); } while (0)
; #define PG8_MMA(ai, bj, At, Bt) do { __builtin_amdgcn_s_setprio(1); _Pragma("unroll") for (int m = 0; m < 4; ++m) _Pragma("unroll") for (int n = 0; n < 2; ++n) _Pragma("unroll") for (int k = 0; k < 2; ++k) \
;         acc[ai][bj][m][n] = __builtin_amdgcn_mfma_f32_16x16x32_bf16(Bt[n][k], At[m][k], acc[ai][bj][m][n], 0, 0, 0); __builtin_amdgcn_s_setprio(0); } while (0)
; #define PG8_WAIT_V(n) asm volatile("s_waitcnt vmcnt(" #n ")" ::: "memory")
; #define PG8_WAIT_L(n) asm volatile("s_waitcnt lgkmcnt(" #n ")" ::: "memory")
; #define PG8_BAR __builtin_amdgcn_s_barrier()
; #define PG8_SCHED __builtin_amdgcn_sched_barrier(0)
; template <class Epi, class Sched, bool ALIGN_EPI = false, bool SP2 = false>
; __device__ __forceinline__ void gemm_phase(PG8_LAS unsigned char* lds, const Gemm g, const Sched& S, const Epi& E) {
;     ...
;             PG8_WAIT_V(8); PG8_WAIT_L(0); PG8_BAR; PG8_MMA(1, 0, At, B0); PG8_MMA(1, 1, At, B1); PG8_BAR; PG8_SCHED;
;             PG8_LDB(B0, 1, 0); PG8_LDB(B1, 1, 1); PG8_SCHED; PG8_LDA(At, 1, 0); PG8_STAGE(PG8_SA(0, 1), a2 + hstep, voffA);
;             PG8_WAIT_V(8); PG8_WAIT_L(0); PG8_BAR; PG8_MMA(0, 0, At, B0); PG8_MMA(0, 1, At, B1); PG8_BAR; PG8_SCHED;
.Lrx7_1_join:
	s_waitcnt lgkmcnt(0)
	s_barrier
	s_setprio 1
	s_waitcnt lgkmcnt(0)
	v_mfma_f32_16x16x32_bf16 v[60:63], v[146:149], v[178:181], v[60:63]
	v_mfma_f32_16x16x32_bf16 v[56:59], v[154:157], v[178:181], v[56:59]
	v_mfma_f32_16x16x32_bf16 v[52:55], v[146:149], v[186:189], v[52:55]
	v_mfma_f32_16x16x32_bf16 v[44:47], v[154:157], v[186:189], v[44:47]
	v_mfma_f32_16x16x32_bf16 v[36:39], v[146:149], v[220:223], v[36:39]
	v_mfma_f32_16x16x32_bf16 v[28:31], v[154:157], v[220:223], v[28:31]
	v_mfma_f32_16x16x32_bf16 v[20:23], v[146:149], v[228:231], v[20:23]
	v_mfma_f32_16x16x32_bf16 v[12:15], v[154:157], v[228:231], v[12:15]
	v_mfma_f32_16x16x32_bf16 v[60:63], v[150:153], v[182:185], v[60:63]
	v_mfma_f32_16x16x32_bf16 v[56:59], v[158:161], v[182:185], v[56:59]
	v_mfma_f32_16x16x32_bf16 v[52:55], v[150:153], v[190:193], v[52:55]
	v_mfma_f32_16x16x32_bf16 v[44:47], v[158:161], v[190:193], v[44:47]
	v_mfma_f32_16x16x32_bf16 v[36:39], v[150:153], v[224:227], v[36:39]
	v_mfma_f32_16x16x32_bf16 v[28:31], v[158:161], v[224:227], v[28:31]
	v_mfma_f32_16x16x32_bf16 v[20:23], v[150:153], v[232:235], v[20:23]
	v_mfma_f32_16x16x32_bf16 v[12:15], v[158:161], v[232:235], v[12:15]
	s_setprio 0
	s_setprio 1
	v_mfma_f32_16x16x32_bf16 v[48:51], v[162:165], v[178:181], v[48:51]
	v_mfma_f32_16x16x32_bf16 v[40:43], v[170:173], v[178:181], v[40:43]
	v_mfma_f32_16x16x32_bf16 v[32:35], v[162:165], v[186:189], v[32:35]
	v_mfma_f32_16x16x32_bf16 v[24:27], v[170:173], v[186:189], v[24:27]
	v_mfma_f32_16x16x32_bf16 v[16:19], v[162:165], v[220:223], v[16:19]
	v_mfma_f32_16x16x32_bf16 v[8:11], v[170:173], v[220:223], v[8:11]
	v_mfma_f32_16x16x32_bf16 v[4:7], v[162:165], v[228:231], v[4:7]
	v_mfma_f32_16x16x32_bf16 v[0:3], v[170:173], v[228:231], v[0:3]
	v_mfma_f32_16x16x32_bf16 v[48:51], v[166:169], v[182:185], v[48:51]
	v_mfma_f32_16x16x32_bf16 v[40:43], v[174:177], v[182:185], v[40:43]
	v_mfma_f32_16x16x32_bf16 v[32:35], v[166:169], v[190:193], v[32:35]
	v_mfma_f32_16x16x32_bf16 v[24:27], v[174:177], v[190:193], v[24:27]
	v_mfma_f32_16x16x32_bf16 v[16:19], v[166:169], v[224:227], v[16:19]
	v_mfma_f32_16x16x32_bf16 v[8:11], v[174:177], v[224:227], v[8:11]
	v_mfma_f32_16x16x32_bf16 v[4:7], v[166:169], v[232:235], v[4:7]
	v_mfma_f32_16x16x32_bf16 v[0:3], v[174:177], v[232:235], v[0:3]
	s_setprio 0
	s_barrier
	s_add_i32 s49, 0, 0x18000
	s_add_i32 s83, 0, 0x1c000
	v_add_u32_e32 v158, s49, v143
	v_add_u32_e32 v174, s83, v143
	ds_read_b128 v[146:149], v158
	ds_read_b128 v[150:153], v158 offset:1024
	ds_read_b128 v[154:157], v158 offset:2048
	ds_read_b128 v[158:161], v158 offset:3072
	ds_read_b128 v[162:165], v174
	ds_read_b128 v[166:169], v174 offset:1024
	ds_read_b128 v[170:173], v174 offset:2048
	ds_read_b128 v[174:177], v174 offset:3072
	s_add_u32 s52, s70, 0x200000
	s_addc_u32 s53, s71, 0
	s_mov_b32 m0, s26
	v_lshl_add_u64 v[236:237], s[52:53], 0, v[134:135]
	ds_read_b128 v[178:181], v145 offset:32768
	ds_read_b128 v[182:185], v145 offset:33792
	ds_read_b128 v[186:189], v145 offset:34816
	ds_read_b128 v[190:193], v145 offset:35840
	ds_read_b128 v[220:223], v145 offset:36864
	ds_read_b128 v[224:227], v145 offset:37888
	ds_read_b128 v[228:231], v145 offset:38912
	ds_read_b128 v[232:235], v145 offset:39936
	global_load_lds_dwordx4 v[236:237], off
	v_lshl_add_u64 v[236:237], s[52:53], 0, v[132:133]
	s_mov_b32 m0, s27
	s_nop 0
	global_load_lds_dwordx4 v[236:237], off
	s_waitcnt vmcnt(8)
	s_waitcnt lgkmcnt(0)
	s_barrier
	s_setprio 1
	s_waitcnt lgkmcnt(0)
	v_mfma_f32_16x16x32_bf16 v[124:127], v[146:149], v[178:181], v[124:127]
	v_mfma_f32_16x16x32_bf16 v[120:123], v[154:157], v[178:181], v[120:123]
	v_mfma_f32_16x16x32_bf16 v[116:119], v[146:149], v[186:189], v[116:119]
	v_mfma_f32_16x16x32_bf16 v[108:111], v[154:157], v[186:189], v[108:111]
	v_mfma_f32_16x16x32_bf16 v[100:103], v[146:149], v[220:223], v[100:103]
	v_mfma_f32_16x16x32_bf16 v[92:95], v[154:157], v[220:223], v[92:95]
	v_mfma_f32_16x16x32_bf16 v[84:87], v[146:149], v[228:231], v[84:87]
	v_mfma_f32_16x16x32_bf16 v[76:79], v[154:157], v[228:231], v[76:79]
	v_mfma_f32_16x16x32_bf16 v[124:127], v[150:153], v[182:185], v[124:127]
	v_mfma_f32_16x16x32_bf16 v[120:123], v[158:161], v[182:185], v[120:123]
	v_mfma_f32_16x16x32_bf16 v[116:119], v[150:153], v[190:193], v[116:119]
	v_mfma_f32_16x16x32_bf16 v[108:111], v[158:161], v[190:193], v[108:111]
	v_mfma_f32_16x16x32_bf16 v[100:103], v[150:153], v[224:227], v[100:103]
	v_mfma_f32_16x16x32_bf16 v[92:95], v[158:161], v[224:227], v[92:95]
	v_mfma_f32_16x16x32_bf16 v[84:87], v[150:153], v[232:235], v[84:87]
	v_mfma_f32_16x16x32_bf16 v[76:79], v[158:161], v[232:235], v[76:79]
	s_setprio 0
	s_setprio 1
	v_mfma_f32_16x16x32_bf16 v[112:115], v[162:165], v[178:181], v[112:115]
	v_mfma_f32_16x16x32_bf16 v[104:107], v[170:173], v[178:181], v[104:107]
	v_mfma_f32_16x16x32_bf16 v[96:99], v[162:165], v[186:189], v[96:99]
	v_mfma_f32_16x16x32_bf16 v[88:91], v[170:173], v[186:189], v[88:91]
	v_mfma_f32_16x16x32_bf16 v[80:83], v[162:165], v[220:223], v[80:83]
	v_mfma_f32_16x16x32_bf16 v[72:75], v[170:173], v[220:223], v[72:75]
	v_mfma_f32_16x16x32_bf16 v[68:71], v[162:165], v[228:231], v[68:71]
	v_mfma_f32_16x16x32_bf16 v[64:67], v[170:173], v[228:231], v[64:67]
	v_mfma_f32_16x16x32_bf16 v[112:115], v[166:169], v[182:185], v[112:115]
	v_mfma_f32_16x16x32_bf16 v[104:107], v[174:177], v[182:185], v[104:107]
	v_mfma_f32_16x16x32_bf16 v[96:99], v[166:169], v[190:193], v[96:99]
	v_mfma_f32_16x16x32_bf16 v[88:91], v[174:177], v[190:193], v[88:91]
	v_mfma_f32_16x16x32_bf16 v[80:83], v[166:169], v[224:227], v[80:83]
	v_mfma_f32_16x16x32_bf16 v[72:75], v[174:177], v[224:227], v[72:75]
	v_mfma_f32_16x16x32_bf16 v[68:71], v[166:169], v[232:235], v[68:71]
	v_mfma_f32_16x16x32_bf16 v[64:67], v[174:177], v[232:235], v[64:67]
	s_setprio 0
	s_barrier
; __device__ __forceinline__ u32x4 pack8_bf16(f32x4 a, f32x4 b) { u32x4 w; w.x = cvt_pk_bf16(a[0], a[1]); w.y = cvt_pk_bf16(a[2], a[3]); w.z = cvt_pk_bf16(b[0], b[1]); w.w = cvt_pk_bf16(b[2], b[3]); return w; }
; #define PG8_STAGE(bufoff, gbase, voff) do { _Pragma("unroll") for (int _i = 0; _i < 2; ++_i) \
;         __builtin_amdgcn_global_load_lds((const unsigned*)((const char*)(gbase) + (voff)[_i]), (PG8_LAS unsigned*)(lds + (bufoff) + ldsw + _i * 8192), 16, 0, 0); } while (0)
; #define PG8_LDA(dst, b, h) do { _Pragma("unroll") for (int m = 0; m < 4; ++m) _Pragma("unroll") for (int k = 0; k < 2; ++k) dst[m][k] = *(const PG8_LAS bf16x8*)(lds + PG8_SA(b, h) + aoff + m * 2048 + k * 1024); } while (0)
; #define PG8_WAIT_V(n) asm volatile("s_waitcnt vmcnt(" #n ")" ::: "memory")
; #define PG8_WAIT_L(n) asm volatile("s_waitcnt lgkmcnt(" #n ")" ::: "memory")
; #define PG8_BAR __builtin_amdgcn_s_barrier()
; #define PG8_SCHED __builtin_amdgcn_sched_barrier(0)
;     __device__ __forceinline__ void operator()(const f32x4 (&acc)[2][2][4][2], const Unit& u, int wr, int wc, int fr, int fq) const {
;         const int g = u.pn / nNper, pnl = u.pn - g * nNper, pml = u.pm & 63;
;         bf16_t* base = O + (size_t)g * gstride;
;         const int row0 = pml * BM + wr * 64 + fr, col0 = pnl * BM + wc * 32 + 8 * fq;
; #pragma unroll
;         for (int ai = 0; ai < 2; ++ai)
; #pragma unroll
;             for (int m = 0; m < 4; ++m) { bf16_t* rowp = base + (size_t)(row0 + ai * HALF + m * 16) * ldc + col0;
; #pragma unroll
;                 for (int bj = 0; bj < 2; ++bj) { f32x4 v0 = acc[ai][bj][m][0], v1 = acc[ai][bj][m][1];
;                     if (ACT == 1) {
; #pragma unroll
;                         for (int j = 0; j < 4; ++j) { float a = fmaxf(v0[j], 0.f), b = fmaxf(v1[j], 0.f); v0[j] = a * a; v1[j] = b * b; } }
;                     *(u32x4*)(rowp + bj * HALF) = pack8_bf16(v0, v1); } }
; template <class Epi, class Sched, bool ALIGN_EPI = false, bool SP2 = false>
; __device__ __forceinline__ void gemm_phase(PG8_LAS unsigned char* lds, const Gemm g, const Sched& S, const Epi& E) {
;     ...
;             PG8_LDA(At, 1, 1); PG8_STAGE(PG8_SB(1, 0), b3, voffB); PG8_STAGE(PG8_SB(1, 1), b3 + hstep, voffB); PG8_STAGE(PG8_SA(1, 0), a3, voffA);
;             PG8_WAIT_V(8); PG8_WAIT_L(0); PG8_BAR; PG8_MMA(1, 0, At, B0); PG8_MMA(1, 1, At, B1); PG8_BAR; PG8_SCHED;
	s_add_i32 s49, s49, s2
	v_lshl_add_u64 v[140:141], v[140:141], 0, s[20:21]
	s_mov_b32 m0, s49
	ds_read_b128 v[178:181], v145 offset:49152
	ds_read_b128 v[182:185], v145 offset:50176
	ds_read_b128 v[186:189], v145 offset:51200
	ds_read_b128 v[190:193], v145 offset:52224
	ds_read_b128 v[220:223], v145 offset:53248
	ds_read_b128 v[224:227], v145 offset:54272
	ds_read_b128 v[228:231], v145 offset:55296
	ds_read_b128 v[232:235], v145 offset:56320
	global_load_lds_dwordx4 v[140:141], off
	s_add_i32 m0, s49, 0x2000
	s_add_u32 s52, s68, 0x80080
	v_lshl_add_u64 v[140:141], v[206:207], 0, s[20:21]
	s_addc_u32 s53, s69, 0
	s_add_i32 s49, s83, s2
	global_load_lds_dwordx4 v[140:141], off
	v_lshl_add_u64 v[140:141], s[52:53], 0, v[128:129]
	s_mov_b32 m0, s49
	s_nop 0
	global_load_lds_dwordx4 v[140:141], off
	v_lshl_add_u64 v[140:141], s[52:53], 0, v[130:131]
	s_add_i32 m0, s49, 0x2000
	s_nop 0
	global_load_lds_dwordx4 v[140:141], off
	v_lshl_add_u64 v[140:141], v[214:215], 0, s[20:21]
	s_mov_b32 m0, s28
	s_nop 0
	global_load_lds_dwordx4 v[140:141], off
	v_lshl_add_u64 v[140:141], v[216:217], 0, s[20:21]
	s_mov_b32 m0, s29
	s_nop 0
	global_load_lds_dwordx4 v[140:141], off
	s_waitcnt vmcnt(8)
	s_waitcnt lgkmcnt(0)
	s_barrier
	s_setprio 1
	s_waitcnt lgkmcnt(0)
	v_mfma_f32_16x16x32_bf16 v[60:63], v[146:149], v[178:181], v[60:63]
	v_mfma_f32_16x16x32_bf16 v[56:59], v[154:157], v[178:181], v[56:59]
	v_mfma_f32_16x16x32_bf16 v[52:55], v[146:149], v[186:189], v[52:55]
	v_mfma_f32_16x16x32_bf16 v[44:47], v[154:157], v[186:189], v[44:47]
	v_mfma_f32_16x16x32_bf16 v[36:39], v[146:149], v[220:223], v[36:39]
	v_mfma_f32_16x16x32_bf16 v[28:31], v[154:157], v[220:223], v[28:31]
	v_mfma_f32_16x16x32_bf16 v[20:23], v[146:149], v[228:231], v[20:23]
	v_mfma_f32_16x16x32_bf16 v[12:15], v[154:157], v[228:231], v[12:15]
	v_mfma_f32_16x16x32_bf16 v[60:63], v[150:153], v[182:185], v[60:63]
	v_mfma_f32_16x16x32_bf16 v[56:59], v[158:161], v[182:185], v[56:59]
	v_mfma_f32_16x16x32_bf16 v[52:55], v[150:153], v[190:193], v[52:55]
	v_mfma_f32_16x16x32_bf16 v[44:47], v[158:161], v[190:193], v[44:47]
	v_mfma_f32_16x16x32_bf16 v[36:39], v[150:153], v[224:227], v[36:39]
	v_mfma_f32_16x16x32_bf16 v[28:31], v[158:161], v[224:227], v[28:31]
	v_mfma_f32_16x16x32_bf16 v[20:23], v[150:153], v[232:235], v[20:23]
	v_mfma_f32_16x16x32_bf16 v[12:15], v[158:161], v[232:235], v[12:15]
	s_setprio 0
	s_setprio 1
	v_mfma_f32_16x16x32_bf16 v[48:51], v[162:165], v[178:181], v[48:51]
	v_mfma_f32_16x16x32_bf16 v[40:43], v[170:173], v[178:181], v[40:43]
	v_mfma_f32_16x16x32_bf16 v[32:35], v[162:165], v[186:189], v[32:35]
	v_mfma_f32_16x16x32_bf16 v[24:27], v[170:173], v[186:189], v[24:27]
	v_mfma_f32_16x16x32_bf16 v[16:19], v[162:165], v[220:223], v[16:19]
	v_mfma_f32_16x16x32_bf16 v[8:11], v[170:173], v[220:223], v[8:11]
	v_mfma_f32_16x16x32_bf16 v[4:7], v[162:165], v[228:231], v[4:7]
	v_mfma_f32_16x16x32_bf16 v[0:3], v[170:173], v[228:231], v[0:3]
	v_mfma_f32_16x16x32_bf16 v[48:51], v[166:169], v[182:185], v[48:51]
	v_mfma_f32_16x16x32_bf16 v[40:43], v[174:177], v[182:185], v[40:43]
	v_mfma_f32_16x16x32_bf16 v[32:35], v[166:169], v[190:193], v[32:35]
	v_mfma_f32_16x16x32_bf16 v[24:27], v[174:177], v[190:193], v[24:27]
	v_mfma_f32_16x16x32_bf16 v[16:19], v[166:169], v[224:227], v[16:19]
	v_mfma_f32_16x16x32_bf16 v[8:11], v[174:177], v[224:227], v[8:11]
	v_mfma_f32_16x16x32_bf16 v[4:7], v[166:169], v[232:235], v[4:7]
	v_mfma_f32_16x16x32_bf16 v[0:3], v[174:177], v[232:235], v[0:3]
	s_setprio 0
	s_barrier
	s_add_i32 s45, s45, 2
	s_add_u32 s66, s66, 0x100
	s_addc_u32 s67, s67, 0
	s_add_u32 s37, s37, 0x100
	s_addc_u32 s43, s43, 0
	s_cmpk_gt_u32 s45, 0x7d
	s_cbranch_scc0 .LBB0_432
	s_and_b64 vcc, exec, s[12:13]
	s_cbranch_vccz .LBB0_435
	s_barrier
.LBB0_435:
	s_ashr_i32 s19, s44, 31
	s_lshr_b32 s19, s19, 29
	s_add_i32 s19, s44, s19
	s_and_b32 s19, s19, 0xfffff8
	s_lshl_b32 s31, s42, 8
	s_sub_i32 s19, s44, s19
	s_and_b32 s31, s31, 0x3f00
	v_add_u32_e32 v146, s31, v142
	v_lshl_or_b32 v140, s19, 8, v144
	v_ashrrev_i32_e32 v141, 31, v140
	v_ashrrev_i32_e32 v147, 31, v146
	v_lshl_add_u64 v[148:149], v[140:141], 1, s[56:57]
	v_lshlrev_b64 v[140:141], 12, v[146:147]
	v_lshl_add_u64 v[140:141], v[148:149], 0, v[140:141]
	s_mov_b64 s[34:35], 0x10000
	v_mov_b32_e32 v242, 0x8000
	v_mov_b32_e32 v243, 0
	v_and_b32_e32 v238, 8, v208
	v_cmp_ne_u32_e32 vcc, 0, v238
	v_and_b32_e32 v240, 63, v208
	v_lshrrev_b32_e32 v241, 3, v240
	v_and_b32_e32 v244, 3, v240
	v_lshl_add_u32 v241, v244, 4, v241
	v_and_b32_e32 v244, 4, v240
	v_lshl_add_u32 v241, v244, 1, v241
	v_lshlrev_b32_e32 v240, 2, v241
	v_cvt_pk_bf16_f32 v124, v124, v125
	v_cvt_pk_bf16_f32 v125, v126, v127
	v_cvt_pk_bf16_f32 v126, v120, v121
	v_cvt_pk_bf16_f32 v127, v122, v123
	v_cvt_pk_bf16_f32 v112, v112, v113
	v_cvt_pk_bf16_f32 v113, v114, v115
	v_cvt_pk_bf16_f32 v114, v104, v105
	v_cvt_pk_bf16_f32 v115, v106, v107
	v_mov_b32_dpp v246, v112 row_ror:8 row_mask:0xf bank_mask:0xf
	v_mov_b32_dpp v247, v113 row_ror:8 row_mask:0xf bank_mask:0xf
	v_mov_b32_dpp v248, v114 row_ror:8 row_mask:0xf bank_mask:0xf
	v_mov_b32_dpp v249, v115 row_ror:8 row_mask:0xf bank_mask:0xf
	v_mov_b32_dpp v250, v124 row_ror:8 row_mask:0xf bank_mask:0xf
	v_mov_b32_dpp v251, v125 row_ror:8 row_mask:0xf bank_mask:0xf
	v_mov_b32_dpp v252, v126 row_ror:8 row_mask:0xf bank_mask:0xf
	v_mov_b32_dpp v253, v127 row_ror:8 row_mask:0xf bank_mask:0xf
	v_cndmask_b32_e32 v246, v124, v246, vcc
	v_cndmask_b32_e32 v247, v125, v247, vcc
	v_cndmask_b32_e32 v248, v126, v248, vcc
	v_cndmask_b32_e32 v249, v127, v249, vcc
	v_cndmask_b32_e32 v250, v250, v112, vcc
	v_cndmask_b32_e32 v251, v251, v113, vcc
	v_cndmask_b32_e32 v252, v252, v114, vcc
	v_cndmask_b32_e32 v253, v253, v115, vcc
	ds_bpermute_b32 v246, v240, v246
	ds_bpermute_b32 v247, v240, v247
	ds_bpermute_b32 v248, v240, v248
	ds_bpermute_b32 v249, v240, v249
	ds_bpermute_b32 v250, v240, v250
	ds_bpermute_b32 v251, v240, v251
	ds_bpermute_b32 v252, v240, v252
	ds_bpermute_b32 v253, v240, v253
	v_lshl_add_u64 v[238:239], v[140:141], 0, v[242:243]
	s_waitcnt lgkmcnt(4)
; __device__ __forceinline__ u32x4 pack8_bf16(f32x4 a, f32x4 b) { u32x4 w; w.x = cvt_pk_bf16(a[0], a[1]); w.y = cvt_pk_bf16(a[2], a[3]); w.z = cvt_pk_bf16(b[0], b[1]); w.w = cvt_pk_bf16(b[2], b[3]); return w; }
; #define ACT(t) (KBASE(t) <= qlo + QBLK - 1 && KBASE(t) + KVBLK - 1 >= qlo - W + 1)
;     __device__ __forceinline__ void operator()(const f32x4 (&acc)[2][2][4][2], const Unit& u, int wr, int wc, int fr, int fq) const {
;     ...
; #pragma unroll
;         for (int ai = 0; ai < 2; ++ai)
; #pragma unroll
;             for (int m = 0; m < 4; ++m) { bf16_t* rowp = base + (size_t)(row0 + ai * HALF + m * 16) * ldc + col0;
; #pragma unroll
;                 for (int bj = 0; bj < 2; ++bj) { f32x4 v0 = acc[ai][bj][m][0], v1 = acc[ai][bj][m][1];
;                     if (ACT == 1) {
; #pragma unroll
;                         for (int j = 0; j < 4; ++j) { float a = fmaxf(v0[j], 0.f), b = fmaxf(v1[j], 0.f); v0[j] = a * a; v1[j] = b * b; } }
;                     *(u32x4*)(rowp + bj * HALF) = pack8_bf16(v0, v1); } }
	global_store_dwordx4 v[140:141], v[246:249], off
	s_waitcnt lgkmcnt(0)
	global_store_dwordx4 v[238:239], v[250:253], off
	v_lshl_add_u64 v[140:141], v[140:141], 0, s[34:35]
	v_cvt_pk_bf16_f32 v116, v116, v117
	v_cvt_pk_bf16_f32 v117, v118, v119
	v_cvt_pk_bf16_f32 v118, v108, v109
	v_cvt_pk_bf16_f32 v119, v110, v111
	v_cvt_pk_bf16_f32 v96, v96, v97
	v_cvt_pk_bf16_f32 v97, v98, v99
	v_cvt_pk_bf16_f32 v98, v88, v89
	v_cvt_pk_bf16_f32 v99, v90, v91
	v_mov_b32_dpp v246, v96 row_ror:8 row_mask:0xf bank_mask:0xf
	v_mov_b32_dpp v247, v97 row_ror:8 row_mask:0xf bank_mask:0xf
	v_mov_b32_dpp v248, v98 row_ror:8 row_mask:0xf bank_mask:0xf
	v_mov_b32_dpp v249, v99 row_ror:8 row_mask:0xf bank_mask:0xf
	v_mov_b32_dpp v250, v116 row_ror:8 row_mask:0xf bank_mask:0xf
	v_mov_b32_dpp v251, v117 row_ror:8 row_mask:0xf bank_mask:0xf
	v_mov_b32_dpp v252, v118 row_ror:8 row_mask:0xf bank_mask:0xf
	v_mov_b32_dpp v253, v119 row_ror:8 row_mask:0xf bank_mask:0xf
	v_cndmask_b32_e32 v246, v116, v246, vcc
	v_cndmask_b32_e32 v247, v117, v247, vcc
	v_cndmask_b32_e32 v248, v118, v248, vcc
	v_cndmask_b32_e32 v249, v119, v249, vcc
	v_cndmask_b32_e32 v250, v250, v96, vcc
	v_cndmask_b32_e32 v251, v251, v97, vcc
	v_cndmask_b32_e32 v252, v252, v98, vcc
	v_cndmask_b32_e32 v253, v253, v99, vcc
	ds_bpermute_b32 v246, v240, v246
	ds_bpermute_b32 v247, v240, v247
	ds_bpermute_b32 v248, v240, v248
	ds_bpermute_b32 v249, v240, v249
	ds_bpermute_b32 v250, v240, v250
	ds_bpermute_b32 v251, v240, v251
	ds_bpermute_b32 v252, v240, v252
	ds_bpermute_b32 v253, v240, v253
	v_lshl_add_u64 v[238:239], v[140:141], 0, v[242:243]
	s_waitcnt lgkmcnt(4)
	global_store_dwordx4 v[140:141], v[246:249], off
	s_waitcnt lgkmcnt(0)
	global_store_dwordx4 v[238:239], v[250:253], off
	v_lshl_add_u64 v[140:141], v[140:141], 0, s[34:35]
	v_cvt_pk_bf16_f32 v100, v100, v101
	v_cvt_pk_bf16_f32 v101, v102, v103
	v_cvt_pk_bf16_f32 v102, v92, v93
	v_cvt_pk_bf16_f32 v103, v94, v95
	v_cvt_pk_bf16_f32 v80, v80, v81
	v_cvt_pk_bf16_f32 v81, v82, v83
	v_cvt_pk_bf16_f32 v82, v72, v73
	v_cvt_pk_bf16_f32 v83, v74, v75
	v_mov_b32_dpp v246, v80 row_ror:8 row_mask:0xf bank_mask:0xf
	v_mov_b32_dpp v247, v81 row_ror:8 row_mask:0xf bank_mask:0xf
	v_mov_b32_dpp v248, v82 row_ror:8 row_mask:0xf bank_mask:0xf
	v_mov_b32_dpp v249, v83 row_ror:8 row_mask:0xf bank_mask:0xf
	v_mov_b32_dpp v250, v100 row_ror:8 row_mask:0xf bank_mask:0xf
	v_mov_b32_dpp v251, v101 row_ror:8 row_mask:0xf bank_mask:0xf
	v_mov_b32_dpp v252, v102 row_ror:8 row_mask:0xf bank_mask:0xf
	v_mov_b32_dpp v253, v103 row_ror:8 row_mask:0xf bank_mask:0xf
	v_cndmask_b32_e32 v246, v100, v246, vcc
	v_cndmask_b32_e32 v247, v101, v247, vcc
	v_cndmask_b32_e32 v248, v102, v248, vcc
	v_cndmask_b32_e32 v249, v103, v249, vcc
	v_cndmask_b32_e32 v250, v250, v80, vcc
	v_cndmask_b32_e32 v251, v251, v81, vcc
	v_cndmask_b32_e32 v252, v252, v82, vcc
	v_cndmask_b32_e32 v253, v253, v83, vcc
	ds_bpermute_b32 v246, v240, v246
	ds_bpermute_b32 v247, v240, v247
	ds_bpermute_b32 v248, v240, v248
	ds_bpermute_b32 v249, v240, v249
	ds_bpermute_b32 v250, v240, v250
	ds_bpermute_b32 v251, v240, v251
	ds_bpermute_b32 v252, v240, v252
	ds_bpermute_b32 v253, v240, v253
	v_lshl_add_u64 v[238:239], v[140:141], 0, v[242:243]
	s_waitcnt lgkmcnt(4)
	global_store_dwordx4 v[140:141], v[246:249], off
	s_waitcnt lgkmcnt(0)
	global_store_dwordx4 v[238:239], v[250:253], off
	v_lshl_add_u64 v[140:141], v[140:141], 0, s[34:35]
	v_cvt_pk_bf16_f32 v84, v84, v85
	v_cvt_pk_bf16_f32 v85, v86, v87
	v_cvt_pk_bf16_f32 v86, v76, v77
	v_cvt_pk_bf16_f32 v87, v78, v79
	v_cvt_pk_bf16_f32 v68, v68, v69
	v_cvt_pk_bf16_f32 v69, v70, v71
	v_cvt_pk_bf16_f32 v70, v64, v65
	v_cvt_pk_bf16_f32 v71, v66, v67
	v_mov_b32_dpp v246, v68 row_ror:8 row_mask:0xf bank_mask:0xf
	v_mov_b32_dpp v247, v69 row_ror:8 row_mask:0xf bank_mask:0xf
	v_mov_b32_dpp v248, v70 row_ror:8 row_mask:0xf bank_mask:0xf
	v_mov_b32_dpp v249, v71 row_ror:8 row_mask:0xf bank_mask:0xf
	v_mov_b32_dpp v250, v84 row_ror:8 row_mask:0xf bank_mask:0xf
	v_mov_b32_dpp v251, v85 row_ror:8 row_mask:0xf bank_mask:0xf
	v_mov_b32_dpp v252, v86 row_ror:8 row_mask:0xf bank_mask:0xf
	v_mov_b32_dpp v253, v87 row_ror:8 row_mask:0xf bank_mask:0xf
	v_cndmask_b32_e32 v246, v84, v246, vcc
	v_cndmask_b32_e32 v247, v85, v247, vcc
	v_cndmask_b32_e32 v248, v86, v248, vcc
	v_cndmask_b32_e32 v249, v87, v249, vcc
	v_cndmask_b32_e32 v250, v250, v68, vcc
	v_cndmask_b32_e32 v251, v251, v69, vcc
	v_cndmask_b32_e32 v252, v252, v70, vcc
	v_cndmask_b32_e32 v253, v253, v71, vcc
	ds_bpermute_b32 v246, v240, v246
	ds_bpermute_b32 v247, v240, v247
	ds_bpermute_b32 v248, v240, v248
	ds_bpermute_b32 v249, v240, v249
	ds_bpermute_b32 v250, v240, v250
	ds_bpermute_b32 v251, v240, v251
	ds_bpermute_b32 v252, v240, v252
	ds_bpermute_b32 v253, v240, v253
	v_lshl_add_u64 v[238:239], v[140:141], 0, v[242:243]
	s_waitcnt lgkmcnt(4)
	global_store_dwordx4 v[140:141], v[246:249], off
	s_waitcnt lgkmcnt(0)
; __device__ __forceinline__ u32x4 pack8_bf16(f32x4 a, f32x4 b) { u32x4 w; w.x = cvt_pk_bf16(a[0], a[1]); w.y = cvt_pk_bf16(a[2], a[3]); w.z = cvt_pk_bf16(b[0], b[1]); w.w = cvt_pk_bf16(b[2], b[3]); return w; }
; #define ACT(t) (KBASE(t) <= qlo + QBLK - 1 && KBASE(t) + KVBLK - 1 >= qlo - W + 1)
;     __device__ __forceinline__ void operator()(const f32x4 (&acc)[2][2][4][2], const Unit& u, int wr, int wc, int fr, int fq) const {
;     ...
; #pragma unroll
;         for (int ai = 0; ai < 2; ++ai)
; #pragma unroll
;             for (int m = 0; m < 4; ++m) { bf16_t* rowp = base + (size_t)(row0 + ai * HALF + m * 16) * ldc + col0;
; #pragma unroll
;                 for (int bj = 0; bj < 2; ++bj) { f32x4 v0 = acc[ai][bj][m][0], v1 = acc[ai][bj][m][1];
;                     if (ACT == 1) {
; #pragma unroll
;                         for (int j = 0; j < 4; ++j) { float a = fmaxf(v0[j], 0.f), b = fmaxf(v1[j], 0.f); v0[j] = a * a; v1[j] = b * b; } }
;                     *(u32x4*)(rowp + bj * HALF) = pack8_bf16(v0, v1); } }
	global_store_dwordx4 v[238:239], v[250:253], off
	s_mov_b64 s[34:35], 0x50000
	v_lshl_add_u64 v[140:141], v[140:141], 0, s[34:35]
	s_mov_b64 s[34:35], 0x10000
	v_cvt_pk_bf16_f32 v60, v60, v61
	v_cvt_pk_bf16_f32 v61, v62, v63
	v_cvt_pk_bf16_f32 v62, v56, v57
	v_cvt_pk_bf16_f32 v63, v58, v59
	v_cvt_pk_bf16_f32 v48, v48, v49
	v_cvt_pk_bf16_f32 v49, v50, v51
	v_cvt_pk_bf16_f32 v50, v40, v41
	v_cvt_pk_bf16_f32 v51, v42, v43
	v_mov_b32_dpp v246, v48 row_ror:8 row_mask:0xf bank_mask:0xf
	v_mov_b32_dpp v247, v49 row_ror:8 row_mask:0xf bank_mask:0xf
	v_mov_b32_dpp v248, v50 row_ror:8 row_mask:0xf bank_mask:0xf
	v_mov_b32_dpp v249, v51 row_ror:8 row_mask:0xf bank_mask:0xf
	v_mov_b32_dpp v250, v60 row_ror:8 row_mask:0xf bank_mask:0xf
	v_mov_b32_dpp v251, v61 row_ror:8 row_mask:0xf bank_mask:0xf
	v_mov_b32_dpp v252, v62 row_ror:8 row_mask:0xf bank_mask:0xf
	v_mov_b32_dpp v253, v63 row_ror:8 row_mask:0xf bank_mask:0xf
	v_cndmask_b32_e32 v246, v60, v246, vcc
	v_cndmask_b32_e32 v247, v61, v247, vcc
	v_cndmask_b32_e32 v248, v62, v248, vcc
	v_cndmask_b32_e32 v249, v63, v249, vcc
	v_cndmask_b32_e32 v250, v250, v48, vcc
	v_cndmask_b32_e32 v251, v251, v49, vcc
	v_cndmask_b32_e32 v252, v252, v50, vcc
	v_cndmask_b32_e32 v253, v253, v51, vcc
	ds_bpermute_b32 v246, v240, v246
	ds_bpermute_b32 v247, v240, v247
	ds_bpermute_b32 v248, v240, v248
	ds_bpermute_b32 v249, v240, v249
	ds_bpermute_b32 v250, v240, v250
	ds_bpermute_b32 v251, v240, v251
	ds_bpermute_b32 v252, v240, v252
	ds_bpermute_b32 v253, v240, v253
	v_lshl_add_u64 v[238:239], v[140:141], 0, v[242:243]
	s_waitcnt lgkmcnt(4)
	global_store_dwordx4 v[140:141], v[246:249], off
	s_waitcnt lgkmcnt(0)
	global_store_dwordx4 v[238:239], v[250:253], off
	v_lshl_add_u64 v[140:141], v[140:141], 0, s[34:35]
	v_cvt_pk_bf16_f32 v52, v52, v53
	v_cvt_pk_bf16_f32 v53, v54, v55
	v_cvt_pk_bf16_f32 v54, v44, v45
	v_cvt_pk_bf16_f32 v55, v46, v47
	v_cvt_pk_bf16_f32 v32, v32, v33
	v_cvt_pk_bf16_f32 v33, v34, v35
	v_cvt_pk_bf16_f32 v34, v24, v25
	v_cvt_pk_bf16_f32 v35, v26, v27
	v_mov_b32_dpp v246, v32 row_ror:8 row_mask:0xf bank_mask:0xf
	v_mov_b32_dpp v247, v33 row_ror:8 row_mask:0xf bank_mask:0xf
	v_mov_b32_dpp v248, v34 row_ror:8 row_mask:0xf bank_mask:0xf
	v_mov_b32_dpp v249, v35 row_ror:8 row_mask:0xf bank_mask:0xf
	v_mov_b32_dpp v250, v52 row_ror:8 row_mask:0xf bank_mask:0xf
	v_mov_b32_dpp v251, v53 row_ror:8 row_mask:0xf bank_mask:0xf
	v_mov_b32_dpp v252, v54 row_ror:8 row_mask:0xf bank_mask:0xf
	v_mov_b32_dpp v253, v55 row_ror:8 row_mask:0xf bank_mask:0xf
	v_cndmask_b32_e32 v246, v52, v246, vcc
	v_cndmask_b32_e32 v247, v53, v247, vcc
	v_cndmask_b32_e32 v248, v54, v248, vcc
	v_cndmask_b32_e32 v249, v55, v249, vcc
	v_cndmask_b32_e32 v250, v250, v32, vcc
	v_cndmask_b32_e32 v251, v251, v33, vcc
	v_cndmask_b32_e32 v252, v252, v34, vcc
	v_cndmask_b32_e32 v253, v253, v35, vcc
	ds_bpermute_b32 v246, v240, v246
	ds_bpermute_b32 v247, v240, v247
	ds_bpermute_b32 v248, v240, v248
	ds_bpermute_b32 v249, v240, v249
	ds_bpermute_b32 v250, v240, v250
	ds_bpermute_b32 v251, v240, v251
	ds_bpermute_b32 v252, v240, v252
	ds_bpermute_b32 v253, v240, v253
	v_lshl_add_u64 v[238:239], v[140:141], 0, v[242:243]
	s_waitcnt lgkmcnt(4)
	global_store_dwordx4 v[140:141], v[246:249], off
	s_waitcnt lgkmcnt(0)
	global_store_dwordx4 v[238:239], v[250:253], off
	v_lshl_add_u64 v[140:141], v[140:141], 0, s[34:35]
	v_cvt_pk_bf16_f32 v36, v36, v37
	v_cvt_pk_bf16_f32 v37, v38, v39
	v_cvt_pk_bf16_f32 v38, v28, v29
	v_cvt_pk_bf16_f32 v39, v30, v31
	v_cvt_pk_bf16_f32 v16, v16, v17
	v_cvt_pk_bf16_f32 v17, v18, v19
	v_cvt_pk_bf16_f32 v18, v8, v9
	v_cvt_pk_bf16_f32 v19, v10, v11
	v_mov_b32_dpp v246, v16 row_ror:8 row_mask:0xf bank_mask:0xf
	v_mov_b32_dpp v247, v17 row_ror:8 row_mask:0xf bank_mask:0xf
	v_mov_b32_dpp v248, v18 row_ror:8 row_mask:0xf bank_mask:0xf
	v_mov_b32_dpp v249, v19 row_ror:8 row_mask:0xf bank_mask:0xf
	v_mov_b32_dpp v250, v36 row_ror:8 row_mask:0xf bank_mask:0xf
	v_mov_b32_dpp v251, v37 row_ror:8 row_mask:0xf bank_mask:0xf
	v_mov_b32_dpp v252, v38 row_ror:8 row_mask:0xf bank_mask:0xf
	v_mov_b32_dpp v253, v39 row_ror:8 row_mask:0xf bank_mask:0xf
	v_cndmask_b32_e32 v246, v36, v246, vcc
	v_cndmask_b32_e32 v247, v37, v247, vcc
	v_cndmask_b32_e32 v248, v38, v248, vcc
	v_cndmask_b32_e32 v249, v39, v249, vcc
	v_cndmask_b32_e32 v250, v250, v16, vcc
	v_cndmask_b32_e32 v251, v251, v17, vcc
	v_cndmask_b32_e32 v252, v252, v18, vcc
	v_cndmask_b32_e32 v253, v253, v19, vcc
	ds_bpermute_b32 v246, v240, v246
	ds_bpermute_b32 v247, v240, v247
	ds_bpermute_b32 v248, v240, v248
	ds_bpermute_b32 v249, v240, v249
	ds_bpermute_b32 v250, v240, v250
	ds_bpermute_b32 v251, v240, v251
	ds_bpermute_b32 v252, v240, v252
	ds_bpermute_b32 v253, v240, v253
	v_lshl_add_u64 v[238:239], v[140:141], 0, v[242:243]
	s_waitcnt lgkmcnt(4)
	global_store_dwordx4 v[140:141], v[246:249], off
	s_waitcnt lgkmcnt(0)
	global_store_dwordx4 v[238:239], v[250:253], off
	v_lshl_add_u64 v[140:141], v[140:141], 0, s[34:35]
	v_cvt_pk_bf16_f32 v20, v20, v21
	v_cvt_pk_bf16_f32 v21, v22, v23
	v_cvt_pk_bf16_f32 v22, v12, v13
	v_cvt_pk_bf16_f32 v23, v14, v15
	v_cvt_pk_bf16_f32 v4, v4, v5
	v_cvt_pk_bf16_f32 v5, v6, v7
	v_cvt_pk_bf16_f32 v6, v0, v1
	v_cvt_pk_bf16_f32 v7, v2, v3
	v_mov_b32_dpp v246, v4 row_ror:8 row_mask:0xf bank_mask:0xf
	v_mov_b32_dpp v247, v5 row_ror:8 row_mask:0xf bank_mask:0xf
	v_mov_b32_dpp v248, v6 row_ror:8 row_mask:0xf bank_mask:0xf
	v_mov_b32_dpp v249, v7 row_ror:8 row_mask:0xf bank_mask:0xf
	v_mov_b32_dpp v250, v20 row_ror:8 row_mask:0xf bank_mask:0xf
	v_mov_b32_dpp v251, v21 row_ror:8 row_mask:0xf bank_mask:0xf
	v_mov_b32_dpp v252, v22 row_ror:8 row_mask:0xf bank_mask:0xf
	v_mov_b32_dpp v253, v23 row_ror:8 row_mask:0xf bank_mask:0xf
	v_cndmask_b32_e32 v246, v20, v246, vcc
	v_cndmask_b32_e32 v247, v21, v247, vcc
	v_cndmask_b32_e32 v248, v22, v248, vcc
	v_cndmask_b32_e32 v249, v23, v249, vcc
	v_cndmask_b32_e32 v250, v250, v4, vcc
	v_cndmask_b32_e32 v251, v251, v5, vcc
	v_cndmask_b32_e32 v252, v252, v6, vcc
	v_cndmask_b32_e32 v253, v253, v7, vcc
	ds_bpermute_b32 v246, v240, v246
	ds_bpermute_b32 v247, v240, v247
	ds_bpermute_b32 v248, v240, v248
	ds_bpermute_b32 v249, v240, v249
	ds_bpermute_b32 v250, v240, v250
	ds_bpermute_b32 v251, v240, v251
	ds_bpermute_b32 v252, v240, v252
	ds_bpermute_b32 v253, v240, v253
	v_lshl_add_u64 v[238:239], v[140:141], 0, v[242:243]
	s_waitcnt lgkmcnt(4)
	global_store_dwordx4 v[140:141], v[246:249], off
	s_waitcnt lgkmcnt(0)
	global_store_dwordx4 v[238:239], v[250:253], off
	s_andn2_b64 vcc, exec, s[40:41]
	s_mov_b64 s[34:35], -1
	s_cbranch_vccnz .LBB0_424
	s_andn2_b64 vcc, exec, s[8:9]
	s_cbranch_vccnz .LBB0_423
	s_barrier
	s_branch .LBB0_423
